# same 64-deep k-chunk operand sets (half of the rows requested as whole 128-byte lines) also in the FFN-down and out-proj macro-tile loops
# baseline (speedup 1.0000x reference)
.LBB0_259:
	s_andn2_b64 vcc, exec, s[10:11]
	s_cbranch_vccnz .LBB0_418
	v_readlane_b32 s8, v247, 19
	v_readlane_b32 s9, v247, 20
	s_mov_b64 s[56:57], s[84:85]
	s_andn2_b64 vcc, exec, s[8:9]
	s_cbranch_vccnz .LBB0_327
	s_load_dwordx2 s[40:41], s[56:57], 0x108
	v_readlane_b32 s2, v246, 27
	v_readlane_b32 s8, v246, 21
	s_add_i32 s2, s2, 2
	v_readlane_b32 s9, v246, 22
	s_and_b64 s[8:9], s[8:9], exec
	s_mov_b32 s6, 0x10b98100
	s_cselect_b32 s6, s6, 0x11c18100
	s_lshl_b64 s[8:9], s[0:1], 21
	s_waitcnt lgkmcnt(0)
	s_add_u32 s42, s40, 0x14958100
	s_mul_hi_i32 s10, s2, 0xc0000
	s_mul_i32 s2, s2, 0xc0000
	s_addc_u32 s43, s41, 0
	s_add_u32 s2, s40, s2
	s_addc_u32 s10, s41, s10
	s_add_u32 s44, s2, 0x7200000
	s_addc_u32 s45, s10, 0
	s_add_u32 s2, s40, s6
	s_addc_u32 s6, s41, 0
	s_add_u32 s46, s2, s8
	s_addc_u32 s47, s6, s9
	s_add_u32 s8, s40, 0x7bc5000
	s_addc_u32 s9, s41, 0
	v_readlane_b32 s12, v247, 44
	s_mov_b32 s13, s83
	v_and_b32_e32 v177, 63, v194
	v_lshrrev_b32_e32 v178, 6, v194
	v_lshrrev_b32_e32 v160, 2, v194
	v_lshlrev_b32_e32 v160, 11, v160
	v_and_b32_e32 v179, 3, v177
	v_bfe_u32 v180, v177, 4, 2
	v_xor_b32_e32 v179, v179, v180
	v_lshl_add_u32 v160, v179, 4, v160
	v_add_u32_e32 v161, 0x20000, v160
	v_and_b32_e32 v174, 31, v177
	v_lshrrev_b32_e32 v182, 5, v177
	v_bfe_u32 v183, v174, 2, 2
	v_xor_b32_e32 v184, v182, v183
	v_xor_b32_e32 v185, 2, v184
	v_lshrrev_b32_e32 v186, 1, v178
	v_and_b32_e32 v187, 1, v178
	v_lshl_add_u32 v188, v186, 6, v174
	v_lshl_add_u32 v189, v187, 6, v174
	v_lshlrev_b32_e32 v188, 6, v188
	v_lshlrev_b32_e32 v189, 6, v189
	v_lshl_add_u32 v154, v184, 4, v188
	v_lshl_add_u32 v155, v185, 4, v188
	v_lshl_add_u32 v156, v184, 4, v189
	v_lshl_add_u32 v157, v185, 4, v189
	v_add_u32_e32 v158, 0x2000, v156
	v_add_u32_e32 v159, 0x2000, v157
	v_lshrrev_b32_e32 v179, 3, v177
	v_lshl_add_u32 v179, v178, 3, v179
	v_lshlrev_b32_e32 v179, 11, v179
	v_and_b32_e32 v180, 1, v178
	v_lshrrev_b32_e32 v183, 4, v177
	v_lshl_add_u32 v180, v180, 2, v183
	v_and_b32_e32 v183, 7, v177
	v_xor_b32_e32 v180, v180, v183
	v_lshl_add_u32 v160, v180, 4, v179
	v_add_u32_e32 v161, 0x20000, v160
	v_add_u32_e32 v242, 0x10000, v160
	v_add_u32_e32 v243, 0x30000, v160
	v_bfe_u32 v183, v174, 1, 3
	v_or_b32_e32 v180, 0, v182
	v_xor_b32_e32 v180, v180, v183
	v_lshlrev_b32_e32 v180, 4, v180
	v_lshl_add_u32 v179, v186, 5, v174
	v_lshl_add_u32 v154, v179, 7, v180
	v_lshl_add_u32 v179, v187, 5, v174
	v_lshl_add_u32 v158, v179, 7, v180
	v_add_u32_e32 v238, 0x4000, v158
	v_or_b32_e32 v180, 4, v182
	v_xor_b32_e32 v180, v180, v183
	v_lshlrev_b32_e32 v180, 4, v180
	v_lshl_add_u32 v179, v186, 5, v174
	v_lshl_add_u32 v155, v179, 7, v180
	v_lshl_add_u32 v179, v187, 5, v174
	v_lshl_add_u32 v159, v179, 7, v180
	v_add_u32_e32 v239, 0x4000, v159
	v_or_b32_e32 v180, 2, v182
	v_xor_b32_e32 v180, v180, v183
	v_lshlrev_b32_e32 v180, 4, v180
	v_lshl_add_u32 v179, v186, 5, v174
	v_lshl_add_u32 v156, v179, 7, v180
	v_lshl_add_u32 v179, v187, 5, v174
	v_lshl_add_u32 v236, v179, 7, v180
	v_add_u32_e32 v240, 0x4000, v236
	v_or_b32_e32 v180, 6, v182
	v_xor_b32_e32 v180, v180, v183
	v_lshlrev_b32_e32 v180, 4, v180
	v_lshl_add_u32 v179, v186, 5, v174
	v_lshl_add_u32 v157, v179, 7, v180
	v_lshl_add_u32 v179, v187, 5, v174
	v_lshl_add_u32 v237, v179, 7, v180
	v_add_u32_e32 v241, 0x4000, v237
	v_lshlrev_b32_e32 v190, 6, v186
	v_lshl_add_u32 v190, v182, 2, v190
	v_lshl_add_u32 v191, v187, 6, v174
	v_lshlrev_b32_e32 v192, 12, v190
	v_lshl_add_u32 v162, v191, 2, v192
	v_add_u32_e32 v163, 0x1000, v162
	v_add_u32_e32 v164, 0x2000, v162
	v_add_u32_e32 v165, 0x3000, v162
	v_lshlrev_b32_e32 v166, 2, v191
	v_mul_u32_u24_e32 v167, 0xc000, v187
	v_lshl_add_u32 v167, v190, 2, v167
	v_xor_b32_e32 v168, 16, v177
	v_lshlrev_b32_e32 v168, 2, v168
	v_xor_b32_e32 v169, 8, v177
	v_lshlrev_b32_e32 v169, 2, v169
	v_xor_b32_e32 v171, 4, v177
	v_lshlrev_b32_e32 v171, 2, v171
	v_xor_b32_e32 v172, 2, v177
	v_lshlrev_b32_e32 v172, 2, v172
	v_xor_b32_e32 v173, 1, v177
	v_lshlrev_b32_e32 v173, 2, v173
	v_readfirstlane_b32 s65, v194
	s_nop 0
	s_lshl_b32 s65, s65, 4
	s_add_u32 s65, s65, 16
	s_mov_b32 s16, s83
.Lhw_outproj_tloop:
	s_cmpk_gt_u32 s16, 47
	s_cbranch_scc1 .Lhw_outproj_exit
	v_readlane_b32 s6, v246, 16
	s_lshr_b32 s2, s16, 2
	s_and_b32 s15, s16, 3
	s_add_i32 s6, s6, s2
	s_lshl_b32 s6, s6, 7
	s_lshl_b32 s15, s15, 8
	s_mul_i32 vcc_lo, s6, 0x800
	s_add_u32 s66, s42, vcc_lo
	s_addc_u32 s67, s43, 0
	s_mul_i32 vcc_lo, s15, 0x800
	s_add_u32 s62, s46, vcc_lo
	s_addc_u32 s63, s47, 0
	s_add_u32 s18, s62, 0x40000
	s_addc_u32 s19, s63, 0
	s_barrier
	s_sub_u32 s66, s66, 64
	s_subb_u32 s67, s67, 0
	s_sub_u32 s62, s62, 64
	s_subb_u32 s63, s63, 0
	s_sub_u32 s18, s18, 64
	s_subb_u32 s19, s19, 0
	s_add_u32 m0, s65, 0x0
	s_nop 0
	global_load_lds_dwordx4 v242, s[66:67]
	s_add_u32 m0, s65, 0x1000
	s_nop 0
	global_load_lds_dwordx4 v243, s[66:67]
	s_add_u32 m0, s65, 0x2000
	s_nop 0
	global_load_lds_dwordx4 v242, s[62:63]
	s_add_u32 m0, s65, 0x3000
	s_nop 0
	global_load_lds_dwordx4 v243, s[62:63]
	s_add_u32 m0, s65, 0x4000
	s_nop 0
	global_load_lds_dwordx4 v242, s[18:19]
	s_add_u32 m0, s65, 0x5000
	s_nop 0
	global_load_lds_dwordx4 v243, s[18:19]
	s_add_u32 s66, s66, 64
	s_addc_u32 s67, s67, 0
	s_add_u32 s62, s62, 64
	s_addc_u32 s63, s63, 0
	s_add_u32 s18, s18, 64
	s_addc_u32 s19, s19, 0
	s_add_u32 m0, s65, 0x6000
	s_nop 0
	global_load_lds_dwordx4 v160, s[66:67]
	s_add_u32 m0, s65, 0x7000
	s_nop 0
	global_load_lds_dwordx4 v161, s[66:67]
	s_add_u32 m0, s65, 0x8000
	s_nop 0
	global_load_lds_dwordx4 v160, s[62:63]
	s_add_u32 m0, s65, 0x9000
	s_nop 0
	global_load_lds_dwordx4 v161, s[62:63]
	s_add_u32 m0, s65, 0xa000
	s_nop 0
	global_load_lds_dwordx4 v160, s[18:19]
	s_add_u32 m0, s65, 0xb000
	s_nop 0
	global_load_lds_dwordx4 v161, s[18:19]
	s_add_u32 s66, s66, 64
	s_addc_u32 s67, s67, 0
	s_add_u32 s62, s62, 64
	s_addc_u32 s63, s63, 0
	s_add_u32 s18, s18, 64
	s_addc_u32 s19, s19, 0
	v_mov_b32_e32 v2, 0
	v_mov_b32_e32 v3, 0
	v_mov_b32_e32 v4, 0
	v_mov_b32_e32 v5, 0
	v_mov_b32_e32 v6, 0
	v_mov_b32_e32 v7, 0
	v_mov_b32_e32 v8, 0
	v_mov_b32_e32 v9, 0
	v_mov_b32_e32 v10, 0
	v_mov_b32_e32 v11, 0
	v_mov_b32_e32 v12, 0
	v_mov_b32_e32 v13, 0
	v_mov_b32_e32 v14, 0
	v_mov_b32_e32 v15, 0
	v_mov_b32_e32 v16, 0
	v_mov_b32_e32 v17, 0
	v_mov_b32_e32 v18, 0
	v_mov_b32_e32 v19, 0
	v_mov_b32_e32 v20, 0
	v_mov_b32_e32 v21, 0
	v_mov_b32_e32 v22, 0
	v_mov_b32_e32 v23, 0
	v_mov_b32_e32 v24, 0
	v_mov_b32_e32 v25, 0
	v_mov_b32_e32 v26, 0
	v_mov_b32_e32 v27, 0
	v_mov_b32_e32 v28, 0
	v_mov_b32_e32 v29, 0
	v_mov_b32_e32 v30, 0
	v_mov_b32_e32 v31, 0
	v_mov_b32_e32 v32, 0
	v_mov_b32_e32 v33, 0
	v_mov_b32_e32 v34, 0
	v_mov_b32_e32 v35, 0
	v_mov_b32_e32 v36, 0
	v_mov_b32_e32 v37, 0
	v_mov_b32_e32 v38, 0
	v_mov_b32_e32 v39, 0
	v_mov_b32_e32 v40, 0
	v_mov_b32_e32 v41, 0
	v_mov_b32_e32 v42, 0
	v_mov_b32_e32 v43, 0
	v_mov_b32_e32 v44, 0
	v_mov_b32_e32 v45, 0
	v_mov_b32_e32 v46, 0
	v_mov_b32_e32 v47, 0
	v_mov_b32_e32 v48, 0
	v_mov_b32_e32 v49, 0
	v_mov_b32_e32 v50, 0
	v_mov_b32_e32 v51, 0
	v_mov_b32_e32 v52, 0
	v_mov_b32_e32 v53, 0
	v_mov_b32_e32 v54, 0
	v_mov_b32_e32 v55, 0
	v_mov_b32_e32 v56, 0
	v_mov_b32_e32 v57, 0
	v_mov_b32_e32 v58, 0
	v_mov_b32_e32 v59, 0
	v_mov_b32_e32 v60, 0
	v_mov_b32_e32 v61, 0
	v_mov_b32_e32 v62, 0
	v_mov_b32_e32 v63, 0
	v_mov_b32_e32 v64, 0
	v_mov_b32_e32 v65, 0
	v_mov_b32_e32 v66, 0
	v_mov_b32_e32 v67, 0
	v_mov_b32_e32 v68, 0
	v_mov_b32_e32 v69, 0
	v_mov_b32_e32 v70, 0
	v_mov_b32_e32 v71, 0
	v_mov_b32_e32 v72, 0
	v_mov_b32_e32 v73, 0
	v_mov_b32_e32 v74, 0
	v_mov_b32_e32 v75, 0
	v_mov_b32_e32 v76, 0
	v_mov_b32_e32 v77, 0
	v_mov_b32_e32 v78, 0
	v_mov_b32_e32 v79, 0
	v_mov_b32_e32 v80, 0
	v_mov_b32_e32 v81, 0
	v_mov_b32_e32 v82, 0
	v_mov_b32_e32 v83, 0
	v_mov_b32_e32 v84, 0
	v_mov_b32_e32 v85, 0
	v_mov_b32_e32 v86, 0
	v_mov_b32_e32 v87, 0
	v_mov_b32_e32 v88, 0
	v_mov_b32_e32 v89, 0
	v_mov_b32_e32 v90, 0
	v_mov_b32_e32 v91, 0
	v_mov_b32_e32 v92, 0
	v_mov_b32_e32 v93, 0
	v_mov_b32_e32 v94, 0
	v_mov_b32_e32 v95, 0
	v_mov_b32_e32 v96, 0
	v_mov_b32_e32 v97, 0
	v_mov_b32_e32 v98, 0
	v_mov_b32_e32 v99, 0
	v_mov_b32_e32 v100, 0
	v_mov_b32_e32 v101, 0
	v_mov_b32_e32 v102, 0
	v_mov_b32_e32 v103, 0
	v_mov_b32_e32 v104, 0
	v_mov_b32_e32 v105, 0
	v_mov_b32_e32 v106, 0
	v_mov_b32_e32 v107, 0
	v_mov_b32_e32 v108, 0
	v_mov_b32_e32 v109, 0
	v_mov_b32_e32 v110, 0
	v_mov_b32_e32 v111, 0
	v_mov_b32_e32 v112, 0
	v_mov_b32_e32 v113, 0
	v_mov_b32_e32 v114, 0
	v_mov_b32_e32 v115, 0
	v_mov_b32_e32 v116, 0
	v_mov_b32_e32 v117, 0
	v_mov_b32_e32 v118, 0
	v_mov_b32_e32 v119, 0
	v_mov_b32_e32 v120, 0
	v_mov_b32_e32 v121, 0
	v_mov_b32_e32 v122, 0
	v_mov_b32_e32 v123, 0
	v_mov_b32_e32 v124, 0
	v_mov_b32_e32 v125, 0
	v_mov_b32_e32 v126, 0
	v_mov_b32_e32 v127, 0
	v_mov_b32_e32 v128, 0
	v_mov_b32_e32 v129, 0
	s_waitcnt vmcnt(0)
	s_barrier
	ds_read_b128 v[134:137], v155 offset:16
	ds_read_b128 v[142:145], v159 offset:8208
	ds_read_b128 v[150:153], v239 offset:16
	s_mov_b32 s59, 5
.Lhw_outproj_loop:
	s_waitcnt vmcnt(0)
	s_barrier
	ds_read_b128 v[130:133], v154 offset:24592
	ds_read_b128 v[138:141], v158 offset:32784
	ds_read_b128 v[146:149], v238 offset:24592
	s_waitcnt lgkmcnt(4)
	v_mfma_f32_32x32x16_bf16 v[50:65], v[134:137], v[142:145], v[50:65]
	s_add_u32 m0, s65, 0xc000
	ds_read_b128 v[216:219], v157 offset:16
	global_load_lds_dwordx4 v242, s[66:67]
	s_waitcnt lgkmcnt(4)
	v_mfma_f32_32x32x16_bf16 v[114:129], v[134:137], v[150:153], v[114:129]
	s_add_u32 m0, s65, 0xd000
	ds_read_b128 v[224:227], v237 offset:8208
	global_load_lds_dwordx4 v243, s[66:67]
	s_waitcnt lgkmcnt(4)
	v_mfma_f32_32x32x16_bf16 v[18:33], v[130:133], v[142:145], v[18:33]
	s_add_u32 m0, s65, 0xe000
	ds_read_b128 v[232:235], v241 offset:16
	global_load_lds_dwordx4 v242, s[62:63]
	s_waitcnt lgkmcnt(4)
	v_mfma_f32_32x32x16_bf16 v[34:49], v[134:137], v[138:141], v[34:49]
	s_add_u32 m0, s65, 0xf000
	ds_read_b128 v[212:215], v156 offset:24592
	global_load_lds_dwordx4 v243, s[62:63]
	v_mfma_f32_32x32x16_bf16 v[82:97], v[130:133], v[150:153], v[82:97]
	s_add_u32 m0, s65, 0x10000
	ds_read_b128 v[220:223], v236 offset:32784
	global_load_lds_dwordx4 v242, s[18:19]
	s_waitcnt lgkmcnt(5)
	v_mfma_f32_32x32x16_bf16 v[98:113], v[134:137], v[146:149], v[98:113]
	s_add_u32 m0, s65, 0x11000
	ds_read_b128 v[228:231], v240 offset:24592
	global_load_lds_dwordx4 v243, s[18:19]
	v_mfma_f32_32x32x16_bf16 v[2:17], v[130:133], v[138:141], v[2:17]
	v_mfma_f32_32x32x16_bf16 v[66:81], v[130:133], v[146:149], v[66:81]
	s_waitcnt lgkmcnt(4)
	v_mfma_f32_32x32x16_bf16 v[50:65], v[216:219], v[224:227], v[50:65]
	ds_read_b128 v[130:133], v155 offset:24592
	s_waitcnt lgkmcnt(4)
	v_mfma_f32_32x32x16_bf16 v[114:129], v[216:219], v[232:235], v[114:129]
	ds_read_b128 v[138:141], v159 offset:32784
	s_waitcnt lgkmcnt(4)
	v_mfma_f32_32x32x16_bf16 v[18:33], v[212:215], v[224:227], v[18:33]
	ds_read_b128 v[146:149], v239 offset:24592
	s_waitcnt lgkmcnt(4)
	v_mfma_f32_32x32x16_bf16 v[34:49], v[216:219], v[220:223], v[34:49]
	s_add_u32 s66, s66, 64
	s_addc_u32 s67, s67, 0
	v_mfma_f32_32x32x16_bf16 v[82:97], v[212:215], v[232:235], v[82:97]
	s_add_u32 s62, s62, 64
	s_addc_u32 s63, s63, 0
	s_waitcnt lgkmcnt(3)
	v_mfma_f32_32x32x16_bf16 v[98:113], v[216:219], v[228:231], v[98:113]
	s_add_u32 s18, s18, 64
	s_addc_u32 s19, s19, 0
	v_mfma_f32_32x32x16_bf16 v[2:17], v[212:215], v[220:223], v[2:17]
	v_mfma_f32_32x32x16_bf16 v[66:81], v[212:215], v[228:231], v[66:81]
	s_waitcnt vmcnt(0)
	s_barrier
	ds_read_b128 v[134:137], v154 offset:49168
	ds_read_b128 v[142:145], v158 offset:57360
	ds_read_b128 v[150:153], v238 offset:49168
	s_waitcnt lgkmcnt(4)
	v_mfma_f32_32x32x16_bf16 v[2:17], v[130:133], v[138:141], v[2:17]
	s_add_u32 m0, s65, 0x0
	ds_read_b128 v[212:215], v157 offset:24592
	global_load_lds_dwordx4 v160, s[66:67]
	s_waitcnt lgkmcnt(4)
	v_mfma_f32_32x32x16_bf16 v[66:81], v[130:133], v[146:149], v[66:81]
	s_add_u32 m0, s65, 0x1000
	ds_read_b128 v[220:223], v237 offset:32784
	global_load_lds_dwordx4 v161, s[66:67]
	s_waitcnt lgkmcnt(3)
	v_mfma_f32_32x32x16_bf16 v[18:33], v[130:133], v[142:145], v[18:33]
	s_add_u32 m0, s65, 0x2000
	ds_read_b128 v[228:231], v241 offset:24592
	global_load_lds_dwordx4 v160, s[62:63]
	v_mfma_f32_32x32x16_bf16 v[34:49], v[134:137], v[138:141], v[34:49]
	s_add_u32 m0, s65, 0x3000
	ds_read_b128 v[216:219], v156 offset:49168
	global_load_lds_dwordx4 v161, s[62:63]
	s_waitcnt lgkmcnt(4)
	v_mfma_f32_32x32x16_bf16 v[82:97], v[130:133], v[150:153], v[82:97]
	s_add_u32 m0, s65, 0x4000
	ds_read_b128 v[224:227], v236 offset:57360
	global_load_lds_dwordx4 v160, s[18:19]
	v_mfma_f32_32x32x16_bf16 v[98:113], v[134:137], v[146:149], v[98:113]
	s_add_u32 m0, s65, 0x5000
	ds_read_b128 v[232:235], v240 offset:49168
	global_load_lds_dwordx4 v161, s[18:19]
	v_mfma_f32_32x32x16_bf16 v[50:65], v[134:137], v[142:145], v[50:65]
	v_mfma_f32_32x32x16_bf16 v[114:129], v[134:137], v[150:153], v[114:129]
	s_waitcnt lgkmcnt(4)
	v_mfma_f32_32x32x16_bf16 v[2:17], v[212:215], v[220:223], v[2:17]
	ds_read_b128 v[134:137], v155 offset:49168
	s_waitcnt lgkmcnt(4)
	v_mfma_f32_32x32x16_bf16 v[66:81], v[212:215], v[228:231], v[66:81]
	ds_read_b128 v[142:145], v159 offset:57360
	s_waitcnt lgkmcnt(3)
	v_mfma_f32_32x32x16_bf16 v[18:33], v[212:215], v[224:227], v[18:33]
	ds_read_b128 v[150:153], v239 offset:49168
	v_mfma_f32_32x32x16_bf16 v[34:49], v[216:219], v[220:223], v[34:49]
	s_add_u32 s66, s66, 64
	s_addc_u32 s67, s67, 0
	s_waitcnt lgkmcnt(3)
	v_mfma_f32_32x32x16_bf16 v[82:97], v[212:215], v[232:235], v[82:97]
	s_add_u32 s62, s62, 64
	s_addc_u32 s63, s63, 0
	v_mfma_f32_32x32x16_bf16 v[98:113], v[216:219], v[228:231], v[98:113]
	s_add_u32 s18, s18, 64
	s_addc_u32 s19, s19, 0
	v_mfma_f32_32x32x16_bf16 v[50:65], v[216:219], v[224:227], v[50:65]
	v_mfma_f32_32x32x16_bf16 v[114:129], v[216:219], v[232:235], v[114:129]
	s_waitcnt vmcnt(0)
	s_barrier
	ds_read_b128 v[130:133], v154 offset:16
	ds_read_b128 v[138:141], v158 offset:8208
	ds_read_b128 v[146:149], v238 offset:16
	s_waitcnt lgkmcnt(4)
	v_mfma_f32_32x32x16_bf16 v[50:65], v[134:137], v[142:145], v[50:65]
	s_add_u32 m0, s65, 0x6000
	ds_read_b128 v[216:219], v157 offset:49168
	global_load_lds_dwordx4 v242, s[66:67]
	s_waitcnt lgkmcnt(4)
	v_mfma_f32_32x32x16_bf16 v[114:129], v[134:137], v[150:153], v[114:129]
	s_add_u32 m0, s65, 0x7000
	ds_read_b128 v[224:227], v237 offset:57360
	global_load_lds_dwordx4 v243, s[66:67]
	s_waitcnt lgkmcnt(4)
	v_mfma_f32_32x32x16_bf16 v[18:33], v[130:133], v[142:145], v[18:33]
	s_add_u32 m0, s65, 0x8000
	ds_read_b128 v[232:235], v241 offset:49168
	global_load_lds_dwordx4 v242, s[62:63]
	s_waitcnt lgkmcnt(4)
	v_mfma_f32_32x32x16_bf16 v[34:49], v[134:137], v[138:141], v[34:49]
	s_add_u32 m0, s65, 0x9000
	ds_read_b128 v[212:215], v156 offset:16
	global_load_lds_dwordx4 v243, s[62:63]
	v_mfma_f32_32x32x16_bf16 v[82:97], v[130:133], v[150:153], v[82:97]
	s_add_u32 m0, s65, 0xa000
	ds_read_b128 v[220:223], v236 offset:8208
	global_load_lds_dwordx4 v242, s[18:19]
	s_waitcnt lgkmcnt(5)
	v_mfma_f32_32x32x16_bf16 v[98:113], v[134:137], v[146:149], v[98:113]
	s_add_u32 m0, s65, 0xb000
	ds_read_b128 v[228:231], v240 offset:16
	global_load_lds_dwordx4 v243, s[18:19]
	v_mfma_f32_32x32x16_bf16 v[2:17], v[130:133], v[138:141], v[2:17]
	v_mfma_f32_32x32x16_bf16 v[66:81], v[130:133], v[146:149], v[66:81]
	s_waitcnt lgkmcnt(4)
	v_mfma_f32_32x32x16_bf16 v[50:65], v[216:219], v[224:227], v[50:65]
	ds_read_b128 v[130:133], v155 offset:16
	s_waitcnt lgkmcnt(4)
	v_mfma_f32_32x32x16_bf16 v[114:129], v[216:219], v[232:235], v[114:129]
	ds_read_b128 v[138:141], v159 offset:8208
	s_waitcnt lgkmcnt(4)
	v_mfma_f32_32x32x16_bf16 v[18:33], v[212:215], v[224:227], v[18:33]
	ds_read_b128 v[146:149], v239 offset:16
	s_waitcnt lgkmcnt(4)
	v_mfma_f32_32x32x16_bf16 v[34:49], v[216:219], v[220:223], v[34:49]
	s_add_u32 s66, s66, 64
	s_addc_u32 s67, s67, 0
	v_mfma_f32_32x32x16_bf16 v[82:97], v[212:215], v[232:235], v[82:97]
	s_add_u32 s62, s62, 64
	s_addc_u32 s63, s63, 0
	s_waitcnt lgkmcnt(3)
	v_mfma_f32_32x32x16_bf16 v[98:113], v[216:219], v[228:231], v[98:113]
	s_add_u32 s18, s18, 64
	s_addc_u32 s19, s19, 0
	v_mfma_f32_32x32x16_bf16 v[2:17], v[212:215], v[220:223], v[2:17]
	v_mfma_f32_32x32x16_bf16 v[66:81], v[212:215], v[228:231], v[66:81]
	s_waitcnt vmcnt(0)
	s_barrier
	ds_read_b128 v[134:137], v154 offset:24592
	ds_read_b128 v[142:145], v158 offset:32784
	ds_read_b128 v[150:153], v238 offset:24592
	s_waitcnt lgkmcnt(4)
	v_mfma_f32_32x32x16_bf16 v[2:17], v[130:133], v[138:141], v[2:17]
	s_add_u32 m0, s65, 0xc000
	ds_read_b128 v[212:215], v157 offset:16
	global_load_lds_dwordx4 v160, s[66:67]
	s_waitcnt lgkmcnt(4)
	v_mfma_f32_32x32x16_bf16 v[66:81], v[130:133], v[146:149], v[66:81]
	s_add_u32 m0, s65, 0xd000
	ds_read_b128 v[220:223], v237 offset:8208
	global_load_lds_dwordx4 v161, s[66:67]
	s_waitcnt lgkmcnt(3)
	v_mfma_f32_32x32x16_bf16 v[18:33], v[130:133], v[142:145], v[18:33]
	s_add_u32 m0, s65, 0xe000
	ds_read_b128 v[228:231], v241 offset:16
	global_load_lds_dwordx4 v160, s[62:63]
	v_mfma_f32_32x32x16_bf16 v[34:49], v[134:137], v[138:141], v[34:49]
	s_add_u32 m0, s65, 0xf000
	ds_read_b128 v[216:219], v156 offset:24592
	global_load_lds_dwordx4 v161, s[62:63]
	s_waitcnt lgkmcnt(4)
	v_mfma_f32_32x32x16_bf16 v[82:97], v[130:133], v[150:153], v[82:97]
	s_add_u32 m0, s65, 0x10000
	ds_read_b128 v[224:227], v236 offset:32784
	global_load_lds_dwordx4 v160, s[18:19]
	v_mfma_f32_32x32x16_bf16 v[98:113], v[134:137], v[146:149], v[98:113]
	s_add_u32 m0, s65, 0x11000
	ds_read_b128 v[232:235], v240 offset:24592
	global_load_lds_dwordx4 v161, s[18:19]
	v_mfma_f32_32x32x16_bf16 v[50:65], v[134:137], v[142:145], v[50:65]
	v_mfma_f32_32x32x16_bf16 v[114:129], v[134:137], v[150:153], v[114:129]
	s_waitcnt lgkmcnt(4)
	v_mfma_f32_32x32x16_bf16 v[2:17], v[212:215], v[220:223], v[2:17]
	ds_read_b128 v[134:137], v155 offset:24592
	s_waitcnt lgkmcnt(4)
	v_mfma_f32_32x32x16_bf16 v[66:81], v[212:215], v[228:231], v[66:81]
	ds_read_b128 v[142:145], v159 offset:32784
	s_waitcnt lgkmcnt(3)
	v_mfma_f32_32x32x16_bf16 v[18:33], v[212:215], v[224:227], v[18:33]
	ds_read_b128 v[150:153], v239 offset:24592
	v_mfma_f32_32x32x16_bf16 v[34:49], v[216:219], v[220:223], v[34:49]
	s_add_u32 s66, s66, 64
	s_addc_u32 s67, s67, 0
	s_waitcnt lgkmcnt(3)
	v_mfma_f32_32x32x16_bf16 v[82:97], v[212:215], v[232:235], v[82:97]
	s_add_u32 s62, s62, 64
	s_addc_u32 s63, s63, 0
	v_mfma_f32_32x32x16_bf16 v[98:113], v[216:219], v[228:231], v[98:113]
	s_add_u32 s18, s18, 64
	s_addc_u32 s19, s19, 0
	v_mfma_f32_32x32x16_bf16 v[50:65], v[216:219], v[224:227], v[50:65]
	v_mfma_f32_32x32x16_bf16 v[114:129], v[216:219], v[232:235], v[114:129]
	s_waitcnt vmcnt(0)
	s_barrier
	ds_read_b128 v[130:133], v154 offset:49168
	ds_read_b128 v[138:141], v158 offset:57360
	ds_read_b128 v[146:149], v238 offset:49168
	s_waitcnt lgkmcnt(4)
	v_mfma_f32_32x32x16_bf16 v[50:65], v[134:137], v[142:145], v[50:65]
	s_add_u32 m0, s65, 0x0
	ds_read_b128 v[216:219], v157 offset:24592
	global_load_lds_dwordx4 v242, s[66:67]
	s_waitcnt lgkmcnt(4)
	v_mfma_f32_32x32x16_bf16 v[114:129], v[134:137], v[150:153], v[114:129]
	s_add_u32 m0, s65, 0x1000
	ds_read_b128 v[224:227], v237 offset:32784
	global_load_lds_dwordx4 v243, s[66:67]
	s_waitcnt lgkmcnt(4)
	v_mfma_f32_32x32x16_bf16 v[18:33], v[130:133], v[142:145], v[18:33]
	s_add_u32 m0, s65, 0x2000
	ds_read_b128 v[232:235], v241 offset:24592
	global_load_lds_dwordx4 v242, s[62:63]
	s_waitcnt lgkmcnt(4)
	v_mfma_f32_32x32x16_bf16 v[34:49], v[134:137], v[138:141], v[34:49]
	s_add_u32 m0, s65, 0x3000
	ds_read_b128 v[212:215], v156 offset:49168
	global_load_lds_dwordx4 v243, s[62:63]
	v_mfma_f32_32x32x16_bf16 v[82:97], v[130:133], v[150:153], v[82:97]
	s_add_u32 m0, s65, 0x4000
	ds_read_b128 v[220:223], v236 offset:57360
	global_load_lds_dwordx4 v242, s[18:19]
	s_waitcnt lgkmcnt(5)
	v_mfma_f32_32x32x16_bf16 v[98:113], v[134:137], v[146:149], v[98:113]
	s_add_u32 m0, s65, 0x5000
	ds_read_b128 v[228:231], v240 offset:49168
	global_load_lds_dwordx4 v243, s[18:19]
	v_mfma_f32_32x32x16_bf16 v[2:17], v[130:133], v[138:141], v[2:17]
	v_mfma_f32_32x32x16_bf16 v[66:81], v[130:133], v[146:149], v[66:81]
	s_waitcnt lgkmcnt(4)
	v_mfma_f32_32x32x16_bf16 v[50:65], v[216:219], v[224:227], v[50:65]
	ds_read_b128 v[130:133], v155 offset:49168
	s_waitcnt lgkmcnt(4)
	v_mfma_f32_32x32x16_bf16 v[114:129], v[216:219], v[232:235], v[114:129]
	ds_read_b128 v[138:141], v159 offset:57360
	s_waitcnt lgkmcnt(4)
	v_mfma_f32_32x32x16_bf16 v[18:33], v[212:215], v[224:227], v[18:33]
	ds_read_b128 v[146:149], v239 offset:49168
	s_waitcnt lgkmcnt(4)
	v_mfma_f32_32x32x16_bf16 v[34:49], v[216:219], v[220:223], v[34:49]
	s_add_u32 s66, s66, 64
	s_addc_u32 s67, s67, 0
	v_mfma_f32_32x32x16_bf16 v[82:97], v[212:215], v[232:235], v[82:97]
	s_add_u32 s62, s62, 64
	s_addc_u32 s63, s63, 0
	s_waitcnt lgkmcnt(3)
	v_mfma_f32_32x32x16_bf16 v[98:113], v[216:219], v[228:231], v[98:113]
	s_add_u32 s18, s18, 64
	s_addc_u32 s19, s19, 0
	v_mfma_f32_32x32x16_bf16 v[2:17], v[212:215], v[220:223], v[2:17]
	v_mfma_f32_32x32x16_bf16 v[66:81], v[212:215], v[228:231], v[66:81]
	s_waitcnt vmcnt(0)
	s_barrier
	ds_read_b128 v[134:137], v154 offset:16
	ds_read_b128 v[142:145], v158 offset:8208
	ds_read_b128 v[150:153], v238 offset:16
	s_waitcnt lgkmcnt(4)
	v_mfma_f32_32x32x16_bf16 v[2:17], v[130:133], v[138:141], v[2:17]
	s_add_u32 m0, s65, 0x6000
	ds_read_b128 v[212:215], v157 offset:49168
	global_load_lds_dwordx4 v160, s[66:67]
	s_waitcnt lgkmcnt(4)
	v_mfma_f32_32x32x16_bf16 v[66:81], v[130:133], v[146:149], v[66:81]
	s_add_u32 m0, s65, 0x7000
	ds_read_b128 v[220:223], v237 offset:57360
	global_load_lds_dwordx4 v161, s[66:67]
	s_waitcnt lgkmcnt(3)
	v_mfma_f32_32x32x16_bf16 v[18:33], v[130:133], v[142:145], v[18:33]
	s_add_u32 m0, s65, 0x8000
	ds_read_b128 v[228:231], v241 offset:49168
	global_load_lds_dwordx4 v160, s[62:63]
	v_mfma_f32_32x32x16_bf16 v[34:49], v[134:137], v[138:141], v[34:49]
	s_add_u32 m0, s65, 0x9000
	ds_read_b128 v[216:219], v156 offset:16
	global_load_lds_dwordx4 v161, s[62:63]
	s_waitcnt lgkmcnt(4)
	v_mfma_f32_32x32x16_bf16 v[82:97], v[130:133], v[150:153], v[82:97]
	s_add_u32 m0, s65, 0xa000
	ds_read_b128 v[224:227], v236 offset:8208
	global_load_lds_dwordx4 v160, s[18:19]
	v_mfma_f32_32x32x16_bf16 v[98:113], v[134:137], v[146:149], v[98:113]
	s_add_u32 m0, s65, 0xb000
	ds_read_b128 v[232:235], v240 offset:16
	global_load_lds_dwordx4 v161, s[18:19]
	v_mfma_f32_32x32x16_bf16 v[50:65], v[134:137], v[142:145], v[50:65]
	v_mfma_f32_32x32x16_bf16 v[114:129], v[134:137], v[150:153], v[114:129]
	s_waitcnt lgkmcnt(4)
	v_mfma_f32_32x32x16_bf16 v[2:17], v[212:215], v[220:223], v[2:17]
	ds_read_b128 v[134:137], v155 offset:16
	s_waitcnt lgkmcnt(4)
	v_mfma_f32_32x32x16_bf16 v[66:81], v[212:215], v[228:231], v[66:81]
	ds_read_b128 v[142:145], v159 offset:8208
	s_waitcnt lgkmcnt(3)
	v_mfma_f32_32x32x16_bf16 v[18:33], v[212:215], v[224:227], v[18:33]
	ds_read_b128 v[150:153], v239 offset:16
	v_mfma_f32_32x32x16_bf16 v[34:49], v[216:219], v[220:223], v[34:49]
	s_add_u32 s66, s66, 64
	s_addc_u32 s67, s67, 0
	s_waitcnt lgkmcnt(3)
	v_mfma_f32_32x32x16_bf16 v[82:97], v[212:215], v[232:235], v[82:97]
	s_add_u32 s62, s62, 64
	s_addc_u32 s63, s63, 0
	v_mfma_f32_32x32x16_bf16 v[98:113], v[216:219], v[228:231], v[98:113]
	s_add_u32 s18, s18, 64
	s_addc_u32 s19, s19, 0
	v_mfma_f32_32x32x16_bf16 v[50:65], v[216:219], v[224:227], v[50:65]
	v_mfma_f32_32x32x16_bf16 v[114:129], v[216:219], v[232:235], v[114:129]
	s_sub_u32 s59, s59, 1
	s_cmp_lg_u32 s59, 0
	s_cbranch_scc1 .Lhw_outproj_loop
	s_waitcnt vmcnt(0)
	s_barrier
	ds_read_b128 v[130:133], v154 offset:24592
	ds_read_b128 v[138:141], v158 offset:32784
	ds_read_b128 v[146:149], v238 offset:24592
	s_waitcnt lgkmcnt(4)
	v_mfma_f32_32x32x16_bf16 v[50:65], v[134:137], v[142:145], v[50:65]
	s_add_u32 m0, s65, 0xc000
	ds_read_b128 v[216:219], v157 offset:16
	global_load_lds_dwordx4 v242, s[66:67]
	s_waitcnt lgkmcnt(4)
	v_mfma_f32_32x32x16_bf16 v[114:129], v[134:137], v[150:153], v[114:129]
	s_add_u32 m0, s65, 0xd000
	ds_read_b128 v[224:227], v237 offset:8208
	global_load_lds_dwordx4 v243, s[66:67]
	s_waitcnt lgkmcnt(4)
	v_mfma_f32_32x32x16_bf16 v[18:33], v[130:133], v[142:145], v[18:33]
	s_add_u32 m0, s65, 0xe000
	ds_read_b128 v[232:235], v241 offset:16
	global_load_lds_dwordx4 v242, s[62:63]
	s_waitcnt lgkmcnt(4)
	v_mfma_f32_32x32x16_bf16 v[34:49], v[134:137], v[138:141], v[34:49]
	s_add_u32 m0, s65, 0xf000
	ds_read_b128 v[212:215], v156 offset:24592
	global_load_lds_dwordx4 v243, s[62:63]
	v_mfma_f32_32x32x16_bf16 v[82:97], v[130:133], v[150:153], v[82:97]
	s_add_u32 m0, s65, 0x10000
	ds_read_b128 v[220:223], v236 offset:32784
	global_load_lds_dwordx4 v242, s[18:19]
	s_waitcnt lgkmcnt(5)
	v_mfma_f32_32x32x16_bf16 v[98:113], v[134:137], v[146:149], v[98:113]
	s_add_u32 m0, s65, 0x11000
	ds_read_b128 v[228:231], v240 offset:24592
	global_load_lds_dwordx4 v243, s[18:19]
	v_mfma_f32_32x32x16_bf16 v[2:17], v[130:133], v[138:141], v[2:17]
	v_mfma_f32_32x32x16_bf16 v[66:81], v[130:133], v[146:149], v[66:81]
	s_waitcnt lgkmcnt(4)
	v_mfma_f32_32x32x16_bf16 v[50:65], v[216:219], v[224:227], v[50:65]
	ds_read_b128 v[130:133], v155 offset:24592
	s_waitcnt lgkmcnt(4)
	v_mfma_f32_32x32x16_bf16 v[114:129], v[216:219], v[232:235], v[114:129]
	ds_read_b128 v[138:141], v159 offset:32784
	s_waitcnt lgkmcnt(4)
	v_mfma_f32_32x32x16_bf16 v[18:33], v[212:215], v[224:227], v[18:33]
	ds_read_b128 v[146:149], v239 offset:24592
	s_waitcnt lgkmcnt(4)
	v_mfma_f32_32x32x16_bf16 v[34:49], v[216:219], v[220:223], v[34:49]
	s_add_u32 s66, s66, 64
	s_addc_u32 s67, s67, 0
	v_mfma_f32_32x32x16_bf16 v[82:97], v[212:215], v[232:235], v[82:97]
	s_add_u32 s62, s62, 64
	s_addc_u32 s63, s63, 0
	s_waitcnt lgkmcnt(3)
	v_mfma_f32_32x32x16_bf16 v[98:113], v[216:219], v[228:231], v[98:113]
	s_add_u32 s18, s18, 64
	s_addc_u32 s19, s19, 0
	v_mfma_f32_32x32x16_bf16 v[2:17], v[212:215], v[220:223], v[2:17]
	v_mfma_f32_32x32x16_bf16 v[66:81], v[212:215], v[228:231], v[66:81]
	s_waitcnt vmcnt(0)
	s_barrier
	ds_read_b128 v[134:137], v154 offset:49168
	ds_read_b128 v[142:145], v158 offset:57360
	ds_read_b128 v[150:153], v238 offset:49168
	s_waitcnt lgkmcnt(4)
	v_mfma_f32_32x32x16_bf16 v[2:17], v[130:133], v[138:141], v[2:17]
	ds_read_b128 v[212:215], v157 offset:24592
	s_waitcnt lgkmcnt(4)
	v_mfma_f32_32x32x16_bf16 v[66:81], v[130:133], v[146:149], v[66:81]
	ds_read_b128 v[220:223], v237 offset:32784
	s_waitcnt lgkmcnt(3)
	v_mfma_f32_32x32x16_bf16 v[18:33], v[130:133], v[142:145], v[18:33]
	ds_read_b128 v[228:231], v241 offset:24592
	v_mfma_f32_32x32x16_bf16 v[34:49], v[134:137], v[138:141], v[34:49]
	ds_read_b128 v[216:219], v156 offset:49168
	s_waitcnt lgkmcnt(4)
	v_mfma_f32_32x32x16_bf16 v[82:97], v[130:133], v[150:153], v[82:97]
	ds_read_b128 v[224:227], v236 offset:57360
	v_mfma_f32_32x32x16_bf16 v[98:113], v[134:137], v[146:149], v[98:113]
	ds_read_b128 v[232:235], v240 offset:49168
	v_mfma_f32_32x32x16_bf16 v[50:65], v[134:137], v[142:145], v[50:65]
	v_mfma_f32_32x32x16_bf16 v[114:129], v[134:137], v[150:153], v[114:129]
	s_waitcnt lgkmcnt(4)
	v_mfma_f32_32x32x16_bf16 v[2:17], v[212:215], v[220:223], v[2:17]
	s_waitcnt lgkmcnt(3)
	v_mfma_f32_32x32x16_bf16 v[66:81], v[212:215], v[228:231], v[66:81]
	s_waitcnt lgkmcnt(1)
	v_mfma_f32_32x32x16_bf16 v[18:33], v[212:215], v[224:227], v[18:33]
	v_mfma_f32_32x32x16_bf16 v[34:49], v[216:219], v[220:223], v[34:49]
	s_waitcnt lgkmcnt(0)
	v_mfma_f32_32x32x16_bf16 v[82:97], v[212:215], v[232:235], v[82:97]
	v_mfma_f32_32x32x16_bf16 v[98:113], v[216:219], v[228:231], v[98:113]
	v_mfma_f32_32x32x16_bf16 v[50:65], v[216:219], v[224:227], v[50:65]
	v_mfma_f32_32x32x16_bf16 v[114:129], v[216:219], v[232:235], v[114:129]
	s_nop 7
	s_nop 7
	s_sub_i32 s2, s6, 0x1000
	s_ashr_i32 s2, s2, 11
	s_add_i32 s2, s2, 1
	s_max_i32 s2, s2, 0
	v_readlane_b32 s17, v246, 28
	s_nop 0
	s_add_i32 s2, s2, s17
	s_mul_i32 s2, s2, 0x9000
	s_lshl_b32 s17, s15, 2
	s_add_u32 s2, s2, s17
	s_add_u32 s60, s8, s2
	s_addc_u32 s61, s9, 0
	s_lshr_b32 s2, s15, 7
	s_mul_i32 s2, s2, 0x18000
	s_lshl_b32 s20, s6, 2
	s_add_u32 s2, s2, s20
	s_add_u32 s10, s44, s2
	s_addc_u32 s11, s45, 0
	s_lshl_b32 s2, s6, 12
	s_add_u32 s2, s2, s17
	s_add_u32 s48, s40, s2
	s_addc_u32 s49, s41, 0
	global_load_dword v175, v166, s[60:61]
	global_load_dword v176, v166, s[60:61] offset:128
	global_load_dword v130, v162, s[48:49]
	global_load_dword v212, v162, s[48:49] offset:128
	global_load_dword v131, v163, s[48:49]
	global_load_dword v213, v163, s[48:49] offset:128
	global_load_dword v132, v164, s[48:49]
	global_load_dword v214, v164, s[48:49] offset:128
	global_load_dword v133, v165, s[48:49]
	global_load_dword v215, v165, s[48:49] offset:128
	s_add_u32 s48, s48, 0x8000
	s_addc_u32 s49, s49, 0
	global_load_dword v134, v162, s[48:49]
	global_load_dword v216, v162, s[48:49] offset:128
	global_load_dword v135, v163, s[48:49]
	global_load_dword v217, v163, s[48:49] offset:128
	global_load_dword v136, v164, s[48:49]
	global_load_dword v218, v164, s[48:49] offset:128
	global_load_dword v137, v165, s[48:49]
	global_load_dword v219, v165, s[48:49] offset:128
	s_add_u32 s48, s48, 0x8000
	s_addc_u32 s49, s49, 0
	global_load_dword v138, v162, s[48:49]
	global_load_dword v220, v162, s[48:49] offset:128
	global_load_dword v139, v163, s[48:49]
	global_load_dword v221, v163, s[48:49] offset:128
	global_load_dword v140, v164, s[48:49]
	global_load_dword v222, v164, s[48:49] offset:128
	global_load_dword v141, v165, s[48:49]
	global_load_dword v223, v165, s[48:49] offset:128
	s_add_u32 s48, s48, 0x8000
	s_addc_u32 s49, s49, 0
	global_load_dword v142, v162, s[48:49]
	global_load_dword v224, v162, s[48:49] offset:128
	global_load_dword v143, v163, s[48:49]
	global_load_dword v225, v163, s[48:49] offset:128
	global_load_dword v144, v164, s[48:49]
	global_load_dword v226, v164, s[48:49] offset:128
	global_load_dword v145, v165, s[48:49]
	global_load_dword v227, v165, s[48:49] offset:128
	s_sub_u32 s48, s48, 0x18000
	s_subb_u32 s49, s49, 0
	s_waitcnt vmcnt(32)
	s_waitcnt vmcnt(30)
	v_fmac_f32_e32 v130, v2, v175
	v_fmac_f32_e32 v212, v18, v176
	global_store_dword v162, v130, s[48:49]
	global_store_dword v162, v212, s[48:49] offset:128
	s_waitcnt vmcnt(30)
	v_fmac_f32_e32 v131, v3, v175
	v_fmac_f32_e32 v213, v19, v176
	global_store_dword v163, v131, s[48:49]
	global_store_dword v163, v213, s[48:49] offset:128
	s_waitcnt vmcnt(30)
	v_fmac_f32_e32 v132, v4, v175
	v_fmac_f32_e32 v214, v20, v176
	global_store_dword v164, v132, s[48:49]
	global_store_dword v164, v214, s[48:49] offset:128
	s_waitcnt vmcnt(30)
	v_fmac_f32_e32 v133, v5, v175
	v_fmac_f32_e32 v215, v21, v176
	global_store_dword v165, v133, s[48:49]
	global_store_dword v165, v215, s[48:49] offset:128
	s_add_u32 s48, s48, 0x8000
	s_addc_u32 s49, s49, 0
	s_waitcnt vmcnt(30)
	v_fmac_f32_e32 v134, v6, v175
	v_fmac_f32_e32 v216, v22, v176
	global_store_dword v162, v134, s[48:49]
	global_store_dword v162, v216, s[48:49] offset:128
	s_waitcnt vmcnt(30)
	v_fmac_f32_e32 v135, v7, v175
	v_fmac_f32_e32 v217, v23, v176
	global_store_dword v163, v135, s[48:49]
	global_store_dword v163, v217, s[48:49] offset:128
	s_waitcnt vmcnt(30)
	v_fmac_f32_e32 v136, v8, v175
	v_fmac_f32_e32 v218, v24, v176
	global_store_dword v164, v136, s[48:49]
	global_store_dword v164, v218, s[48:49] offset:128
	s_waitcnt vmcnt(30)
	v_fmac_f32_e32 v137, v9, v175
	v_fmac_f32_e32 v219, v25, v176
	global_store_dword v165, v137, s[48:49]
	global_store_dword v165, v219, s[48:49] offset:128
	s_add_u32 s48, s48, 0x8000
	s_addc_u32 s49, s49, 0
	s_waitcnt vmcnt(30)
	v_fmac_f32_e32 v138, v10, v175
	v_fmac_f32_e32 v220, v26, v176
	global_store_dword v162, v138, s[48:49]
	global_store_dword v162, v220, s[48:49] offset:128
	s_waitcnt vmcnt(30)
	v_fmac_f32_e32 v139, v11, v175
	v_fmac_f32_e32 v221, v27, v176
	global_store_dword v163, v139, s[48:49]
	global_store_dword v163, v221, s[48:49] offset:128
	s_waitcnt vmcnt(30)
	v_fmac_f32_e32 v140, v12, v175
	v_fmac_f32_e32 v222, v28, v176
	global_store_dword v164, v140, s[48:49]
	global_store_dword v164, v222, s[48:49] offset:128
	s_waitcnt vmcnt(30)
	v_fmac_f32_e32 v141, v13, v175
	v_fmac_f32_e32 v223, v29, v176
	global_store_dword v165, v141, s[48:49]
	global_store_dword v165, v223, s[48:49] offset:128
	s_add_u32 s48, s48, 0x8000
	s_addc_u32 s49, s49, 0
	s_waitcnt vmcnt(30)
	v_fmac_f32_e32 v142, v14, v175
	v_fmac_f32_e32 v224, v30, v176
	global_store_dword v162, v142, s[48:49]
	global_store_dword v162, v224, s[48:49] offset:128
	s_waitcnt vmcnt(30)
	v_fmac_f32_e32 v143, v15, v175
	v_fmac_f32_e32 v225, v31, v176
	global_store_dword v163, v143, s[48:49]
	global_store_dword v163, v225, s[48:49] offset:128
	s_waitcnt vmcnt(30)
	v_fmac_f32_e32 v144, v16, v175
	v_fmac_f32_e32 v226, v32, v176
	global_store_dword v164, v144, s[48:49]
	global_store_dword v164, v226, s[48:49] offset:128
	s_waitcnt vmcnt(30)
	v_fmac_f32_e32 v145, v17, v175
	v_fmac_f32_e32 v227, v33, v176
	global_store_dword v165, v145, s[48:49]
	global_store_dword v165, v227, s[48:49] offset:128
	s_sub_u32 s48, s48, 0x18000
	s_subb_u32 s49, s49, 0
	v_mul_f32_e32 v130, v130, v130
	v_fmac_f32_e32 v130, v212, v212
	v_mul_f32_e32 v131, v131, v131
	v_fmac_f32_e32 v131, v213, v213
	v_mul_f32_e32 v132, v132, v132
	v_fmac_f32_e32 v132, v214, v214
	v_mul_f32_e32 v133, v133, v133
	v_fmac_f32_e32 v133, v215, v215
	v_mul_f32_e32 v134, v134, v134
	v_fmac_f32_e32 v134, v216, v216
	v_mul_f32_e32 v135, v135, v135
	v_fmac_f32_e32 v135, v217, v217
	v_mul_f32_e32 v136, v136, v136
	v_fmac_f32_e32 v136, v218, v218
	v_mul_f32_e32 v137, v137, v137
	v_fmac_f32_e32 v137, v219, v219
	v_mul_f32_e32 v138, v138, v138
	v_fmac_f32_e32 v138, v220, v220
	v_mul_f32_e32 v139, v139, v139
	v_fmac_f32_e32 v139, v221, v221
	v_mul_f32_e32 v140, v140, v140
	v_fmac_f32_e32 v140, v222, v222
	v_mul_f32_e32 v141, v141, v141
	v_fmac_f32_e32 v141, v223, v223
	v_mul_f32_e32 v142, v142, v142
	v_fmac_f32_e32 v142, v224, v224
	v_mul_f32_e32 v143, v143, v143
	v_fmac_f32_e32 v143, v225, v225
	v_mul_f32_e32 v144, v144, v144
	v_fmac_f32_e32 v144, v226, v226
	v_mul_f32_e32 v145, v145, v145
	v_fmac_f32_e32 v145, v227, v227
	s_waitcnt lgkmcnt(0)
	ds_bpermute_b32 v212, v168, v130
	ds_bpermute_b32 v213, v168, v131
	ds_bpermute_b32 v214, v168, v132
	ds_bpermute_b32 v215, v168, v133
	ds_bpermute_b32 v216, v168, v134
	ds_bpermute_b32 v217, v168, v135
	ds_bpermute_b32 v218, v168, v136
	ds_bpermute_b32 v219, v168, v137
	s_waitcnt lgkmcnt(7)
	v_add_f32_e32 v130, v130, v212
	s_waitcnt lgkmcnt(6)
	v_add_f32_e32 v131, v131, v213
	s_waitcnt lgkmcnt(5)
	v_add_f32_e32 v132, v132, v214
	s_waitcnt lgkmcnt(4)
	v_add_f32_e32 v133, v133, v215
	s_waitcnt lgkmcnt(3)
	v_add_f32_e32 v134, v134, v216
	s_waitcnt lgkmcnt(2)
	v_add_f32_e32 v135, v135, v217
	s_waitcnt lgkmcnt(1)
	v_add_f32_e32 v136, v136, v218
	s_waitcnt lgkmcnt(0)
	v_add_f32_e32 v137, v137, v219
	ds_bpermute_b32 v212, v169, v130
	ds_bpermute_b32 v213, v169, v131
	ds_bpermute_b32 v214, v169, v132
	ds_bpermute_b32 v215, v169, v133
	ds_bpermute_b32 v216, v169, v134
	ds_bpermute_b32 v217, v169, v135
	ds_bpermute_b32 v218, v169, v136
	ds_bpermute_b32 v219, v169, v137
	s_waitcnt lgkmcnt(7)
	v_add_f32_e32 v130, v130, v212
	s_waitcnt lgkmcnt(6)
	v_add_f32_e32 v131, v131, v213
	s_waitcnt lgkmcnt(5)
	v_add_f32_e32 v132, v132, v214
	s_waitcnt lgkmcnt(4)
	v_add_f32_e32 v133, v133, v215
	s_waitcnt lgkmcnt(3)
	v_add_f32_e32 v134, v134, v216
	s_waitcnt lgkmcnt(2)
	v_add_f32_e32 v135, v135, v217
	s_waitcnt lgkmcnt(1)
	v_add_f32_e32 v136, v136, v218
	s_waitcnt lgkmcnt(0)
	v_add_f32_e32 v137, v137, v219
	ds_bpermute_b32 v212, v171, v130
	ds_bpermute_b32 v213, v171, v131
	ds_bpermute_b32 v214, v171, v132
	ds_bpermute_b32 v215, v171, v133
	ds_bpermute_b32 v216, v171, v134
	ds_bpermute_b32 v217, v171, v135
	ds_bpermute_b32 v218, v171, v136
	ds_bpermute_b32 v219, v171, v137
	s_waitcnt lgkmcnt(7)
	v_add_f32_e32 v130, v130, v212
	s_waitcnt lgkmcnt(6)
	v_add_f32_e32 v131, v131, v213
	s_waitcnt lgkmcnt(5)
	v_add_f32_e32 v132, v132, v214
	s_waitcnt lgkmcnt(4)
	v_add_f32_e32 v133, v133, v215
	s_waitcnt lgkmcnt(3)
	v_add_f32_e32 v134, v134, v216
	s_waitcnt lgkmcnt(2)
	v_add_f32_e32 v135, v135, v217
	s_waitcnt lgkmcnt(1)
	v_add_f32_e32 v136, v136, v218
	s_waitcnt lgkmcnt(0)
	v_add_f32_e32 v137, v137, v219
	ds_bpermute_b32 v212, v172, v130
	ds_bpermute_b32 v213, v172, v131
	ds_bpermute_b32 v214, v172, v132
	ds_bpermute_b32 v215, v172, v133
	ds_bpermute_b32 v216, v172, v134
	ds_bpermute_b32 v217, v172, v135
	ds_bpermute_b32 v218, v172, v136
	ds_bpermute_b32 v219, v172, v137
	s_waitcnt lgkmcnt(7)
	v_add_f32_e32 v130, v130, v212
	s_waitcnt lgkmcnt(6)
	v_add_f32_e32 v131, v131, v213
	s_waitcnt lgkmcnt(5)
	v_add_f32_e32 v132, v132, v214
	s_waitcnt lgkmcnt(4)
	v_add_f32_e32 v133, v133, v215
	s_waitcnt lgkmcnt(3)
	v_add_f32_e32 v134, v134, v216
	s_waitcnt lgkmcnt(2)
	v_add_f32_e32 v135, v135, v217
	s_waitcnt lgkmcnt(1)
	v_add_f32_e32 v136, v136, v218
	s_waitcnt lgkmcnt(0)
	v_add_f32_e32 v137, v137, v219
	ds_bpermute_b32 v212, v173, v130
	ds_bpermute_b32 v213, v173, v131
	ds_bpermute_b32 v214, v173, v132
	ds_bpermute_b32 v215, v173, v133
	ds_bpermute_b32 v216, v173, v134
	ds_bpermute_b32 v217, v173, v135
	ds_bpermute_b32 v218, v173, v136
	ds_bpermute_b32 v219, v173, v137
	s_waitcnt lgkmcnt(7)
	v_add_f32_e32 v130, v130, v212
	s_waitcnt lgkmcnt(6)
	v_add_f32_e32 v131, v131, v213
	s_waitcnt lgkmcnt(5)
	v_add_f32_e32 v132, v132, v214
	s_waitcnt lgkmcnt(4)
	v_add_f32_e32 v133, v133, v215
	s_waitcnt lgkmcnt(3)
	v_add_f32_e32 v134, v134, v216
	s_waitcnt lgkmcnt(2)
	v_add_f32_e32 v135, v135, v217
	s_waitcnt lgkmcnt(1)
	v_add_f32_e32 v136, v136, v218
	s_waitcnt lgkmcnt(0)
	v_add_f32_e32 v137, v137, v219
	ds_bpermute_b32 v220, v168, v138
	ds_bpermute_b32 v221, v168, v139
	ds_bpermute_b32 v222, v168, v140
	ds_bpermute_b32 v223, v168, v141
	ds_bpermute_b32 v224, v168, v142
	ds_bpermute_b32 v225, v168, v143
	ds_bpermute_b32 v226, v168, v144
	ds_bpermute_b32 v227, v168, v145
	s_waitcnt lgkmcnt(7)
	v_add_f32_e32 v138, v138, v220
	s_waitcnt lgkmcnt(6)
	v_add_f32_e32 v139, v139, v221
	s_waitcnt lgkmcnt(5)
	v_add_f32_e32 v140, v140, v222
	s_waitcnt lgkmcnt(4)
	v_add_f32_e32 v141, v141, v223
	s_waitcnt lgkmcnt(3)
	v_add_f32_e32 v142, v142, v224
	s_waitcnt lgkmcnt(2)
	v_add_f32_e32 v143, v143, v225
	s_waitcnt lgkmcnt(1)
	v_add_f32_e32 v144, v144, v226
	s_waitcnt lgkmcnt(0)
	v_add_f32_e32 v145, v145, v227
	ds_bpermute_b32 v220, v169, v138
	ds_bpermute_b32 v221, v169, v139
	ds_bpermute_b32 v222, v169, v140
	ds_bpermute_b32 v223, v169, v141
	ds_bpermute_b32 v224, v169, v142
	ds_bpermute_b32 v225, v169, v143
	ds_bpermute_b32 v226, v169, v144
	ds_bpermute_b32 v227, v169, v145
	s_waitcnt lgkmcnt(7)
	v_add_f32_e32 v138, v138, v220
	s_waitcnt lgkmcnt(6)
	v_add_f32_e32 v139, v139, v221
	s_waitcnt lgkmcnt(5)
	v_add_f32_e32 v140, v140, v222
	s_waitcnt lgkmcnt(4)
	v_add_f32_e32 v141, v141, v223
	s_waitcnt lgkmcnt(3)
	v_add_f32_e32 v142, v142, v224
	s_waitcnt lgkmcnt(2)
	v_add_f32_e32 v143, v143, v225
	s_waitcnt lgkmcnt(1)
	v_add_f32_e32 v144, v144, v226
	s_waitcnt lgkmcnt(0)
	v_add_f32_e32 v145, v145, v227
	ds_bpermute_b32 v220, v171, v138
	ds_bpermute_b32 v221, v171, v139
	ds_bpermute_b32 v222, v171, v140
	ds_bpermute_b32 v223, v171, v141
	ds_bpermute_b32 v224, v171, v142
	ds_bpermute_b32 v225, v171, v143
	ds_bpermute_b32 v226, v171, v144
	ds_bpermute_b32 v227, v171, v145
	s_waitcnt lgkmcnt(7)
	v_add_f32_e32 v138, v138, v220
	s_waitcnt lgkmcnt(6)
	v_add_f32_e32 v139, v139, v221
	s_waitcnt lgkmcnt(5)
	v_add_f32_e32 v140, v140, v222
	s_waitcnt lgkmcnt(4)
	v_add_f32_e32 v141, v141, v223
	s_waitcnt lgkmcnt(3)
	v_add_f32_e32 v142, v142, v224
	s_waitcnt lgkmcnt(2)
	v_add_f32_e32 v143, v143, v225
	s_waitcnt lgkmcnt(1)
	v_add_f32_e32 v144, v144, v226
	s_waitcnt lgkmcnt(0)
	v_add_f32_e32 v145, v145, v227
	ds_bpermute_b32 v220, v172, v138
	ds_bpermute_b32 v221, v172, v139
	ds_bpermute_b32 v222, v172, v140
	ds_bpermute_b32 v223, v172, v141
	ds_bpermute_b32 v224, v172, v142
	ds_bpermute_b32 v225, v172, v143
	ds_bpermute_b32 v226, v172, v144
	ds_bpermute_b32 v227, v172, v145
	s_waitcnt lgkmcnt(7)
	v_add_f32_e32 v138, v138, v220
	s_waitcnt lgkmcnt(6)
	v_add_f32_e32 v139, v139, v221
	s_waitcnt lgkmcnt(5)
	v_add_f32_e32 v140, v140, v222
	s_waitcnt lgkmcnt(4)
	v_add_f32_e32 v141, v141, v223
	s_waitcnt lgkmcnt(3)
	v_add_f32_e32 v142, v142, v224
	s_waitcnt lgkmcnt(2)
	v_add_f32_e32 v143, v143, v225
	s_waitcnt lgkmcnt(1)
	v_add_f32_e32 v144, v144, v226
	s_waitcnt lgkmcnt(0)
	v_add_f32_e32 v145, v145, v227
	ds_bpermute_b32 v220, v173, v138
	ds_bpermute_b32 v221, v173, v139
	ds_bpermute_b32 v222, v173, v140
	ds_bpermute_b32 v223, v173, v141
	ds_bpermute_b32 v224, v173, v142
	ds_bpermute_b32 v225, v173, v143
	ds_bpermute_b32 v226, v173, v144
	ds_bpermute_b32 v227, v173, v145
	s_waitcnt lgkmcnt(7)
	v_add_f32_e32 v138, v138, v220
	s_waitcnt lgkmcnt(6)
	v_add_f32_e32 v139, v139, v221
	s_waitcnt lgkmcnt(5)
	v_add_f32_e32 v140, v140, v222
	s_waitcnt lgkmcnt(4)
	v_add_f32_e32 v141, v141, v223
	s_waitcnt lgkmcnt(3)
	v_add_f32_e32 v142, v142, v224
	s_waitcnt lgkmcnt(2)
	v_add_f32_e32 v143, v143, v225
	s_waitcnt lgkmcnt(1)
	v_add_f32_e32 v144, v144, v226
	s_waitcnt lgkmcnt(0)
	v_add_f32_e32 v145, v145, v227
	v_cmp_eq_u32_e32 vcc, 0, v174
	s_and_saveexec_b64 s[58:59], vcc
	global_store_dword v167, v130, s[10:11]
	global_store_dword v167, v131, s[10:11] offset:4
	global_store_dword v167, v132, s[10:11] offset:8
	global_store_dword v167, v133, s[10:11] offset:12
	global_store_dword v167, v134, s[10:11] offset:32
	global_store_dword v167, v135, s[10:11] offset:36
	global_store_dword v167, v136, s[10:11] offset:40
	global_store_dword v167, v137, s[10:11] offset:44
	global_store_dword v167, v138, s[10:11] offset:64
	global_store_dword v167, v139, s[10:11] offset:68
	global_store_dword v167, v140, s[10:11] offset:72
	global_store_dword v167, v141, s[10:11] offset:76
	global_store_dword v167, v142, s[10:11] offset:96
	global_store_dword v167, v143, s[10:11] offset:100
	global_store_dword v167, v144, s[10:11] offset:104
	global_store_dword v167, v145, s[10:11] offset:108
	s_mov_b64 exec, -1
	s_add_u32 s48, s48, 0x20000
	s_addc_u32 s49, s49, 0
	global_load_dword v130, v162, s[48:49]
	global_load_dword v212, v162, s[48:49] offset:128
	global_load_dword v131, v163, s[48:49]
	global_load_dword v213, v163, s[48:49] offset:128
	global_load_dword v132, v164, s[48:49]
	global_load_dword v214, v164, s[48:49] offset:128
	global_load_dword v133, v165, s[48:49]
	global_load_dword v215, v165, s[48:49] offset:128
	s_add_u32 s48, s48, 0x8000
	s_addc_u32 s49, s49, 0
	global_load_dword v134, v162, s[48:49]
	global_load_dword v216, v162, s[48:49] offset:128
	global_load_dword v135, v163, s[48:49]
	global_load_dword v217, v163, s[48:49] offset:128
	global_load_dword v136, v164, s[48:49]
	global_load_dword v218, v164, s[48:49] offset:128
	global_load_dword v137, v165, s[48:49]
	global_load_dword v219, v165, s[48:49] offset:128
	s_add_u32 s48, s48, 0x8000
	s_addc_u32 s49, s49, 0
	global_load_dword v138, v162, s[48:49]
	global_load_dword v220, v162, s[48:49] offset:128
	global_load_dword v139, v163, s[48:49]
	global_load_dword v221, v163, s[48:49] offset:128
	global_load_dword v140, v164, s[48:49]
	global_load_dword v222, v164, s[48:49] offset:128
	global_load_dword v141, v165, s[48:49]
	global_load_dword v223, v165, s[48:49] offset:128
	s_add_u32 s48, s48, 0x8000
	s_addc_u32 s49, s49, 0
	global_load_dword v142, v162, s[48:49]
	global_load_dword v224, v162, s[48:49] offset:128
	global_load_dword v143, v163, s[48:49]
	global_load_dword v225, v163, s[48:49] offset:128
	global_load_dword v144, v164, s[48:49]
	global_load_dword v226, v164, s[48:49] offset:128
	global_load_dword v145, v165, s[48:49]
	global_load_dword v227, v165, s[48:49] offset:128
	s_sub_u32 s48, s48, 0x18000
	s_subb_u32 s49, s49, 0
	s_waitcnt vmcnt(30)
	v_fmac_f32_e32 v130, v34, v175
	v_fmac_f32_e32 v212, v50, v176
	global_store_dword v162, v130, s[48:49]
	global_store_dword v162, v212, s[48:49] offset:128
	s_waitcnt vmcnt(30)
	v_fmac_f32_e32 v131, v35, v175
	v_fmac_f32_e32 v213, v51, v176
	global_store_dword v163, v131, s[48:49]
	global_store_dword v163, v213, s[48:49] offset:128
	s_waitcnt vmcnt(30)
	v_fmac_f32_e32 v132, v36, v175
	v_fmac_f32_e32 v214, v52, v176
	global_store_dword v164, v132, s[48:49]
	global_store_dword v164, v214, s[48:49] offset:128
	s_waitcnt vmcnt(30)
	v_fmac_f32_e32 v133, v37, v175
	v_fmac_f32_e32 v215, v53, v176
	global_store_dword v165, v133, s[48:49]
	global_store_dword v165, v215, s[48:49] offset:128
	s_add_u32 s48, s48, 0x8000
	s_addc_u32 s49, s49, 0
	s_waitcnt vmcnt(30)
	v_fmac_f32_e32 v134, v38, v175
	v_fmac_f32_e32 v216, v54, v176
	global_store_dword v162, v134, s[48:49]
	global_store_dword v162, v216, s[48:49] offset:128
	s_waitcnt vmcnt(30)
	v_fmac_f32_e32 v135, v39, v175
	v_fmac_f32_e32 v217, v55, v176
	global_store_dword v163, v135, s[48:49]
	global_store_dword v163, v217, s[48:49] offset:128
	s_waitcnt vmcnt(30)
	v_fmac_f32_e32 v136, v40, v175
	v_fmac_f32_e32 v218, v56, v176
	global_store_dword v164, v136, s[48:49]
	global_store_dword v164, v218, s[48:49] offset:128
	s_waitcnt vmcnt(30)
	v_fmac_f32_e32 v137, v41, v175
	v_fmac_f32_e32 v219, v57, v176
	global_store_dword v165, v137, s[48:49]
	global_store_dword v165, v219, s[48:49] offset:128
	s_add_u32 s48, s48, 0x8000
	s_addc_u32 s49, s49, 0
	s_waitcnt vmcnt(30)
	v_fmac_f32_e32 v138, v42, v175
	v_fmac_f32_e32 v220, v58, v176
	global_store_dword v162, v138, s[48:49]
	global_store_dword v162, v220, s[48:49] offset:128
	s_waitcnt vmcnt(30)
	v_fmac_f32_e32 v139, v43, v175
	v_fmac_f32_e32 v221, v59, v176
	global_store_dword v163, v139, s[48:49]
	global_store_dword v163, v221, s[48:49] offset:128
	s_waitcnt vmcnt(30)
	v_fmac_f32_e32 v140, v44, v175
	v_fmac_f32_e32 v222, v60, v176
	global_store_dword v164, v140, s[48:49]
	global_store_dword v164, v222, s[48:49] offset:128
	s_waitcnt vmcnt(30)
	v_fmac_f32_e32 v141, v45, v175
	v_fmac_f32_e32 v223, v61, v176
	global_store_dword v165, v141, s[48:49]
	global_store_dword v165, v223, s[48:49] offset:128
	s_add_u32 s48, s48, 0x8000
	s_addc_u32 s49, s49, 0
	s_waitcnt vmcnt(30)
	v_fmac_f32_e32 v142, v46, v175
	v_fmac_f32_e32 v224, v62, v176
	global_store_dword v162, v142, s[48:49]
	global_store_dword v162, v224, s[48:49] offset:128
	s_waitcnt vmcnt(30)
	v_fmac_f32_e32 v143, v47, v175
	v_fmac_f32_e32 v225, v63, v176
	global_store_dword v163, v143, s[48:49]
	global_store_dword v163, v225, s[48:49] offset:128
	s_waitcnt vmcnt(30)
	v_fmac_f32_e32 v144, v48, v175
	v_fmac_f32_e32 v226, v64, v176
	global_store_dword v164, v144, s[48:49]
	global_store_dword v164, v226, s[48:49] offset:128
	s_waitcnt vmcnt(30)
	v_fmac_f32_e32 v145, v49, v175
	v_fmac_f32_e32 v227, v65, v176
	global_store_dword v165, v145, s[48:49]
	global_store_dword v165, v227, s[48:49] offset:128
	s_sub_u32 s48, s48, 0x18000
	s_subb_u32 s49, s49, 0
	v_mul_f32_e32 v130, v130, v130
	v_fmac_f32_e32 v130, v212, v212
	v_mul_f32_e32 v131, v131, v131
	v_fmac_f32_e32 v131, v213, v213
	v_mul_f32_e32 v132, v132, v132
	v_fmac_f32_e32 v132, v214, v214
	v_mul_f32_e32 v133, v133, v133
	v_fmac_f32_e32 v133, v215, v215
	v_mul_f32_e32 v134, v134, v134
	v_fmac_f32_e32 v134, v216, v216
	v_mul_f32_e32 v135, v135, v135
	v_fmac_f32_e32 v135, v217, v217
	v_mul_f32_e32 v136, v136, v136
	v_fmac_f32_e32 v136, v218, v218
	v_mul_f32_e32 v137, v137, v137
	v_fmac_f32_e32 v137, v219, v219
	v_mul_f32_e32 v138, v138, v138
	v_fmac_f32_e32 v138, v220, v220
	v_mul_f32_e32 v139, v139, v139
	v_fmac_f32_e32 v139, v221, v221
	v_mul_f32_e32 v140, v140, v140
	v_fmac_f32_e32 v140, v222, v222
	v_mul_f32_e32 v141, v141, v141
	v_fmac_f32_e32 v141, v223, v223
	v_mul_f32_e32 v142, v142, v142
	v_fmac_f32_e32 v142, v224, v224
	v_mul_f32_e32 v143, v143, v143
	v_fmac_f32_e32 v143, v225, v225
	v_mul_f32_e32 v144, v144, v144
	v_fmac_f32_e32 v144, v226, v226
	v_mul_f32_e32 v145, v145, v145
	v_fmac_f32_e32 v145, v227, v227
	s_waitcnt lgkmcnt(0)
	ds_bpermute_b32 v212, v168, v130
	ds_bpermute_b32 v213, v168, v131
	ds_bpermute_b32 v214, v168, v132
	ds_bpermute_b32 v215, v168, v133
	ds_bpermute_b32 v216, v168, v134
	ds_bpermute_b32 v217, v168, v135
	ds_bpermute_b32 v218, v168, v136
	ds_bpermute_b32 v219, v168, v137
	s_waitcnt lgkmcnt(7)
	v_add_f32_e32 v130, v130, v212
	s_waitcnt lgkmcnt(6)
	v_add_f32_e32 v131, v131, v213
	s_waitcnt lgkmcnt(5)
	v_add_f32_e32 v132, v132, v214
	s_waitcnt lgkmcnt(4)
	v_add_f32_e32 v133, v133, v215
	s_waitcnt lgkmcnt(3)
	v_add_f32_e32 v134, v134, v216
	s_waitcnt lgkmcnt(2)
	v_add_f32_e32 v135, v135, v217
	s_waitcnt lgkmcnt(1)
	v_add_f32_e32 v136, v136, v218
	s_waitcnt lgkmcnt(0)
	v_add_f32_e32 v137, v137, v219
	ds_bpermute_b32 v212, v169, v130
	ds_bpermute_b32 v213, v169, v131
	ds_bpermute_b32 v214, v169, v132
	ds_bpermute_b32 v215, v169, v133
	ds_bpermute_b32 v216, v169, v134
	ds_bpermute_b32 v217, v169, v135
	ds_bpermute_b32 v218, v169, v136
	ds_bpermute_b32 v219, v169, v137
	s_waitcnt lgkmcnt(7)
	v_add_f32_e32 v130, v130, v212
	s_waitcnt lgkmcnt(6)
	v_add_f32_e32 v131, v131, v213
	s_waitcnt lgkmcnt(5)
	v_add_f32_e32 v132, v132, v214
	s_waitcnt lgkmcnt(4)
	v_add_f32_e32 v133, v133, v215
	s_waitcnt lgkmcnt(3)
	v_add_f32_e32 v134, v134, v216
	s_waitcnt lgkmcnt(2)
	v_add_f32_e32 v135, v135, v217
	s_waitcnt lgkmcnt(1)
	v_add_f32_e32 v136, v136, v218
	s_waitcnt lgkmcnt(0)
	v_add_f32_e32 v137, v137, v219
	ds_bpermute_b32 v212, v171, v130
	ds_bpermute_b32 v213, v171, v131
	ds_bpermute_b32 v214, v171, v132
	ds_bpermute_b32 v215, v171, v133
	ds_bpermute_b32 v216, v171, v134
	ds_bpermute_b32 v217, v171, v135
	ds_bpermute_b32 v218, v171, v136
	ds_bpermute_b32 v219, v171, v137
	s_waitcnt lgkmcnt(7)
	v_add_f32_e32 v130, v130, v212
	s_waitcnt lgkmcnt(6)
	v_add_f32_e32 v131, v131, v213
	s_waitcnt lgkmcnt(5)
	v_add_f32_e32 v132, v132, v214
	s_waitcnt lgkmcnt(4)
	v_add_f32_e32 v133, v133, v215
	s_waitcnt lgkmcnt(3)
	v_add_f32_e32 v134, v134, v216
	s_waitcnt lgkmcnt(2)
	v_add_f32_e32 v135, v135, v217
	s_waitcnt lgkmcnt(1)
	v_add_f32_e32 v136, v136, v218
	s_waitcnt lgkmcnt(0)
	v_add_f32_e32 v137, v137, v219
	ds_bpermute_b32 v212, v172, v130
	ds_bpermute_b32 v213, v172, v131
	ds_bpermute_b32 v214, v172, v132
	ds_bpermute_b32 v215, v172, v133
	ds_bpermute_b32 v216, v172, v134
	ds_bpermute_b32 v217, v172, v135
	ds_bpermute_b32 v218, v172, v136
	ds_bpermute_b32 v219, v172, v137
	s_waitcnt lgkmcnt(7)
	v_add_f32_e32 v130, v130, v212
	s_waitcnt lgkmcnt(6)
	v_add_f32_e32 v131, v131, v213
	s_waitcnt lgkmcnt(5)
	v_add_f32_e32 v132, v132, v214
	s_waitcnt lgkmcnt(4)
	v_add_f32_e32 v133, v133, v215
	s_waitcnt lgkmcnt(3)
	v_add_f32_e32 v134, v134, v216
	s_waitcnt lgkmcnt(2)
	v_add_f32_e32 v135, v135, v217
	s_waitcnt lgkmcnt(1)
	v_add_f32_e32 v136, v136, v218
	s_waitcnt lgkmcnt(0)
	v_add_f32_e32 v137, v137, v219
	ds_bpermute_b32 v212, v173, v130
	ds_bpermute_b32 v213, v173, v131
	ds_bpermute_b32 v214, v173, v132
	ds_bpermute_b32 v215, v173, v133
	ds_bpermute_b32 v216, v173, v134
	ds_bpermute_b32 v217, v173, v135
	ds_bpermute_b32 v218, v173, v136
	ds_bpermute_b32 v219, v173, v137
	s_waitcnt lgkmcnt(7)
	v_add_f32_e32 v130, v130, v212
	s_waitcnt lgkmcnt(6)
	v_add_f32_e32 v131, v131, v213
	s_waitcnt lgkmcnt(5)
	v_add_f32_e32 v132, v132, v214
	s_waitcnt lgkmcnt(4)
	v_add_f32_e32 v133, v133, v215
	s_waitcnt lgkmcnt(3)
	v_add_f32_e32 v134, v134, v216
	s_waitcnt lgkmcnt(2)
	v_add_f32_e32 v135, v135, v217
	s_waitcnt lgkmcnt(1)
	v_add_f32_e32 v136, v136, v218
	s_waitcnt lgkmcnt(0)
	v_add_f32_e32 v137, v137, v219
	ds_bpermute_b32 v220, v168, v138
	ds_bpermute_b32 v221, v168, v139
	ds_bpermute_b32 v222, v168, v140
	ds_bpermute_b32 v223, v168, v141
	ds_bpermute_b32 v224, v168, v142
	ds_bpermute_b32 v225, v168, v143
	ds_bpermute_b32 v226, v168, v144
	ds_bpermute_b32 v227, v168, v145
	s_waitcnt lgkmcnt(7)
	v_add_f32_e32 v138, v138, v220
	s_waitcnt lgkmcnt(6)
	v_add_f32_e32 v139, v139, v221
	s_waitcnt lgkmcnt(5)
	v_add_f32_e32 v140, v140, v222
	s_waitcnt lgkmcnt(4)
	v_add_f32_e32 v141, v141, v223
	s_waitcnt lgkmcnt(3)
	v_add_f32_e32 v142, v142, v224
	s_waitcnt lgkmcnt(2)
	v_add_f32_e32 v143, v143, v225
	s_waitcnt lgkmcnt(1)
	v_add_f32_e32 v144, v144, v226
	s_waitcnt lgkmcnt(0)
	v_add_f32_e32 v145, v145, v227
	ds_bpermute_b32 v220, v169, v138
	ds_bpermute_b32 v221, v169, v139
	ds_bpermute_b32 v222, v169, v140
	ds_bpermute_b32 v223, v169, v141
	ds_bpermute_b32 v224, v169, v142
	ds_bpermute_b32 v225, v169, v143
	ds_bpermute_b32 v226, v169, v144
	ds_bpermute_b32 v227, v169, v145
	s_waitcnt lgkmcnt(7)
	v_add_f32_e32 v138, v138, v220
	s_waitcnt lgkmcnt(6)
	v_add_f32_e32 v139, v139, v221
	s_waitcnt lgkmcnt(5)
	v_add_f32_e32 v140, v140, v222
	s_waitcnt lgkmcnt(4)
	v_add_f32_e32 v141, v141, v223
	s_waitcnt lgkmcnt(3)
	v_add_f32_e32 v142, v142, v224
	s_waitcnt lgkmcnt(2)
	v_add_f32_e32 v143, v143, v225
	s_waitcnt lgkmcnt(1)
	v_add_f32_e32 v144, v144, v226
	s_waitcnt lgkmcnt(0)
	v_add_f32_e32 v145, v145, v227
	ds_bpermute_b32 v220, v171, v138
	ds_bpermute_b32 v221, v171, v139
	ds_bpermute_b32 v222, v171, v140
	ds_bpermute_b32 v223, v171, v141
	ds_bpermute_b32 v224, v171, v142
	ds_bpermute_b32 v225, v171, v143
	ds_bpermute_b32 v226, v171, v144
	ds_bpermute_b32 v227, v171, v145
	s_waitcnt lgkmcnt(7)
	v_add_f32_e32 v138, v138, v220
	s_waitcnt lgkmcnt(6)
	v_add_f32_e32 v139, v139, v221
	s_waitcnt lgkmcnt(5)
	v_add_f32_e32 v140, v140, v222
	s_waitcnt lgkmcnt(4)
	v_add_f32_e32 v141, v141, v223
	s_waitcnt lgkmcnt(3)
	v_add_f32_e32 v142, v142, v224
	s_waitcnt lgkmcnt(2)
	v_add_f32_e32 v143, v143, v225
	s_waitcnt lgkmcnt(1)
	v_add_f32_e32 v144, v144, v226
	s_waitcnt lgkmcnt(0)
	v_add_f32_e32 v145, v145, v227
	ds_bpermute_b32 v220, v172, v138
	ds_bpermute_b32 v221, v172, v139
	ds_bpermute_b32 v222, v172, v140
	ds_bpermute_b32 v223, v172, v141
	ds_bpermute_b32 v224, v172, v142
	ds_bpermute_b32 v225, v172, v143
	ds_bpermute_b32 v226, v172, v144
	ds_bpermute_b32 v227, v172, v145
	s_waitcnt lgkmcnt(7)
	v_add_f32_e32 v138, v138, v220
	s_waitcnt lgkmcnt(6)
	v_add_f32_e32 v139, v139, v221
	s_waitcnt lgkmcnt(5)
	v_add_f32_e32 v140, v140, v222
	s_waitcnt lgkmcnt(4)
	v_add_f32_e32 v141, v141, v223
	s_waitcnt lgkmcnt(3)
	v_add_f32_e32 v142, v142, v224
	s_waitcnt lgkmcnt(2)
	v_add_f32_e32 v143, v143, v225
	s_waitcnt lgkmcnt(1)
	v_add_f32_e32 v144, v144, v226
	s_waitcnt lgkmcnt(0)
	v_add_f32_e32 v145, v145, v227
	ds_bpermute_b32 v220, v173, v138
	ds_bpermute_b32 v221, v173, v139
	ds_bpermute_b32 v222, v173, v140
	ds_bpermute_b32 v223, v173, v141
	ds_bpermute_b32 v224, v173, v142
	ds_bpermute_b32 v225, v173, v143
	ds_bpermute_b32 v226, v173, v144
	ds_bpermute_b32 v227, v173, v145
	s_waitcnt lgkmcnt(7)
	v_add_f32_e32 v138, v138, v220
	s_waitcnt lgkmcnt(6)
	v_add_f32_e32 v139, v139, v221
	s_waitcnt lgkmcnt(5)
	v_add_f32_e32 v140, v140, v222
	s_waitcnt lgkmcnt(4)
	v_add_f32_e32 v141, v141, v223
	s_waitcnt lgkmcnt(3)
	v_add_f32_e32 v142, v142, v224
	s_waitcnt lgkmcnt(2)
	v_add_f32_e32 v143, v143, v225
	s_waitcnt lgkmcnt(1)
	v_add_f32_e32 v144, v144, v226
	s_waitcnt lgkmcnt(0)
	v_add_f32_e32 v145, v145, v227
	v_cmp_eq_u32_e32 vcc, 0, v174
	s_and_saveexec_b64 s[58:59], vcc
	global_store_dword v167, v130, s[10:11] offset:128
	global_store_dword v167, v131, s[10:11] offset:132
	global_store_dword v167, v132, s[10:11] offset:136
	global_store_dword v167, v133, s[10:11] offset:140
	global_store_dword v167, v134, s[10:11] offset:160
	global_store_dword v167, v135, s[10:11] offset:164
	global_store_dword v167, v136, s[10:11] offset:168
	global_store_dword v167, v137, s[10:11] offset:172
	global_store_dword v167, v138, s[10:11] offset:192
	global_store_dword v167, v139, s[10:11] offset:196
	global_store_dword v167, v140, s[10:11] offset:200
	global_store_dword v167, v141, s[10:11] offset:204
	global_store_dword v167, v142, s[10:11] offset:224
	global_store_dword v167, v143, s[10:11] offset:228
	global_store_dword v167, v144, s[10:11] offset:232
	global_store_dword v167, v145, s[10:11] offset:236
	s_mov_b64 exec, -1
	s_sub_u32 s48, s48, 0x20000
	s_subb_u32 s49, s49, 0
	s_add_u32 s60, s60, 0x200
	s_addc_u32 s61, s61, 0
	s_add_u32 s10, s10, 0x18000
	s_addc_u32 s11, s11, 0
	s_add_u32 s48, s48, 0x200
	s_addc_u32 s49, s49, 0
	global_load_dword v175, v166, s[60:61]
	global_load_dword v176, v166, s[60:61] offset:128
	global_load_dword v130, v162, s[48:49]
	global_load_dword v212, v162, s[48:49] offset:128
	global_load_dword v131, v163, s[48:49]
	global_load_dword v213, v163, s[48:49] offset:128
	global_load_dword v132, v164, s[48:49]
	global_load_dword v214, v164, s[48:49] offset:128
	global_load_dword v133, v165, s[48:49]
	global_load_dword v215, v165, s[48:49] offset:128
	s_add_u32 s48, s48, 0x8000
	s_addc_u32 s49, s49, 0
	global_load_dword v134, v162, s[48:49]
	global_load_dword v216, v162, s[48:49] offset:128
	global_load_dword v135, v163, s[48:49]
	global_load_dword v217, v163, s[48:49] offset:128
	global_load_dword v136, v164, s[48:49]
	global_load_dword v218, v164, s[48:49] offset:128
	global_load_dword v137, v165, s[48:49]
	global_load_dword v219, v165, s[48:49] offset:128
	s_add_u32 s48, s48, 0x8000
	s_addc_u32 s49, s49, 0
	global_load_dword v138, v162, s[48:49]
	global_load_dword v220, v162, s[48:49] offset:128
	global_load_dword v139, v163, s[48:49]
	global_load_dword v221, v163, s[48:49] offset:128
	global_load_dword v140, v164, s[48:49]
	global_load_dword v222, v164, s[48:49] offset:128
	global_load_dword v141, v165, s[48:49]
	global_load_dword v223, v165, s[48:49] offset:128
	s_add_u32 s48, s48, 0x8000
	s_addc_u32 s49, s49, 0
	global_load_dword v142, v162, s[48:49]
	global_load_dword v224, v162, s[48:49] offset:128
	global_load_dword v143, v163, s[48:49]
	global_load_dword v225, v163, s[48:49] offset:128
	global_load_dword v144, v164, s[48:49]
	global_load_dword v226, v164, s[48:49] offset:128
	global_load_dword v145, v165, s[48:49]
	global_load_dword v227, v165, s[48:49] offset:128
	s_sub_u32 s48, s48, 0x18000
	s_subb_u32 s49, s49, 0
	s_waitcnt vmcnt(32)
	s_waitcnt vmcnt(30)
	v_fmac_f32_e32 v130, v66, v175
	v_fmac_f32_e32 v212, v82, v176
	global_store_dword v162, v130, s[48:49]
	global_store_dword v162, v212, s[48:49] offset:128
	s_waitcnt vmcnt(30)
	v_fmac_f32_e32 v131, v67, v175
	v_fmac_f32_e32 v213, v83, v176
	global_store_dword v163, v131, s[48:49]
	global_store_dword v163, v213, s[48:49] offset:128
	s_waitcnt vmcnt(30)
	v_fmac_f32_e32 v132, v68, v175
	v_fmac_f32_e32 v214, v84, v176
	global_store_dword v164, v132, s[48:49]
	global_store_dword v164, v214, s[48:49] offset:128
	s_waitcnt vmcnt(30)
	v_fmac_f32_e32 v133, v69, v175
	v_fmac_f32_e32 v215, v85, v176
	global_store_dword v165, v133, s[48:49]
	global_store_dword v165, v215, s[48:49] offset:128
	s_add_u32 s48, s48, 0x8000
	s_addc_u32 s49, s49, 0
	s_waitcnt vmcnt(30)
	v_fmac_f32_e32 v134, v70, v175
	v_fmac_f32_e32 v216, v86, v176
	global_store_dword v162, v134, s[48:49]
	global_store_dword v162, v216, s[48:49] offset:128
	s_waitcnt vmcnt(30)
	v_fmac_f32_e32 v135, v71, v175
	v_fmac_f32_e32 v217, v87, v176
	global_store_dword v163, v135, s[48:49]
	global_store_dword v163, v217, s[48:49] offset:128
	s_waitcnt vmcnt(30)
	v_fmac_f32_e32 v136, v72, v175
	v_fmac_f32_e32 v218, v88, v176
	global_store_dword v164, v136, s[48:49]
	global_store_dword v164, v218, s[48:49] offset:128
	s_waitcnt vmcnt(30)
	v_fmac_f32_e32 v137, v73, v175
	v_fmac_f32_e32 v219, v89, v176
	global_store_dword v165, v137, s[48:49]
	global_store_dword v165, v219, s[48:49] offset:128
	s_add_u32 s48, s48, 0x8000
	s_addc_u32 s49, s49, 0
	s_waitcnt vmcnt(30)
	v_fmac_f32_e32 v138, v74, v175
	v_fmac_f32_e32 v220, v90, v176
	global_store_dword v162, v138, s[48:49]
	global_store_dword v162, v220, s[48:49] offset:128
	s_waitcnt vmcnt(30)
	v_fmac_f32_e32 v139, v75, v175
	v_fmac_f32_e32 v221, v91, v176
	global_store_dword v163, v139, s[48:49]
	global_store_dword v163, v221, s[48:49] offset:128
	s_waitcnt vmcnt(30)
	v_fmac_f32_e32 v140, v76, v175
	v_fmac_f32_e32 v222, v92, v176
	global_store_dword v164, v140, s[48:49]
	global_store_dword v164, v222, s[48:49] offset:128
	s_waitcnt vmcnt(30)
	v_fmac_f32_e32 v141, v77, v175
	v_fmac_f32_e32 v223, v93, v176
	global_store_dword v165, v141, s[48:49]
	global_store_dword v165, v223, s[48:49] offset:128
	s_add_u32 s48, s48, 0x8000
	s_addc_u32 s49, s49, 0
	s_waitcnt vmcnt(30)
	v_fmac_f32_e32 v142, v78, v175
	v_fmac_f32_e32 v224, v94, v176
	global_store_dword v162, v142, s[48:49]
	global_store_dword v162, v224, s[48:49] offset:128
	s_waitcnt vmcnt(30)
	v_fmac_f32_e32 v143, v79, v175
	v_fmac_f32_e32 v225, v95, v176
	global_store_dword v163, v143, s[48:49]
	global_store_dword v163, v225, s[48:49] offset:128
	s_waitcnt vmcnt(30)
	v_fmac_f32_e32 v144, v80, v175
	v_fmac_f32_e32 v226, v96, v176
	global_store_dword v164, v144, s[48:49]
	global_store_dword v164, v226, s[48:49] offset:128
	s_waitcnt vmcnt(30)
	v_fmac_f32_e32 v145, v81, v175
	v_fmac_f32_e32 v227, v97, v176
	global_store_dword v165, v145, s[48:49]
	global_store_dword v165, v227, s[48:49] offset:128
	s_sub_u32 s48, s48, 0x18000
	s_subb_u32 s49, s49, 0
	v_mul_f32_e32 v130, v130, v130
	v_fmac_f32_e32 v130, v212, v212
	v_mul_f32_e32 v131, v131, v131
	v_fmac_f32_e32 v131, v213, v213
	v_mul_f32_e32 v132, v132, v132
	v_fmac_f32_e32 v132, v214, v214
	v_mul_f32_e32 v133, v133, v133
	v_fmac_f32_e32 v133, v215, v215
	v_mul_f32_e32 v134, v134, v134
	v_fmac_f32_e32 v134, v216, v216
	v_mul_f32_e32 v135, v135, v135
	v_fmac_f32_e32 v135, v217, v217
	v_mul_f32_e32 v136, v136, v136
	v_fmac_f32_e32 v136, v218, v218
	v_mul_f32_e32 v137, v137, v137
	v_fmac_f32_e32 v137, v219, v219
	v_mul_f32_e32 v138, v138, v138
	v_fmac_f32_e32 v138, v220, v220
	v_mul_f32_e32 v139, v139, v139
	v_fmac_f32_e32 v139, v221, v221
	v_mul_f32_e32 v140, v140, v140
	v_fmac_f32_e32 v140, v222, v222
	v_mul_f32_e32 v141, v141, v141
	v_fmac_f32_e32 v141, v223, v223
	v_mul_f32_e32 v142, v142, v142
	v_fmac_f32_e32 v142, v224, v224
	v_mul_f32_e32 v143, v143, v143
	v_fmac_f32_e32 v143, v225, v225
	v_mul_f32_e32 v144, v144, v144
	v_fmac_f32_e32 v144, v226, v226
	v_mul_f32_e32 v145, v145, v145
	v_fmac_f32_e32 v145, v227, v227
	s_waitcnt lgkmcnt(0)
	ds_bpermute_b32 v212, v168, v130
	ds_bpermute_b32 v213, v168, v131
	ds_bpermute_b32 v214, v168, v132
	ds_bpermute_b32 v215, v168, v133
	ds_bpermute_b32 v216, v168, v134
	ds_bpermute_b32 v217, v168, v135
	ds_bpermute_b32 v218, v168, v136
	ds_bpermute_b32 v219, v168, v137
	s_waitcnt lgkmcnt(7)
	v_add_f32_e32 v130, v130, v212
	s_waitcnt lgkmcnt(6)
	v_add_f32_e32 v131, v131, v213
	s_waitcnt lgkmcnt(5)
	v_add_f32_e32 v132, v132, v214
	s_waitcnt lgkmcnt(4)
	v_add_f32_e32 v133, v133, v215
	s_waitcnt lgkmcnt(3)
	v_add_f32_e32 v134, v134, v216
	s_waitcnt lgkmcnt(2)
	v_add_f32_e32 v135, v135, v217
	s_waitcnt lgkmcnt(1)
	v_add_f32_e32 v136, v136, v218
	s_waitcnt lgkmcnt(0)
	v_add_f32_e32 v137, v137, v219
	ds_bpermute_b32 v212, v169, v130
	ds_bpermute_b32 v213, v169, v131
	ds_bpermute_b32 v214, v169, v132
	ds_bpermute_b32 v215, v169, v133
	ds_bpermute_b32 v216, v169, v134
	ds_bpermute_b32 v217, v169, v135
	ds_bpermute_b32 v218, v169, v136
	ds_bpermute_b32 v219, v169, v137
	s_waitcnt lgkmcnt(7)
	v_add_f32_e32 v130, v130, v212
	s_waitcnt lgkmcnt(6)
	v_add_f32_e32 v131, v131, v213
	s_waitcnt lgkmcnt(5)
	v_add_f32_e32 v132, v132, v214
	s_waitcnt lgkmcnt(4)
	v_add_f32_e32 v133, v133, v215
	s_waitcnt lgkmcnt(3)
	v_add_f32_e32 v134, v134, v216
	s_waitcnt lgkmcnt(2)
	v_add_f32_e32 v135, v135, v217
	s_waitcnt lgkmcnt(1)
	v_add_f32_e32 v136, v136, v218
	s_waitcnt lgkmcnt(0)
	v_add_f32_e32 v137, v137, v219
	ds_bpermute_b32 v212, v171, v130
	ds_bpermute_b32 v213, v171, v131
	ds_bpermute_b32 v214, v171, v132
	ds_bpermute_b32 v215, v171, v133
	ds_bpermute_b32 v216, v171, v134
	ds_bpermute_b32 v217, v171, v135
	ds_bpermute_b32 v218, v171, v136
	ds_bpermute_b32 v219, v171, v137
	s_waitcnt lgkmcnt(7)
	v_add_f32_e32 v130, v130, v212
	s_waitcnt lgkmcnt(6)
	v_add_f32_e32 v131, v131, v213
	s_waitcnt lgkmcnt(5)
	v_add_f32_e32 v132, v132, v214
	s_waitcnt lgkmcnt(4)
	v_add_f32_e32 v133, v133, v215
	s_waitcnt lgkmcnt(3)
	v_add_f32_e32 v134, v134, v216
	s_waitcnt lgkmcnt(2)
	v_add_f32_e32 v135, v135, v217
	s_waitcnt lgkmcnt(1)
	v_add_f32_e32 v136, v136, v218
	s_waitcnt lgkmcnt(0)
	v_add_f32_e32 v137, v137, v219
	ds_bpermute_b32 v212, v172, v130
	ds_bpermute_b32 v213, v172, v131
	ds_bpermute_b32 v214, v172, v132
	ds_bpermute_b32 v215, v172, v133
	ds_bpermute_b32 v216, v172, v134
	ds_bpermute_b32 v217, v172, v135
	ds_bpermute_b32 v218, v172, v136
	ds_bpermute_b32 v219, v172, v137
	s_waitcnt lgkmcnt(7)
	v_add_f32_e32 v130, v130, v212
	s_waitcnt lgkmcnt(6)
	v_add_f32_e32 v131, v131, v213
	s_waitcnt lgkmcnt(5)
	v_add_f32_e32 v132, v132, v214
	s_waitcnt lgkmcnt(4)
	v_add_f32_e32 v133, v133, v215
	s_waitcnt lgkmcnt(3)
	v_add_f32_e32 v134, v134, v216
	s_waitcnt lgkmcnt(2)
	v_add_f32_e32 v135, v135, v217
	s_waitcnt lgkmcnt(1)
	v_add_f32_e32 v136, v136, v218
	s_waitcnt lgkmcnt(0)
	v_add_f32_e32 v137, v137, v219
	ds_bpermute_b32 v212, v173, v130
	ds_bpermute_b32 v213, v173, v131
	ds_bpermute_b32 v214, v173, v132
	ds_bpermute_b32 v215, v173, v133
	ds_bpermute_b32 v216, v173, v134
	ds_bpermute_b32 v217, v173, v135
	ds_bpermute_b32 v218, v173, v136
	ds_bpermute_b32 v219, v173, v137
	s_waitcnt lgkmcnt(7)
	v_add_f32_e32 v130, v130, v212
	s_waitcnt lgkmcnt(6)
	v_add_f32_e32 v131, v131, v213
	s_waitcnt lgkmcnt(5)
	v_add_f32_e32 v132, v132, v214
	s_waitcnt lgkmcnt(4)
	v_add_f32_e32 v133, v133, v215
	s_waitcnt lgkmcnt(3)
	v_add_f32_e32 v134, v134, v216
	s_waitcnt lgkmcnt(2)
	v_add_f32_e32 v135, v135, v217
	s_waitcnt lgkmcnt(1)
	v_add_f32_e32 v136, v136, v218
	s_waitcnt lgkmcnt(0)
	v_add_f32_e32 v137, v137, v219
	ds_bpermute_b32 v220, v168, v138
	ds_bpermute_b32 v221, v168, v139
	ds_bpermute_b32 v222, v168, v140
	ds_bpermute_b32 v223, v168, v141
	ds_bpermute_b32 v224, v168, v142
	ds_bpermute_b32 v225, v168, v143
	ds_bpermute_b32 v226, v168, v144
	ds_bpermute_b32 v227, v168, v145
	s_waitcnt lgkmcnt(7)
	v_add_f32_e32 v138, v138, v220
	s_waitcnt lgkmcnt(6)
	v_add_f32_e32 v139, v139, v221
	s_waitcnt lgkmcnt(5)
	v_add_f32_e32 v140, v140, v222
	s_waitcnt lgkmcnt(4)
	v_add_f32_e32 v141, v141, v223
	s_waitcnt lgkmcnt(3)
	v_add_f32_e32 v142, v142, v224
	s_waitcnt lgkmcnt(2)
	v_add_f32_e32 v143, v143, v225
	s_waitcnt lgkmcnt(1)
	v_add_f32_e32 v144, v144, v226
	s_waitcnt lgkmcnt(0)
	v_add_f32_e32 v145, v145, v227
	ds_bpermute_b32 v220, v169, v138
	ds_bpermute_b32 v221, v169, v139
	ds_bpermute_b32 v222, v169, v140
	ds_bpermute_b32 v223, v169, v141
	ds_bpermute_b32 v224, v169, v142
	ds_bpermute_b32 v225, v169, v143
	ds_bpermute_b32 v226, v169, v144
	ds_bpermute_b32 v227, v169, v145
	s_waitcnt lgkmcnt(7)
	v_add_f32_e32 v138, v138, v220
	s_waitcnt lgkmcnt(6)
	v_add_f32_e32 v139, v139, v221
	s_waitcnt lgkmcnt(5)
	v_add_f32_e32 v140, v140, v222
	s_waitcnt lgkmcnt(4)
	v_add_f32_e32 v141, v141, v223
	s_waitcnt lgkmcnt(3)
	v_add_f32_e32 v142, v142, v224
	s_waitcnt lgkmcnt(2)
	v_add_f32_e32 v143, v143, v225
	s_waitcnt lgkmcnt(1)
	v_add_f32_e32 v144, v144, v226
	s_waitcnt lgkmcnt(0)
	v_add_f32_e32 v145, v145, v227
	ds_bpermute_b32 v220, v171, v138
	ds_bpermute_b32 v221, v171, v139
	ds_bpermute_b32 v222, v171, v140
	ds_bpermute_b32 v223, v171, v141
	ds_bpermute_b32 v224, v171, v142
	ds_bpermute_b32 v225, v171, v143
	ds_bpermute_b32 v226, v171, v144
	ds_bpermute_b32 v227, v171, v145
	s_waitcnt lgkmcnt(7)
	v_add_f32_e32 v138, v138, v220
	s_waitcnt lgkmcnt(6)
	v_add_f32_e32 v139, v139, v221
	s_waitcnt lgkmcnt(5)
	v_add_f32_e32 v140, v140, v222
	s_waitcnt lgkmcnt(4)
	v_add_f32_e32 v141, v141, v223
	s_waitcnt lgkmcnt(3)
	v_add_f32_e32 v142, v142, v224
	s_waitcnt lgkmcnt(2)
	v_add_f32_e32 v143, v143, v225
	s_waitcnt lgkmcnt(1)
	v_add_f32_e32 v144, v144, v226
	s_waitcnt lgkmcnt(0)
	v_add_f32_e32 v145, v145, v227
	ds_bpermute_b32 v220, v172, v138
	ds_bpermute_b32 v221, v172, v139
	ds_bpermute_b32 v222, v172, v140
	ds_bpermute_b32 v223, v172, v141
	ds_bpermute_b32 v224, v172, v142
	ds_bpermute_b32 v225, v172, v143
	ds_bpermute_b32 v226, v172, v144
	ds_bpermute_b32 v227, v172, v145
	s_waitcnt lgkmcnt(7)
	v_add_f32_e32 v138, v138, v220
	s_waitcnt lgkmcnt(6)
	v_add_f32_e32 v139, v139, v221
	s_waitcnt lgkmcnt(5)
	v_add_f32_e32 v140, v140, v222
	s_waitcnt lgkmcnt(4)
	v_add_f32_e32 v141, v141, v223
	s_waitcnt lgkmcnt(3)
	v_add_f32_e32 v142, v142, v224
	s_waitcnt lgkmcnt(2)
	v_add_f32_e32 v143, v143, v225
	s_waitcnt lgkmcnt(1)
	v_add_f32_e32 v144, v144, v226
	s_waitcnt lgkmcnt(0)
	v_add_f32_e32 v145, v145, v227
	ds_bpermute_b32 v220, v173, v138
	ds_bpermute_b32 v221, v173, v139
	ds_bpermute_b32 v222, v173, v140
	ds_bpermute_b32 v223, v173, v141
	ds_bpermute_b32 v224, v173, v142
	ds_bpermute_b32 v225, v173, v143
	ds_bpermute_b32 v226, v173, v144
	ds_bpermute_b32 v227, v173, v145
	s_waitcnt lgkmcnt(7)
	v_add_f32_e32 v138, v138, v220
	s_waitcnt lgkmcnt(6)
	v_add_f32_e32 v139, v139, v221
	s_waitcnt lgkmcnt(5)
	v_add_f32_e32 v140, v140, v222
	s_waitcnt lgkmcnt(4)
	v_add_f32_e32 v141, v141, v223
	s_waitcnt lgkmcnt(3)
	v_add_f32_e32 v142, v142, v224
	s_waitcnt lgkmcnt(2)
	v_add_f32_e32 v143, v143, v225
	s_waitcnt lgkmcnt(1)
	v_add_f32_e32 v144, v144, v226
	s_waitcnt lgkmcnt(0)
	v_add_f32_e32 v145, v145, v227
	v_cmp_eq_u32_e32 vcc, 0, v174
	s_and_saveexec_b64 s[58:59], vcc
	global_store_dword v167, v130, s[10:11]
	global_store_dword v167, v131, s[10:11] offset:4
	global_store_dword v167, v132, s[10:11] offset:8
	global_store_dword v167, v133, s[10:11] offset:12
	global_store_dword v167, v134, s[10:11] offset:32
	global_store_dword v167, v135, s[10:11] offset:36
	global_store_dword v167, v136, s[10:11] offset:40
	global_store_dword v167, v137, s[10:11] offset:44
	global_store_dword v167, v138, s[10:11] offset:64
	global_store_dword v167, v139, s[10:11] offset:68
	global_store_dword v167, v140, s[10:11] offset:72
	global_store_dword v167, v141, s[10:11] offset:76
	global_store_dword v167, v142, s[10:11] offset:96
	global_store_dword v167, v143, s[10:11] offset:100
	global_store_dword v167, v144, s[10:11] offset:104
	global_store_dword v167, v145, s[10:11] offset:108
	s_mov_b64 exec, -1
	s_add_u32 s48, s48, 0x20000
	s_addc_u32 s49, s49, 0
	global_load_dword v130, v162, s[48:49]
	global_load_dword v212, v162, s[48:49] offset:128
	global_load_dword v131, v163, s[48:49]
	global_load_dword v213, v163, s[48:49] offset:128
	global_load_dword v132, v164, s[48:49]
	global_load_dword v214, v164, s[48:49] offset:128
	global_load_dword v133, v165, s[48:49]
	global_load_dword v215, v165, s[48:49] offset:128
	s_add_u32 s48, s48, 0x8000
	s_addc_u32 s49, s49, 0
	global_load_dword v134, v162, s[48:49]
	global_load_dword v216, v162, s[48:49] offset:128
	global_load_dword v135, v163, s[48:49]
	global_load_dword v217, v163, s[48:49] offset:128
	global_load_dword v136, v164, s[48:49]
	global_load_dword v218, v164, s[48:49] offset:128
	global_load_dword v137, v165, s[48:49]
	global_load_dword v219, v165, s[48:49] offset:128
	s_add_u32 s48, s48, 0x8000
	s_addc_u32 s49, s49, 0
	global_load_dword v138, v162, s[48:49]
	global_load_dword v220, v162, s[48:49] offset:128
	global_load_dword v139, v163, s[48:49]
	global_load_dword v221, v163, s[48:49] offset:128
	global_load_dword v140, v164, s[48:49]
	global_load_dword v222, v164, s[48:49] offset:128
	global_load_dword v141, v165, s[48:49]
	global_load_dword v223, v165, s[48:49] offset:128
	s_add_u32 s48, s48, 0x8000
	s_addc_u32 s49, s49, 0
	global_load_dword v142, v162, s[48:49]
	global_load_dword v224, v162, s[48:49] offset:128
	global_load_dword v143, v163, s[48:49]
	global_load_dword v225, v163, s[48:49] offset:128
	global_load_dword v144, v164, s[48:49]
	global_load_dword v226, v164, s[48:49] offset:128
	global_load_dword v145, v165, s[48:49]
	global_load_dword v227, v165, s[48:49] offset:128
	s_sub_u32 s48, s48, 0x18000
	s_subb_u32 s49, s49, 0
	s_waitcnt vmcnt(30)
	v_fmac_f32_e32 v130, v98, v175
	v_fmac_f32_e32 v212, v114, v176
	global_store_dword v162, v130, s[48:49]
	global_store_dword v162, v212, s[48:49] offset:128
	s_waitcnt vmcnt(30)
	v_fmac_f32_e32 v131, v99, v175
	v_fmac_f32_e32 v213, v115, v176
	global_store_dword v163, v131, s[48:49]
	global_store_dword v163, v213, s[48:49] offset:128
	s_waitcnt vmcnt(30)
	v_fmac_f32_e32 v132, v100, v175
	v_fmac_f32_e32 v214, v116, v176
	global_store_dword v164, v132, s[48:49]
	global_store_dword v164, v214, s[48:49] offset:128
	s_waitcnt vmcnt(30)
	v_fmac_f32_e32 v133, v101, v175
	v_fmac_f32_e32 v215, v117, v176
	global_store_dword v165, v133, s[48:49]
	global_store_dword v165, v215, s[48:49] offset:128
	s_add_u32 s48, s48, 0x8000
	s_addc_u32 s49, s49, 0
	s_waitcnt vmcnt(30)
	v_fmac_f32_e32 v134, v102, v175
	v_fmac_f32_e32 v216, v118, v176
	global_store_dword v162, v134, s[48:49]
	global_store_dword v162, v216, s[48:49] offset:128
	s_waitcnt vmcnt(30)
	v_fmac_f32_e32 v135, v103, v175
	v_fmac_f32_e32 v217, v119, v176
	global_store_dword v163, v135, s[48:49]
	global_store_dword v163, v217, s[48:49] offset:128
	s_waitcnt vmcnt(30)
	v_fmac_f32_e32 v136, v104, v175
	v_fmac_f32_e32 v218, v120, v176
	global_store_dword v164, v136, s[48:49]
	global_store_dword v164, v218, s[48:49] offset:128
	s_waitcnt vmcnt(30)
	v_fmac_f32_e32 v137, v105, v175
	v_fmac_f32_e32 v219, v121, v176
	global_store_dword v165, v137, s[48:49]
	global_store_dword v165, v219, s[48:49] offset:128
	s_add_u32 s48, s48, 0x8000
	s_addc_u32 s49, s49, 0
	s_waitcnt vmcnt(30)
	v_fmac_f32_e32 v138, v106, v175
	v_fmac_f32_e32 v220, v122, v176
	global_store_dword v162, v138, s[48:49]
	global_store_dword v162, v220, s[48:49] offset:128
	s_waitcnt vmcnt(30)
	v_fmac_f32_e32 v139, v107, v175
	v_fmac_f32_e32 v221, v123, v176
	global_store_dword v163, v139, s[48:49]
	global_store_dword v163, v221, s[48:49] offset:128
	s_waitcnt vmcnt(30)
	v_fmac_f32_e32 v140, v108, v175
	v_fmac_f32_e32 v222, v124, v176
	global_store_dword v164, v140, s[48:49]
	global_store_dword v164, v222, s[48:49] offset:128
	s_waitcnt vmcnt(30)
	v_fmac_f32_e32 v141, v109, v175
	v_fmac_f32_e32 v223, v125, v176
	global_store_dword v165, v141, s[48:49]
	global_store_dword v165, v223, s[48:49] offset:128
	s_add_u32 s48, s48, 0x8000
	s_addc_u32 s49, s49, 0
	s_waitcnt vmcnt(30)
	v_fmac_f32_e32 v142, v110, v175
	v_fmac_f32_e32 v224, v126, v176
	global_store_dword v162, v142, s[48:49]
	global_store_dword v162, v224, s[48:49] offset:128
	s_waitcnt vmcnt(30)
	v_fmac_f32_e32 v143, v111, v175
	v_fmac_f32_e32 v225, v127, v176
	global_store_dword v163, v143, s[48:49]
	global_store_dword v163, v225, s[48:49] offset:128
	s_waitcnt vmcnt(30)
	v_fmac_f32_e32 v144, v112, v175
	v_fmac_f32_e32 v226, v128, v176
	global_store_dword v164, v144, s[48:49]
	global_store_dword v164, v226, s[48:49] offset:128
	s_waitcnt vmcnt(30)
	v_fmac_f32_e32 v145, v113, v175
	v_fmac_f32_e32 v227, v129, v176
	global_store_dword v165, v145, s[48:49]
	global_store_dword v165, v227, s[48:49] offset:128
	s_sub_u32 s48, s48, 0x18000
	s_subb_u32 s49, s49, 0
	v_mul_f32_e32 v130, v130, v130
	v_fmac_f32_e32 v130, v212, v212
	v_mul_f32_e32 v131, v131, v131
	v_fmac_f32_e32 v131, v213, v213
	v_mul_f32_e32 v132, v132, v132
	v_fmac_f32_e32 v132, v214, v214
	v_mul_f32_e32 v133, v133, v133
	v_fmac_f32_e32 v133, v215, v215
	v_mul_f32_e32 v134, v134, v134
	v_fmac_f32_e32 v134, v216, v216
	v_mul_f32_e32 v135, v135, v135
	v_fmac_f32_e32 v135, v217, v217
	v_mul_f32_e32 v136, v136, v136
	v_fmac_f32_e32 v136, v218, v218
	v_mul_f32_e32 v137, v137, v137
	v_fmac_f32_e32 v137, v219, v219
	v_mul_f32_e32 v138, v138, v138
	v_fmac_f32_e32 v138, v220, v220
	v_mul_f32_e32 v139, v139, v139
	v_fmac_f32_e32 v139, v221, v221
	v_mul_f32_e32 v140, v140, v140
	v_fmac_f32_e32 v140, v222, v222
	v_mul_f32_e32 v141, v141, v141
	v_fmac_f32_e32 v141, v223, v223
	v_mul_f32_e32 v142, v142, v142
	v_fmac_f32_e32 v142, v224, v224
	v_mul_f32_e32 v143, v143, v143
	v_fmac_f32_e32 v143, v225, v225
	v_mul_f32_e32 v144, v144, v144
	v_fmac_f32_e32 v144, v226, v226
	v_mul_f32_e32 v145, v145, v145
	v_fmac_f32_e32 v145, v227, v227
	s_waitcnt lgkmcnt(0)
	ds_bpermute_b32 v212, v168, v130
	ds_bpermute_b32 v213, v168, v131
	ds_bpermute_b32 v214, v168, v132
	ds_bpermute_b32 v215, v168, v133
	ds_bpermute_b32 v216, v168, v134
	ds_bpermute_b32 v217, v168, v135
	ds_bpermute_b32 v218, v168, v136
	ds_bpermute_b32 v219, v168, v137
	s_waitcnt lgkmcnt(7)
	v_add_f32_e32 v130, v130, v212
	s_waitcnt lgkmcnt(6)
	v_add_f32_e32 v131, v131, v213
	s_waitcnt lgkmcnt(5)
	v_add_f32_e32 v132, v132, v214
	s_waitcnt lgkmcnt(4)
	v_add_f32_e32 v133, v133, v215
	s_waitcnt lgkmcnt(3)
	v_add_f32_e32 v134, v134, v216
	s_waitcnt lgkmcnt(2)
	v_add_f32_e32 v135, v135, v217
	s_waitcnt lgkmcnt(1)
	v_add_f32_e32 v136, v136, v218
	s_waitcnt lgkmcnt(0)
	v_add_f32_e32 v137, v137, v219
	ds_bpermute_b32 v212, v169, v130
	ds_bpermute_b32 v213, v169, v131
	ds_bpermute_b32 v214, v169, v132
	ds_bpermute_b32 v215, v169, v133
	ds_bpermute_b32 v216, v169, v134
	ds_bpermute_b32 v217, v169, v135
	ds_bpermute_b32 v218, v169, v136
	ds_bpermute_b32 v219, v169, v137
	s_waitcnt lgkmcnt(7)
	v_add_f32_e32 v130, v130, v212
	s_waitcnt lgkmcnt(6)
	v_add_f32_e32 v131, v131, v213
	s_waitcnt lgkmcnt(5)
	v_add_f32_e32 v132, v132, v214
	s_waitcnt lgkmcnt(4)
	v_add_f32_e32 v133, v133, v215
	s_waitcnt lgkmcnt(3)
	v_add_f32_e32 v134, v134, v216
	s_waitcnt lgkmcnt(2)
	v_add_f32_e32 v135, v135, v217
	s_waitcnt lgkmcnt(1)
	v_add_f32_e32 v136, v136, v218
	s_waitcnt lgkmcnt(0)
	v_add_f32_e32 v137, v137, v219
	ds_bpermute_b32 v212, v171, v130
	ds_bpermute_b32 v213, v171, v131
	ds_bpermute_b32 v214, v171, v132
	ds_bpermute_b32 v215, v171, v133
	ds_bpermute_b32 v216, v171, v134
	ds_bpermute_b32 v217, v171, v135
	ds_bpermute_b32 v218, v171, v136
	ds_bpermute_b32 v219, v171, v137
	s_waitcnt lgkmcnt(7)
	v_add_f32_e32 v130, v130, v212
	s_waitcnt lgkmcnt(6)
	v_add_f32_e32 v131, v131, v213
	s_waitcnt lgkmcnt(5)
	v_add_f32_e32 v132, v132, v214
	s_waitcnt lgkmcnt(4)
	v_add_f32_e32 v133, v133, v215
	s_waitcnt lgkmcnt(3)
	v_add_f32_e32 v134, v134, v216
	s_waitcnt lgkmcnt(2)
	v_add_f32_e32 v135, v135, v217
	s_waitcnt lgkmcnt(1)
	v_add_f32_e32 v136, v136, v218
	s_waitcnt lgkmcnt(0)
	v_add_f32_e32 v137, v137, v219
	ds_bpermute_b32 v212, v172, v130
	ds_bpermute_b32 v213, v172, v131
	ds_bpermute_b32 v214, v172, v132
	ds_bpermute_b32 v215, v172, v133
	ds_bpermute_b32 v216, v172, v134
	ds_bpermute_b32 v217, v172, v135
	ds_bpermute_b32 v218, v172, v136
	ds_bpermute_b32 v219, v172, v137
	s_waitcnt lgkmcnt(7)
	v_add_f32_e32 v130, v130, v212
	s_waitcnt lgkmcnt(6)
	v_add_f32_e32 v131, v131, v213
	s_waitcnt lgkmcnt(5)
	v_add_f32_e32 v132, v132, v214
	s_waitcnt lgkmcnt(4)
	v_add_f32_e32 v133, v133, v215
	s_waitcnt lgkmcnt(3)
	v_add_f32_e32 v134, v134, v216
	s_waitcnt lgkmcnt(2)
	v_add_f32_e32 v135, v135, v217
	s_waitcnt lgkmcnt(1)
	v_add_f32_e32 v136, v136, v218
	s_waitcnt lgkmcnt(0)
	v_add_f32_e32 v137, v137, v219
	ds_bpermute_b32 v212, v173, v130
	ds_bpermute_b32 v213, v173, v131
	ds_bpermute_b32 v214, v173, v132
	ds_bpermute_b32 v215, v173, v133
	ds_bpermute_b32 v216, v173, v134
	ds_bpermute_b32 v217, v173, v135
	ds_bpermute_b32 v218, v173, v136
	ds_bpermute_b32 v219, v173, v137
	s_waitcnt lgkmcnt(7)
	v_add_f32_e32 v130, v130, v212
	s_waitcnt lgkmcnt(6)
	v_add_f32_e32 v131, v131, v213
	s_waitcnt lgkmcnt(5)
	v_add_f32_e32 v132, v132, v214
	s_waitcnt lgkmcnt(4)
	v_add_f32_e32 v133, v133, v215
	s_waitcnt lgkmcnt(3)
	v_add_f32_e32 v134, v134, v216
	s_waitcnt lgkmcnt(2)
	v_add_f32_e32 v135, v135, v217
	s_waitcnt lgkmcnt(1)
	v_add_f32_e32 v136, v136, v218
	s_waitcnt lgkmcnt(0)
	v_add_f32_e32 v137, v137, v219
	ds_bpermute_b32 v220, v168, v138
	ds_bpermute_b32 v221, v168, v139
	ds_bpermute_b32 v222, v168, v140
	ds_bpermute_b32 v223, v168, v141
	ds_bpermute_b32 v224, v168, v142
	ds_bpermute_b32 v225, v168, v143
	ds_bpermute_b32 v226, v168, v144
	ds_bpermute_b32 v227, v168, v145
	s_waitcnt lgkmcnt(7)
	v_add_f32_e32 v138, v138, v220
	s_waitcnt lgkmcnt(6)
	v_add_f32_e32 v139, v139, v221
	s_waitcnt lgkmcnt(5)
	v_add_f32_e32 v140, v140, v222
	s_waitcnt lgkmcnt(4)
	v_add_f32_e32 v141, v141, v223
	s_waitcnt lgkmcnt(3)
	v_add_f32_e32 v142, v142, v224
	s_waitcnt lgkmcnt(2)
	v_add_f32_e32 v143, v143, v225
	s_waitcnt lgkmcnt(1)
	v_add_f32_e32 v144, v144, v226
	s_waitcnt lgkmcnt(0)
	v_add_f32_e32 v145, v145, v227
	ds_bpermute_b32 v220, v169, v138
	ds_bpermute_b32 v221, v169, v139
	ds_bpermute_b32 v222, v169, v140
	ds_bpermute_b32 v223, v169, v141
	ds_bpermute_b32 v224, v169, v142
	ds_bpermute_b32 v225, v169, v143
	ds_bpermute_b32 v226, v169, v144
	ds_bpermute_b32 v227, v169, v145
	s_waitcnt lgkmcnt(7)
	v_add_f32_e32 v138, v138, v220
	s_waitcnt lgkmcnt(6)
	v_add_f32_e32 v139, v139, v221
	s_waitcnt lgkmcnt(5)
	v_add_f32_e32 v140, v140, v222
	s_waitcnt lgkmcnt(4)
	v_add_f32_e32 v141, v141, v223
	s_waitcnt lgkmcnt(3)
	v_add_f32_e32 v142, v142, v224
	s_waitcnt lgkmcnt(2)
	v_add_f32_e32 v143, v143, v225
	s_waitcnt lgkmcnt(1)
	v_add_f32_e32 v144, v144, v226
	s_waitcnt lgkmcnt(0)
	v_add_f32_e32 v145, v145, v227
	ds_bpermute_b32 v220, v171, v138
	ds_bpermute_b32 v221, v171, v139
	ds_bpermute_b32 v222, v171, v140
	ds_bpermute_b32 v223, v171, v141
	ds_bpermute_b32 v224, v171, v142
	ds_bpermute_b32 v225, v171, v143
	ds_bpermute_b32 v226, v171, v144
	ds_bpermute_b32 v227, v171, v145
	s_waitcnt lgkmcnt(7)
	v_add_f32_e32 v138, v138, v220
	s_waitcnt lgkmcnt(6)
	v_add_f32_e32 v139, v139, v221
	s_waitcnt lgkmcnt(5)
	v_add_f32_e32 v140, v140, v222
	s_waitcnt lgkmcnt(4)
	v_add_f32_e32 v141, v141, v223
	s_waitcnt lgkmcnt(3)
	v_add_f32_e32 v142, v142, v224
	s_waitcnt lgkmcnt(2)
	v_add_f32_e32 v143, v143, v225
	s_waitcnt lgkmcnt(1)
	v_add_f32_e32 v144, v144, v226
	s_waitcnt lgkmcnt(0)
	v_add_f32_e32 v145, v145, v227
	ds_bpermute_b32 v220, v172, v138
	ds_bpermute_b32 v221, v172, v139
	ds_bpermute_b32 v222, v172, v140
	ds_bpermute_b32 v223, v172, v141
	ds_bpermute_b32 v224, v172, v142
	ds_bpermute_b32 v225, v172, v143
	ds_bpermute_b32 v226, v172, v144
	ds_bpermute_b32 v227, v172, v145
	s_waitcnt lgkmcnt(7)
	v_add_f32_e32 v138, v138, v220
	s_waitcnt lgkmcnt(6)
	v_add_f32_e32 v139, v139, v221
	s_waitcnt lgkmcnt(5)
	v_add_f32_e32 v140, v140, v222
	s_waitcnt lgkmcnt(4)
	v_add_f32_e32 v141, v141, v223
	s_waitcnt lgkmcnt(3)
	v_add_f32_e32 v142, v142, v224
	s_waitcnt lgkmcnt(2)
	v_add_f32_e32 v143, v143, v225
	s_waitcnt lgkmcnt(1)
	v_add_f32_e32 v144, v144, v226
	s_waitcnt lgkmcnt(0)
	v_add_f32_e32 v145, v145, v227
	ds_bpermute_b32 v220, v173, v138
	ds_bpermute_b32 v221, v173, v139
	ds_bpermute_b32 v222, v173, v140
	ds_bpermute_b32 v223, v173, v141
	ds_bpermute_b32 v224, v173, v142
	ds_bpermute_b32 v225, v173, v143
	ds_bpermute_b32 v226, v173, v144
	ds_bpermute_b32 v227, v173, v145
	s_waitcnt lgkmcnt(7)
	v_add_f32_e32 v138, v138, v220
	s_waitcnt lgkmcnt(6)
	v_add_f32_e32 v139, v139, v221
	s_waitcnt lgkmcnt(5)
	v_add_f32_e32 v140, v140, v222
	s_waitcnt lgkmcnt(4)
	v_add_f32_e32 v141, v141, v223
	s_waitcnt lgkmcnt(3)
	v_add_f32_e32 v142, v142, v224
	s_waitcnt lgkmcnt(2)
	v_add_f32_e32 v143, v143, v225
	s_waitcnt lgkmcnt(1)
	v_add_f32_e32 v144, v144, v226
	s_waitcnt lgkmcnt(0)
	v_add_f32_e32 v145, v145, v227
	v_cmp_eq_u32_e32 vcc, 0, v174
	s_and_saveexec_b64 s[58:59], vcc
	global_store_dword v167, v130, s[10:11] offset:128
	global_store_dword v167, v131, s[10:11] offset:132
	global_store_dword v167, v132, s[10:11] offset:136
	global_store_dword v167, v133, s[10:11] offset:140
	global_store_dword v167, v134, s[10:11] offset:160
	global_store_dword v167, v135, s[10:11] offset:164
	global_store_dword v167, v136, s[10:11] offset:168
	global_store_dword v167, v137, s[10:11] offset:172
	global_store_dword v167, v138, s[10:11] offset:192
	global_store_dword v167, v139, s[10:11] offset:196
	global_store_dword v167, v140, s[10:11] offset:200
	global_store_dword v167, v141, s[10:11] offset:204
	global_store_dword v167, v142, s[10:11] offset:224
	global_store_dword v167, v143, s[10:11] offset:228
	global_store_dword v167, v144, s[10:11] offset:232
	global_store_dword v167, v145, s[10:11] offset:236
	s_mov_b64 exec, -1
	s_sub_u32 s48, s48, 0x20000
	s_subb_u32 s49, s49, 0
	v_readlane_b32 s2, v246, 14
	s_nop 0
	s_add_i32 s16, s16, s2
	s_branch .Lhw_outproj_tloop

.LBB0_2297:
	s_lshl_b32 s58, s88, 1
	v_readlane_b32 s0, v246, 25
	v_readlane_b32 s66, v246, 19
	s_cmp_gt_i32 s0, 1
	s_mov_b64 s[0:1], -1
	s_mov_b32 s59, 0x30000
	s_movk_i32 s62, 0xfff
	s_mov_b32 s63, 0x20000
	s_mov_b32 s64, 0xfffffc0
	s_movk_i32 s65, 0x1ff
	v_readlane_b32 s67, v246, 20
	s_cbranch_scc0 .LBB0_2457
	v_readlane_b32 s0, v246, 26
	v_readlane_b32 s10, v247, 19
	s_cmp_eq_u32 s0, 11
	v_readlane_b32 s11, v247, 20
	s_cselect_b64 s[8:9], -1, 0
	s_mov_b64 s[0:1], s[84:85]
	s_andn2_b64 vcc, exec, s[10:11]
	s_cbranch_vccnz .LBB0_2365
	v_cndmask_b32_e64 v0, 0, 1, s[8:9]
	s_load_dwordx2 s[40:41], s[0:1], 0x108
	v_readfirstlane_b32 s2, v0
	s_or_b32 s2, s58, s2
	s_and_b64 s[10:11], s[8:9], exec
	s_cselect_b32 s10, 3, 1
	v_readlane_b32 s11, v246, 27
	s_cselect_b32 s12, 8, 2
	s_add_i32 s10, s11, s10
	s_waitcnt lgkmcnt(0)
	s_add_u32 s42, s40, 0x3000000
	s_addc_u32 s43, s41, 0
	s_add_u32 s13, s40, 0x7bc0000
	s_addc_u32 s14, s41, 0
	s_mul_hi_i32 s11, s10, 0xc0000
	s_mul_i32 s10, s10, 0xc0000
	s_add_u32 s10, s40, s10
	s_addc_u32 s11, s41, s11
	s_add_u32 s44, s10, 0x7200000
	s_mul_hi_i32 s6, s2, 0x580000
	s_mul_i32 s2, s2, 0x580000
	s_addc_u32 s45, s11, 0
	s_add_u32 s2, s40, s2
	s_addc_u32 s6, s41, s6
	s_add_u32 s46, s2, 0xd478100
	s_addc_u32 s47, s6, 0
	v_readlane_b32 s15, v247, 44
	s_mov_b32 s16, s83
	s_lshl_b32 s2, s12, 12
	s_add_u32 s12, s13, s2
	s_addc_u32 s13, s14, 0
	v_and_b32_e32 v177, 63, v194
	v_lshrrev_b32_e32 v178, 6, v194
	v_lshrrev_b32_e32 v160, 2, v194
	v_mul_u32_u24_e32 v160, 0x1600, v160
	v_and_b32_e32 v179, 3, v177
	v_bfe_u32 v180, v177, 4, 2
	v_xor_b32_e32 v179, v179, v180
	v_lshl_add_u32 v160, v179, 4, v160
	v_add_u32_e32 v161, 0x58000, v160
	v_and_b32_e32 v174, 31, v177
	v_lshrrev_b32_e32 v182, 5, v177
	v_bfe_u32 v183, v174, 2, 2
	v_xor_b32_e32 v184, v182, v183
	v_xor_b32_e32 v185, 2, v184
	v_lshrrev_b32_e32 v186, 1, v178
	v_and_b32_e32 v187, 1, v178
	v_lshl_add_u32 v188, v186, 6, v174
	v_lshl_add_u32 v189, v187, 6, v174
	v_lshlrev_b32_e32 v188, 6, v188
	v_lshlrev_b32_e32 v189, 6, v189
	v_lshl_add_u32 v154, v184, 4, v188
	v_lshl_add_u32 v155, v185, 4, v188
	v_lshl_add_u32 v156, v184, 4, v189
	v_lshl_add_u32 v157, v185, 4, v189
	v_add_u32_e32 v158, 0x2000, v156
	v_add_u32_e32 v159, 0x2000, v157
	v_lshrrev_b32_e32 v179, 3, v177
	v_lshl_add_u32 v179, v178, 3, v179
	v_mul_u32_u24_e32 v179, 0x1600, v179
	v_and_b32_e32 v180, 1, v178
	v_lshrrev_b32_e32 v183, 4, v177
	v_lshl_add_u32 v180, v180, 2, v183
	v_and_b32_e32 v183, 7, v177
	v_xor_b32_e32 v180, v180, v183
	v_lshl_add_u32 v160, v180, 4, v179
	v_add_u32_e32 v161, 0x58000, v160
	v_add_u32_e32 v242, 0x2c000, v160
	v_add_u32_e32 v243, 0x84000, v160
	v_bfe_u32 v183, v174, 1, 3
	v_or_b32_e32 v180, 0, v182
	v_xor_b32_e32 v180, v180, v183
	v_lshlrev_b32_e32 v180, 4, v180
	v_lshl_add_u32 v179, v186, 5, v174
	v_lshl_add_u32 v154, v179, 7, v180
	v_lshl_add_u32 v179, v187, 5, v174
	v_lshl_add_u32 v158, v179, 7, v180
	v_add_u32_e32 v238, 0x4000, v158
	v_or_b32_e32 v180, 4, v182
	v_xor_b32_e32 v180, v180, v183
	v_lshlrev_b32_e32 v180, 4, v180
	v_lshl_add_u32 v179, v186, 5, v174
	v_lshl_add_u32 v155, v179, 7, v180
	v_lshl_add_u32 v179, v187, 5, v174
	v_lshl_add_u32 v159, v179, 7, v180
	v_add_u32_e32 v239, 0x4000, v159
	v_or_b32_e32 v180, 2, v182
	v_xor_b32_e32 v180, v180, v183
	v_lshlrev_b32_e32 v180, 4, v180
	v_lshl_add_u32 v179, v186, 5, v174
	v_lshl_add_u32 v156, v179, 7, v180
	v_lshl_add_u32 v179, v187, 5, v174
	v_lshl_add_u32 v236, v179, 7, v180
	v_add_u32_e32 v240, 0x4000, v236
	v_or_b32_e32 v180, 6, v182
	v_xor_b32_e32 v180, v180, v183
	v_lshlrev_b32_e32 v180, 4, v180
	v_lshl_add_u32 v179, v186, 5, v174
	v_lshl_add_u32 v157, v179, 7, v180
	v_lshl_add_u32 v179, v187, 5, v174
	v_lshl_add_u32 v237, v179, 7, v180
	v_add_u32_e32 v241, 0x4000, v237
	v_lshlrev_b32_e32 v190, 6, v186
	v_lshl_add_u32 v190, v182, 2, v190
	v_lshl_add_u32 v191, v187, 6, v174
	v_lshlrev_b32_e32 v192, 12, v190
	v_lshl_add_u32 v162, v191, 2, v192
	v_add_u32_e32 v163, 0x1000, v162
	v_add_u32_e32 v164, 0x2000, v162
	v_add_u32_e32 v165, 0x3000, v162
	v_lshlrev_b32_e32 v166, 2, v191
	v_mul_u32_u24_e32 v167, 0xc000, v187
	v_lshl_add_u32 v167, v190, 2, v167
	v_xor_b32_e32 v168, 16, v177
	v_lshlrev_b32_e32 v168, 2, v168
	v_xor_b32_e32 v169, 8, v177
	v_lshlrev_b32_e32 v169, 2, v169
	v_xor_b32_e32 v171, 4, v177
	v_lshlrev_b32_e32 v171, 2, v171
	v_xor_b32_e32 v172, 2, v177
	v_lshlrev_b32_e32 v172, 2, v172
	v_xor_b32_e32 v173, 1, v177
	v_lshlrev_b32_e32 v173, 2, v173
	v_readfirstlane_b32 s65, v194
	s_nop 0
	s_lshl_b32 s65, s65, 4
	s_add_u32 s65, s65, 16
	s_mov_b32 s16, s83
.Lhw_ffndown_tloop:
	s_cmpk_gt_u32 s16, 47
	s_cbranch_scc1 .Lhw_ffndown_exit
	v_readlane_b32 s6, v246, 16
	s_lshr_b32 s2, s16, 2
	s_and_b32 s15, s16, 3
	s_add_i32 s6, s6, s2
	s_lshl_b32 s6, s6, 7
	s_lshl_b32 s15, s15, 8
	s_mul_i32 vcc_lo, s6, 0x1600
	s_add_u32 s66, s42, vcc_lo
	s_addc_u32 s67, s43, 0
	s_mul_i32 vcc_lo, s15, 0x1600
	s_add_u32 s62, s46, vcc_lo
	s_addc_u32 s63, s47, 0
	s_add_u32 s18, s62, 0xb0000
	s_addc_u32 s19, s63, 0
	s_barrier
	s_sub_u32 s66, s66, 64
	s_subb_u32 s67, s67, 0
	s_sub_u32 s62, s62, 64
	s_subb_u32 s63, s63, 0
	s_sub_u32 s18, s18, 64
	s_subb_u32 s19, s19, 0
	s_add_u32 m0, s65, 0x0
	s_nop 0
	global_load_lds_dwordx4 v242, s[66:67]
	s_add_u32 m0, s65, 0x1000
	s_nop 0
	global_load_lds_dwordx4 v243, s[66:67]
	s_add_u32 m0, s65, 0x2000
	s_nop 0
	global_load_lds_dwordx4 v242, s[62:63]
	s_add_u32 m0, s65, 0x3000
	s_nop 0
	global_load_lds_dwordx4 v243, s[62:63]
	s_add_u32 m0, s65, 0x4000
	s_nop 0
	global_load_lds_dwordx4 v242, s[18:19]
	s_add_u32 m0, s65, 0x5000
	s_nop 0
	global_load_lds_dwordx4 v243, s[18:19]
	s_add_u32 s66, s66, 64
	s_addc_u32 s67, s67, 0
	s_add_u32 s62, s62, 64
	s_addc_u32 s63, s63, 0
	s_add_u32 s18, s18, 64
	s_addc_u32 s19, s19, 0
	s_add_u32 m0, s65, 0x6000
	s_nop 0
	global_load_lds_dwordx4 v160, s[66:67]
	s_add_u32 m0, s65, 0x7000
	s_nop 0
	global_load_lds_dwordx4 v161, s[66:67]
	s_add_u32 m0, s65, 0x8000
	s_nop 0
	global_load_lds_dwordx4 v160, s[62:63]
	s_add_u32 m0, s65, 0x9000
	s_nop 0
	global_load_lds_dwordx4 v161, s[62:63]
	s_add_u32 m0, s65, 0xa000
	s_nop 0
	global_load_lds_dwordx4 v160, s[18:19]
	s_add_u32 m0, s65, 0xb000
	s_nop 0
	global_load_lds_dwordx4 v161, s[18:19]
	s_add_u32 s66, s66, 64
	s_addc_u32 s67, s67, 0
	s_add_u32 s62, s62, 64
	s_addc_u32 s63, s63, 0
	s_add_u32 s18, s18, 64
	s_addc_u32 s19, s19, 0
	v_mov_b32_e32 v2, 0
	v_mov_b32_e32 v3, 0
	v_mov_b32_e32 v4, 0
	v_mov_b32_e32 v5, 0
	v_mov_b32_e32 v6, 0
	v_mov_b32_e32 v7, 0
	v_mov_b32_e32 v8, 0
	v_mov_b32_e32 v9, 0
	v_mov_b32_e32 v10, 0
	v_mov_b32_e32 v11, 0
	v_mov_b32_e32 v12, 0
	v_mov_b32_e32 v13, 0
	v_mov_b32_e32 v14, 0
	v_mov_b32_e32 v15, 0
	v_mov_b32_e32 v16, 0
	v_mov_b32_e32 v17, 0
	v_mov_b32_e32 v18, 0
	v_mov_b32_e32 v19, 0
	v_mov_b32_e32 v20, 0
	v_mov_b32_e32 v21, 0
	v_mov_b32_e32 v22, 0
	v_mov_b32_e32 v23, 0
	v_mov_b32_e32 v24, 0
	v_mov_b32_e32 v25, 0
	v_mov_b32_e32 v26, 0
	v_mov_b32_e32 v27, 0
	v_mov_b32_e32 v28, 0
	v_mov_b32_e32 v29, 0
	v_mov_b32_e32 v30, 0
	v_mov_b32_e32 v31, 0
	v_mov_b32_e32 v32, 0
	v_mov_b32_e32 v33, 0
	v_mov_b32_e32 v34, 0
	v_mov_b32_e32 v35, 0
	v_mov_b32_e32 v36, 0
	v_mov_b32_e32 v37, 0
	v_mov_b32_e32 v38, 0
	v_mov_b32_e32 v39, 0
	v_mov_b32_e32 v40, 0
	v_mov_b32_e32 v41, 0
	v_mov_b32_e32 v42, 0
	v_mov_b32_e32 v43, 0
	v_mov_b32_e32 v44, 0
	v_mov_b32_e32 v45, 0
	v_mov_b32_e32 v46, 0
	v_mov_b32_e32 v47, 0
	v_mov_b32_e32 v48, 0
	v_mov_b32_e32 v49, 0
	v_mov_b32_e32 v50, 0
	v_mov_b32_e32 v51, 0
	v_mov_b32_e32 v52, 0
	v_mov_b32_e32 v53, 0
	v_mov_b32_e32 v54, 0
	v_mov_b32_e32 v55, 0
	v_mov_b32_e32 v56, 0
	v_mov_b32_e32 v57, 0
	v_mov_b32_e32 v58, 0
	v_mov_b32_e32 v59, 0
	v_mov_b32_e32 v60, 0
	v_mov_b32_e32 v61, 0
	v_mov_b32_e32 v62, 0
	v_mov_b32_e32 v63, 0
	v_mov_b32_e32 v64, 0
	v_mov_b32_e32 v65, 0
	v_mov_b32_e32 v66, 0
	v_mov_b32_e32 v67, 0
	v_mov_b32_e32 v68, 0
	v_mov_b32_e32 v69, 0
	v_mov_b32_e32 v70, 0
	v_mov_b32_e32 v71, 0
	v_mov_b32_e32 v72, 0
	v_mov_b32_e32 v73, 0
	v_mov_b32_e32 v74, 0
	v_mov_b32_e32 v75, 0
	v_mov_b32_e32 v76, 0
	v_mov_b32_e32 v77, 0
	v_mov_b32_e32 v78, 0
	v_mov_b32_e32 v79, 0
	v_mov_b32_e32 v80, 0
	v_mov_b32_e32 v81, 0
	v_mov_b32_e32 v82, 0
	v_mov_b32_e32 v83, 0
	v_mov_b32_e32 v84, 0
	v_mov_b32_e32 v85, 0
	v_mov_b32_e32 v86, 0
	v_mov_b32_e32 v87, 0
	v_mov_b32_e32 v88, 0
	v_mov_b32_e32 v89, 0
	v_mov_b32_e32 v90, 0
	v_mov_b32_e32 v91, 0
	v_mov_b32_e32 v92, 0
	v_mov_b32_e32 v93, 0
	v_mov_b32_e32 v94, 0
	v_mov_b32_e32 v95, 0
	v_mov_b32_e32 v96, 0
	v_mov_b32_e32 v97, 0
	v_mov_b32_e32 v98, 0
	v_mov_b32_e32 v99, 0
	v_mov_b32_e32 v100, 0
	v_mov_b32_e32 v101, 0
	v_mov_b32_e32 v102, 0
	v_mov_b32_e32 v103, 0
	v_mov_b32_e32 v104, 0
	v_mov_b32_e32 v105, 0
	v_mov_b32_e32 v106, 0
	v_mov_b32_e32 v107, 0
	v_mov_b32_e32 v108, 0
	v_mov_b32_e32 v109, 0
	v_mov_b32_e32 v110, 0
	v_mov_b32_e32 v111, 0
	v_mov_b32_e32 v112, 0
	v_mov_b32_e32 v113, 0
	v_mov_b32_e32 v114, 0
	v_mov_b32_e32 v115, 0
	v_mov_b32_e32 v116, 0
	v_mov_b32_e32 v117, 0
	v_mov_b32_e32 v118, 0
	v_mov_b32_e32 v119, 0
	v_mov_b32_e32 v120, 0
	v_mov_b32_e32 v121, 0
	v_mov_b32_e32 v122, 0
	v_mov_b32_e32 v123, 0
	v_mov_b32_e32 v124, 0
	v_mov_b32_e32 v125, 0
	v_mov_b32_e32 v126, 0
	v_mov_b32_e32 v127, 0
	v_mov_b32_e32 v128, 0
	v_mov_b32_e32 v129, 0
	s_waitcnt vmcnt(0)
	s_barrier
	ds_read_b128 v[134:137], v155 offset:16
	ds_read_b128 v[142:145], v159 offset:8208
	ds_read_b128 v[150:153], v239 offset:16
	s_mov_b32 s59, 14
.Lhw_ffndown_loop:
	s_waitcnt vmcnt(0)
	s_barrier
	ds_read_b128 v[130:133], v154 offset:24592
	ds_read_b128 v[138:141], v158 offset:32784
	ds_read_b128 v[146:149], v238 offset:24592
	s_waitcnt lgkmcnt(4)
	v_mfma_f32_32x32x16_bf16 v[50:65], v[134:137], v[142:145], v[50:65]
	s_add_u32 m0, s65, 0xc000
	ds_read_b128 v[216:219], v157 offset:16
	global_load_lds_dwordx4 v242, s[66:67]
	s_waitcnt lgkmcnt(4)
	v_mfma_f32_32x32x16_bf16 v[114:129], v[134:137], v[150:153], v[114:129]
	s_add_u32 m0, s65, 0xd000
	ds_read_b128 v[224:227], v237 offset:8208
	global_load_lds_dwordx4 v243, s[66:67]
	s_waitcnt lgkmcnt(4)
	v_mfma_f32_32x32x16_bf16 v[18:33], v[130:133], v[142:145], v[18:33]
	s_add_u32 m0, s65, 0xe000
	ds_read_b128 v[232:235], v241 offset:16
	global_load_lds_dwordx4 v242, s[62:63]
	s_waitcnt lgkmcnt(4)
	v_mfma_f32_32x32x16_bf16 v[34:49], v[134:137], v[138:141], v[34:49]
	s_add_u32 m0, s65, 0xf000
	ds_read_b128 v[212:215], v156 offset:24592
	global_load_lds_dwordx4 v243, s[62:63]
	v_mfma_f32_32x32x16_bf16 v[82:97], v[130:133], v[150:153], v[82:97]
	s_add_u32 m0, s65, 0x10000
	ds_read_b128 v[220:223], v236 offset:32784
	global_load_lds_dwordx4 v242, s[18:19]
	s_waitcnt lgkmcnt(5)
	v_mfma_f32_32x32x16_bf16 v[98:113], v[134:137], v[146:149], v[98:113]
	s_add_u32 m0, s65, 0x11000
	ds_read_b128 v[228:231], v240 offset:24592
	global_load_lds_dwordx4 v243, s[18:19]
	v_mfma_f32_32x32x16_bf16 v[2:17], v[130:133], v[138:141], v[2:17]
	v_mfma_f32_32x32x16_bf16 v[66:81], v[130:133], v[146:149], v[66:81]
	s_waitcnt lgkmcnt(4)
	v_mfma_f32_32x32x16_bf16 v[50:65], v[216:219], v[224:227], v[50:65]
	ds_read_b128 v[130:133], v155 offset:24592
	s_waitcnt lgkmcnt(4)
	v_mfma_f32_32x32x16_bf16 v[114:129], v[216:219], v[232:235], v[114:129]
	ds_read_b128 v[138:141], v159 offset:32784
	s_waitcnt lgkmcnt(4)
	v_mfma_f32_32x32x16_bf16 v[18:33], v[212:215], v[224:227], v[18:33]
	ds_read_b128 v[146:149], v239 offset:24592
	s_waitcnt lgkmcnt(4)
	v_mfma_f32_32x32x16_bf16 v[34:49], v[216:219], v[220:223], v[34:49]
	s_add_u32 s66, s66, 64
	s_addc_u32 s67, s67, 0
	v_mfma_f32_32x32x16_bf16 v[82:97], v[212:215], v[232:235], v[82:97]
	s_add_u32 s62, s62, 64
	s_addc_u32 s63, s63, 0
	s_waitcnt lgkmcnt(3)
	v_mfma_f32_32x32x16_bf16 v[98:113], v[216:219], v[228:231], v[98:113]
	s_add_u32 s18, s18, 64
	s_addc_u32 s19, s19, 0
	v_mfma_f32_32x32x16_bf16 v[2:17], v[212:215], v[220:223], v[2:17]
	v_mfma_f32_32x32x16_bf16 v[66:81], v[212:215], v[228:231], v[66:81]
	s_waitcnt vmcnt(0)
	s_barrier
	ds_read_b128 v[134:137], v154 offset:49168
	ds_read_b128 v[142:145], v158 offset:57360
	ds_read_b128 v[150:153], v238 offset:49168
	s_waitcnt lgkmcnt(4)
	v_mfma_f32_32x32x16_bf16 v[2:17], v[130:133], v[138:141], v[2:17]
	s_add_u32 m0, s65, 0x0
	ds_read_b128 v[212:215], v157 offset:24592
	global_load_lds_dwordx4 v160, s[66:67]
	s_waitcnt lgkmcnt(4)
	v_mfma_f32_32x32x16_bf16 v[66:81], v[130:133], v[146:149], v[66:81]
	s_add_u32 m0, s65, 0x1000
	ds_read_b128 v[220:223], v237 offset:32784
	global_load_lds_dwordx4 v161, s[66:67]
	s_waitcnt lgkmcnt(3)
	v_mfma_f32_32x32x16_bf16 v[18:33], v[130:133], v[142:145], v[18:33]
	s_add_u32 m0, s65, 0x2000
	ds_read_b128 v[228:231], v241 offset:24592
	global_load_lds_dwordx4 v160, s[62:63]
	v_mfma_f32_32x32x16_bf16 v[34:49], v[134:137], v[138:141], v[34:49]
	s_add_u32 m0, s65, 0x3000
	ds_read_b128 v[216:219], v156 offset:49168
	global_load_lds_dwordx4 v161, s[62:63]
	s_waitcnt lgkmcnt(4)
	v_mfma_f32_32x32x16_bf16 v[82:97], v[130:133], v[150:153], v[82:97]
	s_add_u32 m0, s65, 0x4000
	ds_read_b128 v[224:227], v236 offset:57360
	global_load_lds_dwordx4 v160, s[18:19]
	v_mfma_f32_32x32x16_bf16 v[98:113], v[134:137], v[146:149], v[98:113]
	s_add_u32 m0, s65, 0x5000
	ds_read_b128 v[232:235], v240 offset:49168
	global_load_lds_dwordx4 v161, s[18:19]
	v_mfma_f32_32x32x16_bf16 v[50:65], v[134:137], v[142:145], v[50:65]
	v_mfma_f32_32x32x16_bf16 v[114:129], v[134:137], v[150:153], v[114:129]
	s_waitcnt lgkmcnt(4)
	v_mfma_f32_32x32x16_bf16 v[2:17], v[212:215], v[220:223], v[2:17]
	ds_read_b128 v[134:137], v155 offset:49168
	s_waitcnt lgkmcnt(4)
	v_mfma_f32_32x32x16_bf16 v[66:81], v[212:215], v[228:231], v[66:81]
	ds_read_b128 v[142:145], v159 offset:57360
	s_waitcnt lgkmcnt(3)
	v_mfma_f32_32x32x16_bf16 v[18:33], v[212:215], v[224:227], v[18:33]
	ds_read_b128 v[150:153], v239 offset:49168
	v_mfma_f32_32x32x16_bf16 v[34:49], v[216:219], v[220:223], v[34:49]
	s_add_u32 s66, s66, 64
	s_addc_u32 s67, s67, 0
	s_waitcnt lgkmcnt(3)
	v_mfma_f32_32x32x16_bf16 v[82:97], v[212:215], v[232:235], v[82:97]
	s_add_u32 s62, s62, 64
	s_addc_u32 s63, s63, 0
	v_mfma_f32_32x32x16_bf16 v[98:113], v[216:219], v[228:231], v[98:113]
	s_add_u32 s18, s18, 64
	s_addc_u32 s19, s19, 0
	v_mfma_f32_32x32x16_bf16 v[50:65], v[216:219], v[224:227], v[50:65]
	v_mfma_f32_32x32x16_bf16 v[114:129], v[216:219], v[232:235], v[114:129]
	s_waitcnt vmcnt(0)
	s_barrier
	ds_read_b128 v[130:133], v154 offset:16
	ds_read_b128 v[138:141], v158 offset:8208
	ds_read_b128 v[146:149], v238 offset:16
	s_waitcnt lgkmcnt(4)
	v_mfma_f32_32x32x16_bf16 v[50:65], v[134:137], v[142:145], v[50:65]
	s_add_u32 m0, s65, 0x6000
	ds_read_b128 v[216:219], v157 offset:49168
	global_load_lds_dwordx4 v242, s[66:67]
	s_waitcnt lgkmcnt(4)
	v_mfma_f32_32x32x16_bf16 v[114:129], v[134:137], v[150:153], v[114:129]
	s_add_u32 m0, s65, 0x7000
	ds_read_b128 v[224:227], v237 offset:57360
	global_load_lds_dwordx4 v243, s[66:67]
	s_waitcnt lgkmcnt(4)
	v_mfma_f32_32x32x16_bf16 v[18:33], v[130:133], v[142:145], v[18:33]
	s_add_u32 m0, s65, 0x8000
	ds_read_b128 v[232:235], v241 offset:49168
	global_load_lds_dwordx4 v242, s[62:63]
	s_waitcnt lgkmcnt(4)
	v_mfma_f32_32x32x16_bf16 v[34:49], v[134:137], v[138:141], v[34:49]
	s_add_u32 m0, s65, 0x9000
	ds_read_b128 v[212:215], v156 offset:16
	global_load_lds_dwordx4 v243, s[62:63]
	v_mfma_f32_32x32x16_bf16 v[82:97], v[130:133], v[150:153], v[82:97]
	s_add_u32 m0, s65, 0xa000
	ds_read_b128 v[220:223], v236 offset:8208
	global_load_lds_dwordx4 v242, s[18:19]
	s_waitcnt lgkmcnt(5)
	v_mfma_f32_32x32x16_bf16 v[98:113], v[134:137], v[146:149], v[98:113]
	s_add_u32 m0, s65, 0xb000
	ds_read_b128 v[228:231], v240 offset:16
	global_load_lds_dwordx4 v243, s[18:19]
	v_mfma_f32_32x32x16_bf16 v[2:17], v[130:133], v[138:141], v[2:17]
	v_mfma_f32_32x32x16_bf16 v[66:81], v[130:133], v[146:149], v[66:81]
	s_waitcnt lgkmcnt(4)
	v_mfma_f32_32x32x16_bf16 v[50:65], v[216:219], v[224:227], v[50:65]
	ds_read_b128 v[130:133], v155 offset:16
	s_waitcnt lgkmcnt(4)
	v_mfma_f32_32x32x16_bf16 v[114:129], v[216:219], v[232:235], v[114:129]
	ds_read_b128 v[138:141], v159 offset:8208
	s_waitcnt lgkmcnt(4)
	v_mfma_f32_32x32x16_bf16 v[18:33], v[212:215], v[224:227], v[18:33]
	ds_read_b128 v[146:149], v239 offset:16
	s_waitcnt lgkmcnt(4)
	v_mfma_f32_32x32x16_bf16 v[34:49], v[216:219], v[220:223], v[34:49]
	s_add_u32 s66, s66, 64
	s_addc_u32 s67, s67, 0
	v_mfma_f32_32x32x16_bf16 v[82:97], v[212:215], v[232:235], v[82:97]
	s_add_u32 s62, s62, 64
	s_addc_u32 s63, s63, 0
	s_waitcnt lgkmcnt(3)
	v_mfma_f32_32x32x16_bf16 v[98:113], v[216:219], v[228:231], v[98:113]
	s_add_u32 s18, s18, 64
	s_addc_u32 s19, s19, 0
	v_mfma_f32_32x32x16_bf16 v[2:17], v[212:215], v[220:223], v[2:17]
	v_mfma_f32_32x32x16_bf16 v[66:81], v[212:215], v[228:231], v[66:81]
	s_waitcnt vmcnt(0)
	s_barrier
	ds_read_b128 v[134:137], v154 offset:24592
	ds_read_b128 v[142:145], v158 offset:32784
	ds_read_b128 v[150:153], v238 offset:24592
	s_waitcnt lgkmcnt(4)
	v_mfma_f32_32x32x16_bf16 v[2:17], v[130:133], v[138:141], v[2:17]
	s_add_u32 m0, s65, 0xc000
	ds_read_b128 v[212:215], v157 offset:16
	global_load_lds_dwordx4 v160, s[66:67]
	s_waitcnt lgkmcnt(4)
	v_mfma_f32_32x32x16_bf16 v[66:81], v[130:133], v[146:149], v[66:81]
	s_add_u32 m0, s65, 0xd000
	ds_read_b128 v[220:223], v237 offset:8208
	global_load_lds_dwordx4 v161, s[66:67]
	s_waitcnt lgkmcnt(3)
	v_mfma_f32_32x32x16_bf16 v[18:33], v[130:133], v[142:145], v[18:33]
	s_add_u32 m0, s65, 0xe000
	ds_read_b128 v[228:231], v241 offset:16
	global_load_lds_dwordx4 v160, s[62:63]
	v_mfma_f32_32x32x16_bf16 v[34:49], v[134:137], v[138:141], v[34:49]
	s_add_u32 m0, s65, 0xf000
	ds_read_b128 v[216:219], v156 offset:24592
	global_load_lds_dwordx4 v161, s[62:63]
	s_waitcnt lgkmcnt(4)
	v_mfma_f32_32x32x16_bf16 v[82:97], v[130:133], v[150:153], v[82:97]
	s_add_u32 m0, s65, 0x10000
	ds_read_b128 v[224:227], v236 offset:32784
	global_load_lds_dwordx4 v160, s[18:19]
	v_mfma_f32_32x32x16_bf16 v[98:113], v[134:137], v[146:149], v[98:113]
	s_add_u32 m0, s65, 0x11000
	ds_read_b128 v[232:235], v240 offset:24592
	global_load_lds_dwordx4 v161, s[18:19]
	v_mfma_f32_32x32x16_bf16 v[50:65], v[134:137], v[142:145], v[50:65]
	v_mfma_f32_32x32x16_bf16 v[114:129], v[134:137], v[150:153], v[114:129]
	s_waitcnt lgkmcnt(4)
	v_mfma_f32_32x32x16_bf16 v[2:17], v[212:215], v[220:223], v[2:17]
	ds_read_b128 v[134:137], v155 offset:24592
	s_waitcnt lgkmcnt(4)
	v_mfma_f32_32x32x16_bf16 v[66:81], v[212:215], v[228:231], v[66:81]
	ds_read_b128 v[142:145], v159 offset:32784
	s_waitcnt lgkmcnt(3)
	v_mfma_f32_32x32x16_bf16 v[18:33], v[212:215], v[224:227], v[18:33]
	ds_read_b128 v[150:153], v239 offset:24592
	v_mfma_f32_32x32x16_bf16 v[34:49], v[216:219], v[220:223], v[34:49]
	s_add_u32 s66, s66, 64
	s_addc_u32 s67, s67, 0
	s_waitcnt lgkmcnt(3)
	v_mfma_f32_32x32x16_bf16 v[82:97], v[212:215], v[232:235], v[82:97]
	s_add_u32 s62, s62, 64
	s_addc_u32 s63, s63, 0
	v_mfma_f32_32x32x16_bf16 v[98:113], v[216:219], v[228:231], v[98:113]
	s_add_u32 s18, s18, 64
	s_addc_u32 s19, s19, 0
	v_mfma_f32_32x32x16_bf16 v[50:65], v[216:219], v[224:227], v[50:65]
	v_mfma_f32_32x32x16_bf16 v[114:129], v[216:219], v[232:235], v[114:129]
	s_waitcnt vmcnt(0)
	s_barrier
	ds_read_b128 v[130:133], v154 offset:49168
	ds_read_b128 v[138:141], v158 offset:57360
	ds_read_b128 v[146:149], v238 offset:49168
	s_waitcnt lgkmcnt(4)
	v_mfma_f32_32x32x16_bf16 v[50:65], v[134:137], v[142:145], v[50:65]
	s_add_u32 m0, s65, 0x0
	ds_read_b128 v[216:219], v157 offset:24592
	global_load_lds_dwordx4 v242, s[66:67]
	s_waitcnt lgkmcnt(4)
	v_mfma_f32_32x32x16_bf16 v[114:129], v[134:137], v[150:153], v[114:129]
	s_add_u32 m0, s65, 0x1000
	ds_read_b128 v[224:227], v237 offset:32784
	global_load_lds_dwordx4 v243, s[66:67]
	s_waitcnt lgkmcnt(4)
	v_mfma_f32_32x32x16_bf16 v[18:33], v[130:133], v[142:145], v[18:33]
	s_add_u32 m0, s65, 0x2000
	ds_read_b128 v[232:235], v241 offset:24592
	global_load_lds_dwordx4 v242, s[62:63]
	s_waitcnt lgkmcnt(4)
	v_mfma_f32_32x32x16_bf16 v[34:49], v[134:137], v[138:141], v[34:49]
	s_add_u32 m0, s65, 0x3000
	ds_read_b128 v[212:215], v156 offset:49168
	global_load_lds_dwordx4 v243, s[62:63]
	v_mfma_f32_32x32x16_bf16 v[82:97], v[130:133], v[150:153], v[82:97]
	s_add_u32 m0, s65, 0x4000
	ds_read_b128 v[220:223], v236 offset:57360
	global_load_lds_dwordx4 v242, s[18:19]
	s_waitcnt lgkmcnt(5)
	v_mfma_f32_32x32x16_bf16 v[98:113], v[134:137], v[146:149], v[98:113]
	s_add_u32 m0, s65, 0x5000
	ds_read_b128 v[228:231], v240 offset:49168
	global_load_lds_dwordx4 v243, s[18:19]
	v_mfma_f32_32x32x16_bf16 v[2:17], v[130:133], v[138:141], v[2:17]
	v_mfma_f32_32x32x16_bf16 v[66:81], v[130:133], v[146:149], v[66:81]
	s_waitcnt lgkmcnt(4)
	v_mfma_f32_32x32x16_bf16 v[50:65], v[216:219], v[224:227], v[50:65]
	ds_read_b128 v[130:133], v155 offset:49168
	s_waitcnt lgkmcnt(4)
	v_mfma_f32_32x32x16_bf16 v[114:129], v[216:219], v[232:235], v[114:129]
	ds_read_b128 v[138:141], v159 offset:57360
	s_waitcnt lgkmcnt(4)
	v_mfma_f32_32x32x16_bf16 v[18:33], v[212:215], v[224:227], v[18:33]
	ds_read_b128 v[146:149], v239 offset:49168
	s_waitcnt lgkmcnt(4)
	v_mfma_f32_32x32x16_bf16 v[34:49], v[216:219], v[220:223], v[34:49]
	s_add_u32 s66, s66, 64
	s_addc_u32 s67, s67, 0
	v_mfma_f32_32x32x16_bf16 v[82:97], v[212:215], v[232:235], v[82:97]
	s_add_u32 s62, s62, 64
	s_addc_u32 s63, s63, 0
	s_waitcnt lgkmcnt(3)
	v_mfma_f32_32x32x16_bf16 v[98:113], v[216:219], v[228:231], v[98:113]
	s_add_u32 s18, s18, 64
	s_addc_u32 s19, s19, 0
	v_mfma_f32_32x32x16_bf16 v[2:17], v[212:215], v[220:223], v[2:17]
	v_mfma_f32_32x32x16_bf16 v[66:81], v[212:215], v[228:231], v[66:81]
	s_waitcnt vmcnt(0)
	s_barrier
	ds_read_b128 v[134:137], v154 offset:16
	ds_read_b128 v[142:145], v158 offset:8208
	ds_read_b128 v[150:153], v238 offset:16
	s_waitcnt lgkmcnt(4)
	v_mfma_f32_32x32x16_bf16 v[2:17], v[130:133], v[138:141], v[2:17]
	s_add_u32 m0, s65, 0x6000
	ds_read_b128 v[212:215], v157 offset:49168
	global_load_lds_dwordx4 v160, s[66:67]
	s_waitcnt lgkmcnt(4)
	v_mfma_f32_32x32x16_bf16 v[66:81], v[130:133], v[146:149], v[66:81]
	s_add_u32 m0, s65, 0x7000
	ds_read_b128 v[220:223], v237 offset:57360
	global_load_lds_dwordx4 v161, s[66:67]
	s_waitcnt lgkmcnt(3)
	v_mfma_f32_32x32x16_bf16 v[18:33], v[130:133], v[142:145], v[18:33]
	s_add_u32 m0, s65, 0x8000
	ds_read_b128 v[228:231], v241 offset:49168
	global_load_lds_dwordx4 v160, s[62:63]
	v_mfma_f32_32x32x16_bf16 v[34:49], v[134:137], v[138:141], v[34:49]
	s_add_u32 m0, s65, 0x9000
	ds_read_b128 v[216:219], v156 offset:16
	global_load_lds_dwordx4 v161, s[62:63]
	s_waitcnt lgkmcnt(4)
	v_mfma_f32_32x32x16_bf16 v[82:97], v[130:133], v[150:153], v[82:97]
	s_add_u32 m0, s65, 0xa000
	ds_read_b128 v[224:227], v236 offset:8208
	global_load_lds_dwordx4 v160, s[18:19]
	v_mfma_f32_32x32x16_bf16 v[98:113], v[134:137], v[146:149], v[98:113]
	s_add_u32 m0, s65, 0xb000
	ds_read_b128 v[232:235], v240 offset:16
	global_load_lds_dwordx4 v161, s[18:19]
	v_mfma_f32_32x32x16_bf16 v[50:65], v[134:137], v[142:145], v[50:65]
	v_mfma_f32_32x32x16_bf16 v[114:129], v[134:137], v[150:153], v[114:129]
	s_waitcnt lgkmcnt(4)
	v_mfma_f32_32x32x16_bf16 v[2:17], v[212:215], v[220:223], v[2:17]
	ds_read_b128 v[134:137], v155 offset:16
	s_waitcnt lgkmcnt(4)
	v_mfma_f32_32x32x16_bf16 v[66:81], v[212:215], v[228:231], v[66:81]
	ds_read_b128 v[142:145], v159 offset:8208
	s_waitcnt lgkmcnt(3)
	v_mfma_f32_32x32x16_bf16 v[18:33], v[212:215], v[224:227], v[18:33]
	ds_read_b128 v[150:153], v239 offset:16
	v_mfma_f32_32x32x16_bf16 v[34:49], v[216:219], v[220:223], v[34:49]
	s_add_u32 s66, s66, 64
	s_addc_u32 s67, s67, 0
	s_waitcnt lgkmcnt(3)
	v_mfma_f32_32x32x16_bf16 v[82:97], v[212:215], v[232:235], v[82:97]
	s_add_u32 s62, s62, 64
	s_addc_u32 s63, s63, 0
	v_mfma_f32_32x32x16_bf16 v[98:113], v[216:219], v[228:231], v[98:113]
	s_add_u32 s18, s18, 64
	s_addc_u32 s19, s19, 0
	v_mfma_f32_32x32x16_bf16 v[50:65], v[216:219], v[224:227], v[50:65]
	v_mfma_f32_32x32x16_bf16 v[114:129], v[216:219], v[232:235], v[114:129]
	s_sub_u32 s59, s59, 1
	s_cmp_lg_u32 s59, 0
	s_cbranch_scc1 .Lhw_ffndown_loop
	s_waitcnt vmcnt(0)
	s_barrier
	ds_read_b128 v[130:133], v154 offset:24592
	ds_read_b128 v[138:141], v158 offset:32784
	ds_read_b128 v[146:149], v238 offset:24592
	s_waitcnt lgkmcnt(4)
	v_mfma_f32_32x32x16_bf16 v[50:65], v[134:137], v[142:145], v[50:65]
	s_add_u32 m0, s65, 0xc000
	ds_read_b128 v[216:219], v157 offset:16
	global_load_lds_dwordx4 v242, s[66:67]
	s_waitcnt lgkmcnt(4)
	v_mfma_f32_32x32x16_bf16 v[114:129], v[134:137], v[150:153], v[114:129]
	s_add_u32 m0, s65, 0xd000
	ds_read_b128 v[224:227], v237 offset:8208
	global_load_lds_dwordx4 v243, s[66:67]
	s_waitcnt lgkmcnt(4)
	v_mfma_f32_32x32x16_bf16 v[18:33], v[130:133], v[142:145], v[18:33]
	s_add_u32 m0, s65, 0xe000
	ds_read_b128 v[232:235], v241 offset:16
	global_load_lds_dwordx4 v242, s[62:63]
	s_waitcnt lgkmcnt(4)
	v_mfma_f32_32x32x16_bf16 v[34:49], v[134:137], v[138:141], v[34:49]
	s_add_u32 m0, s65, 0xf000
	ds_read_b128 v[212:215], v156 offset:24592
	global_load_lds_dwordx4 v243, s[62:63]
	v_mfma_f32_32x32x16_bf16 v[82:97], v[130:133], v[150:153], v[82:97]
	s_add_u32 m0, s65, 0x10000
	ds_read_b128 v[220:223], v236 offset:32784
	global_load_lds_dwordx4 v242, s[18:19]
	s_waitcnt lgkmcnt(5)
	v_mfma_f32_32x32x16_bf16 v[98:113], v[134:137], v[146:149], v[98:113]
	s_add_u32 m0, s65, 0x11000
	ds_read_b128 v[228:231], v240 offset:24592
	global_load_lds_dwordx4 v243, s[18:19]
	v_mfma_f32_32x32x16_bf16 v[2:17], v[130:133], v[138:141], v[2:17]
	v_mfma_f32_32x32x16_bf16 v[66:81], v[130:133], v[146:149], v[66:81]
	s_waitcnt lgkmcnt(4)
	v_mfma_f32_32x32x16_bf16 v[50:65], v[216:219], v[224:227], v[50:65]
	ds_read_b128 v[130:133], v155 offset:24592
	s_waitcnt lgkmcnt(4)
	v_mfma_f32_32x32x16_bf16 v[114:129], v[216:219], v[232:235], v[114:129]
	ds_read_b128 v[138:141], v159 offset:32784
	s_waitcnt lgkmcnt(4)
	v_mfma_f32_32x32x16_bf16 v[18:33], v[212:215], v[224:227], v[18:33]
	ds_read_b128 v[146:149], v239 offset:24592
	s_waitcnt lgkmcnt(4)
	v_mfma_f32_32x32x16_bf16 v[34:49], v[216:219], v[220:223], v[34:49]
	s_add_u32 s66, s66, 64
	s_addc_u32 s67, s67, 0
	v_mfma_f32_32x32x16_bf16 v[82:97], v[212:215], v[232:235], v[82:97]
	s_add_u32 s62, s62, 64
	s_addc_u32 s63, s63, 0
	s_waitcnt lgkmcnt(3)
	v_mfma_f32_32x32x16_bf16 v[98:113], v[216:219], v[228:231], v[98:113]
	s_add_u32 s18, s18, 64
	s_addc_u32 s19, s19, 0
	v_mfma_f32_32x32x16_bf16 v[2:17], v[212:215], v[220:223], v[2:17]
	v_mfma_f32_32x32x16_bf16 v[66:81], v[212:215], v[228:231], v[66:81]
	s_waitcnt vmcnt(0)
	s_barrier
	ds_read_b128 v[134:137], v154 offset:49168
	ds_read_b128 v[142:145], v158 offset:57360
	ds_read_b128 v[150:153], v238 offset:49168
	s_waitcnt lgkmcnt(4)
	v_mfma_f32_32x32x16_bf16 v[2:17], v[130:133], v[138:141], v[2:17]
	s_add_u32 m0, s65, 0x0
	ds_read_b128 v[212:215], v157 offset:24592
	global_load_lds_dwordx4 v160, s[66:67]
	s_waitcnt lgkmcnt(4)
	v_mfma_f32_32x32x16_bf16 v[66:81], v[130:133], v[146:149], v[66:81]
	s_add_u32 m0, s65, 0x1000
	ds_read_b128 v[220:223], v237 offset:32784
	global_load_lds_dwordx4 v161, s[66:67]
	s_waitcnt lgkmcnt(3)
	v_mfma_f32_32x32x16_bf16 v[18:33], v[130:133], v[142:145], v[18:33]
	s_add_u32 m0, s65, 0x2000
	ds_read_b128 v[228:231], v241 offset:24592
	global_load_lds_dwordx4 v160, s[62:63]
	v_mfma_f32_32x32x16_bf16 v[34:49], v[134:137], v[138:141], v[34:49]
	s_add_u32 m0, s65, 0x3000
	ds_read_b128 v[216:219], v156 offset:49168
	global_load_lds_dwordx4 v161, s[62:63]
	s_waitcnt lgkmcnt(4)
	v_mfma_f32_32x32x16_bf16 v[82:97], v[130:133], v[150:153], v[82:97]
	s_add_u32 m0, s65, 0x4000
	ds_read_b128 v[224:227], v236 offset:57360
	global_load_lds_dwordx4 v160, s[18:19]
	v_mfma_f32_32x32x16_bf16 v[98:113], v[134:137], v[146:149], v[98:113]
	s_add_u32 m0, s65, 0x5000
	ds_read_b128 v[232:235], v240 offset:49168
	global_load_lds_dwordx4 v161, s[18:19]
	v_mfma_f32_32x32x16_bf16 v[50:65], v[134:137], v[142:145], v[50:65]
	v_mfma_f32_32x32x16_bf16 v[114:129], v[134:137], v[150:153], v[114:129]
	s_waitcnt lgkmcnt(4)
	v_mfma_f32_32x32x16_bf16 v[2:17], v[212:215], v[220:223], v[2:17]
	ds_read_b128 v[134:137], v155 offset:49168
	s_waitcnt lgkmcnt(4)
	v_mfma_f32_32x32x16_bf16 v[66:81], v[212:215], v[228:231], v[66:81]
	ds_read_b128 v[142:145], v159 offset:57360
	s_waitcnt lgkmcnt(3)
	v_mfma_f32_32x32x16_bf16 v[18:33], v[212:215], v[224:227], v[18:33]
	ds_read_b128 v[150:153], v239 offset:49168
	v_mfma_f32_32x32x16_bf16 v[34:49], v[216:219], v[220:223], v[34:49]
	s_add_u32 s66, s66, 64
	s_addc_u32 s67, s67, 0
	s_waitcnt lgkmcnt(3)
	v_mfma_f32_32x32x16_bf16 v[82:97], v[212:215], v[232:235], v[82:97]
	s_add_u32 s62, s62, 64
	s_addc_u32 s63, s63, 0
	v_mfma_f32_32x32x16_bf16 v[98:113], v[216:219], v[228:231], v[98:113]
	s_add_u32 s18, s18, 64
	s_addc_u32 s19, s19, 0
	v_mfma_f32_32x32x16_bf16 v[50:65], v[216:219], v[224:227], v[50:65]
	v_mfma_f32_32x32x16_bf16 v[114:129], v[216:219], v[232:235], v[114:129]
	s_waitcnt vmcnt(0)
	s_barrier
	ds_read_b128 v[130:133], v154 offset:16
	ds_read_b128 v[138:141], v158 offset:8208
	ds_read_b128 v[146:149], v238 offset:16
	s_waitcnt lgkmcnt(4)
	v_mfma_f32_32x32x16_bf16 v[50:65], v[134:137], v[142:145], v[50:65]
	s_add_u32 m0, s65, 0x6000
	ds_read_b128 v[216:219], v157 offset:49168
	global_load_lds_dwordx4 v242, s[66:67]
	s_waitcnt lgkmcnt(4)
	v_mfma_f32_32x32x16_bf16 v[114:129], v[134:137], v[150:153], v[114:129]
	s_add_u32 m0, s65, 0x7000
	ds_read_b128 v[224:227], v237 offset:57360
	global_load_lds_dwordx4 v243, s[66:67]
	s_waitcnt lgkmcnt(4)
	v_mfma_f32_32x32x16_bf16 v[18:33], v[130:133], v[142:145], v[18:33]
	s_add_u32 m0, s65, 0x8000
	ds_read_b128 v[232:235], v241 offset:49168
	global_load_lds_dwordx4 v242, s[62:63]
	s_waitcnt lgkmcnt(4)
	v_mfma_f32_32x32x16_bf16 v[34:49], v[134:137], v[138:141], v[34:49]
	s_add_u32 m0, s65, 0x9000
	ds_read_b128 v[212:215], v156 offset:16
	global_load_lds_dwordx4 v243, s[62:63]
	v_mfma_f32_32x32x16_bf16 v[82:97], v[130:133], v[150:153], v[82:97]
	s_add_u32 m0, s65, 0xa000
	ds_read_b128 v[220:223], v236 offset:8208
	global_load_lds_dwordx4 v242, s[18:19]
	s_waitcnt lgkmcnt(5)
	v_mfma_f32_32x32x16_bf16 v[98:113], v[134:137], v[146:149], v[98:113]
	s_add_u32 m0, s65, 0xb000
	ds_read_b128 v[228:231], v240 offset:16
	global_load_lds_dwordx4 v243, s[18:19]
	v_mfma_f32_32x32x16_bf16 v[2:17], v[130:133], v[138:141], v[2:17]
	v_mfma_f32_32x32x16_bf16 v[66:81], v[130:133], v[146:149], v[66:81]
	s_waitcnt lgkmcnt(4)
	v_mfma_f32_32x32x16_bf16 v[50:65], v[216:219], v[224:227], v[50:65]
	ds_read_b128 v[130:133], v155 offset:16
	s_waitcnt lgkmcnt(4)
	v_mfma_f32_32x32x16_bf16 v[114:129], v[216:219], v[232:235], v[114:129]
	ds_read_b128 v[138:141], v159 offset:8208
	s_waitcnt lgkmcnt(4)
	v_mfma_f32_32x32x16_bf16 v[18:33], v[212:215], v[224:227], v[18:33]
	ds_read_b128 v[146:149], v239 offset:16
	s_waitcnt lgkmcnt(4)
	v_mfma_f32_32x32x16_bf16 v[34:49], v[216:219], v[220:223], v[34:49]
	s_add_u32 s66, s66, 64
	s_addc_u32 s67, s67, 0
	v_mfma_f32_32x32x16_bf16 v[82:97], v[212:215], v[232:235], v[82:97]
	s_add_u32 s62, s62, 64
	s_addc_u32 s63, s63, 0
	s_waitcnt lgkmcnt(3)
	v_mfma_f32_32x32x16_bf16 v[98:113], v[216:219], v[228:231], v[98:113]
	s_add_u32 s18, s18, 64
	s_addc_u32 s19, s19, 0
	v_mfma_f32_32x32x16_bf16 v[2:17], v[212:215], v[220:223], v[2:17]
	v_mfma_f32_32x32x16_bf16 v[66:81], v[212:215], v[228:231], v[66:81]
	s_waitcnt vmcnt(0)
	s_barrier
	ds_read_b128 v[134:137], v154 offset:24592
	ds_read_b128 v[142:145], v158 offset:32784
	ds_read_b128 v[150:153], v238 offset:24592
	s_waitcnt lgkmcnt(4)
	v_mfma_f32_32x32x16_bf16 v[2:17], v[130:133], v[138:141], v[2:17]
	ds_read_b128 v[212:215], v157 offset:16
	s_waitcnt lgkmcnt(4)
	v_mfma_f32_32x32x16_bf16 v[66:81], v[130:133], v[146:149], v[66:81]
	ds_read_b128 v[220:223], v237 offset:8208
	s_waitcnt lgkmcnt(3)
	v_mfma_f32_32x32x16_bf16 v[18:33], v[130:133], v[142:145], v[18:33]
	ds_read_b128 v[228:231], v241 offset:16
	v_mfma_f32_32x32x16_bf16 v[34:49], v[134:137], v[138:141], v[34:49]
	ds_read_b128 v[216:219], v156 offset:24592
	s_waitcnt lgkmcnt(4)
	v_mfma_f32_32x32x16_bf16 v[82:97], v[130:133], v[150:153], v[82:97]
	ds_read_b128 v[224:227], v236 offset:32784
	v_mfma_f32_32x32x16_bf16 v[98:113], v[134:137], v[146:149], v[98:113]
	ds_read_b128 v[232:235], v240 offset:24592
	v_mfma_f32_32x32x16_bf16 v[50:65], v[134:137], v[142:145], v[50:65]
	v_mfma_f32_32x32x16_bf16 v[114:129], v[134:137], v[150:153], v[114:129]
	s_waitcnt lgkmcnt(4)
	v_mfma_f32_32x32x16_bf16 v[2:17], v[212:215], v[220:223], v[2:17]
	s_waitcnt lgkmcnt(3)
	v_mfma_f32_32x32x16_bf16 v[66:81], v[212:215], v[228:231], v[66:81]
	s_waitcnt lgkmcnt(1)
	v_mfma_f32_32x32x16_bf16 v[18:33], v[212:215], v[224:227], v[18:33]
	v_mfma_f32_32x32x16_bf16 v[34:49], v[216:219], v[220:223], v[34:49]
	s_waitcnt lgkmcnt(0)
	v_mfma_f32_32x32x16_bf16 v[82:97], v[212:215], v[232:235], v[82:97]
	v_mfma_f32_32x32x16_bf16 v[98:113], v[216:219], v[228:231], v[98:113]
	v_mfma_f32_32x32x16_bf16 v[50:65], v[216:219], v[224:227], v[50:65]
	v_mfma_f32_32x32x16_bf16 v[114:129], v[216:219], v[232:235], v[114:129]
	s_nop 7
	s_nop 7
	s_sub_i32 s2, s6, 0x1000
	s_ashr_i32 s2, s2, 11
	s_add_i32 s2, s2, 1
	s_max_i32 s2, s2, 0
	v_readlane_b32 s17, v246, 28
	s_nop 0
	s_add_i32 s2, s2, s17
	s_mul_i32 s2, s2, 0x9000
	s_lshl_b32 s17, s15, 2
	s_add_u32 s2, s2, s17
	s_add_u32 s60, s12, s2
	s_addc_u32 s61, s13, 0
	s_lshr_b32 s2, s15, 7
	s_mul_i32 s2, s2, 0x18000
	s_lshl_b32 s20, s6, 2
	s_add_u32 s2, s2, s20
	s_add_u32 s10, s44, s2
	s_addc_u32 s11, s45, 0
	s_lshl_b32 s2, s6, 12
	s_add_u32 s2, s2, s17
	s_add_u32 s48, s40, s2
	s_addc_u32 s49, s41, 0
	global_load_dword v175, v166, s[60:61]
	global_load_dword v176, v166, s[60:61] offset:128
	global_load_dword v130, v162, s[48:49]
	global_load_dword v212, v162, s[48:49] offset:128
	global_load_dword v131, v163, s[48:49]
	global_load_dword v213, v163, s[48:49] offset:128
	global_load_dword v132, v164, s[48:49]
	global_load_dword v214, v164, s[48:49] offset:128
	global_load_dword v133, v165, s[48:49]
	global_load_dword v215, v165, s[48:49] offset:128
	s_add_u32 s48, s48, 0x8000
	s_addc_u32 s49, s49, 0
	global_load_dword v134, v162, s[48:49]
	global_load_dword v216, v162, s[48:49] offset:128
	global_load_dword v135, v163, s[48:49]
	global_load_dword v217, v163, s[48:49] offset:128
	global_load_dword v136, v164, s[48:49]
	global_load_dword v218, v164, s[48:49] offset:128
	global_load_dword v137, v165, s[48:49]
	global_load_dword v219, v165, s[48:49] offset:128
	s_add_u32 s48, s48, 0x8000
	s_addc_u32 s49, s49, 0
	global_load_dword v138, v162, s[48:49]
	global_load_dword v220, v162, s[48:49] offset:128
	global_load_dword v139, v163, s[48:49]
	global_load_dword v221, v163, s[48:49] offset:128
	global_load_dword v140, v164, s[48:49]
	global_load_dword v222, v164, s[48:49] offset:128
	global_load_dword v141, v165, s[48:49]
	global_load_dword v223, v165, s[48:49] offset:128
	s_add_u32 s48, s48, 0x8000
	s_addc_u32 s49, s49, 0
	global_load_dword v142, v162, s[48:49]
	global_load_dword v224, v162, s[48:49] offset:128
	global_load_dword v143, v163, s[48:49]
	global_load_dword v225, v163, s[48:49] offset:128
	global_load_dword v144, v164, s[48:49]
	global_load_dword v226, v164, s[48:49] offset:128
	global_load_dword v145, v165, s[48:49]
	global_load_dword v227, v165, s[48:49] offset:128
	s_sub_u32 s48, s48, 0x18000
	s_subb_u32 s49, s49, 0
	s_waitcnt vmcnt(32)
	v_mul_f32_e32 v175, 0.5, v175
	v_mul_f32_e32 v176, 0.5, v176
	s_waitcnt vmcnt(30)
	v_fmac_f32_e32 v130, v2, v175
	v_fmac_f32_e32 v212, v18, v176
	global_store_dword v162, v130, s[48:49]
	global_store_dword v162, v212, s[48:49] offset:128
	s_waitcnt vmcnt(30)
	v_fmac_f32_e32 v131, v3, v175
	v_fmac_f32_e32 v213, v19, v176
	global_store_dword v163, v131, s[48:49]
	global_store_dword v163, v213, s[48:49] offset:128
	s_waitcnt vmcnt(30)
	v_fmac_f32_e32 v132, v4, v175
	v_fmac_f32_e32 v214, v20, v176
	global_store_dword v164, v132, s[48:49]
	global_store_dword v164, v214, s[48:49] offset:128
	s_waitcnt vmcnt(30)
	v_fmac_f32_e32 v133, v5, v175
	v_fmac_f32_e32 v215, v21, v176
	global_store_dword v165, v133, s[48:49]
	global_store_dword v165, v215, s[48:49] offset:128
	s_add_u32 s48, s48, 0x8000
	s_addc_u32 s49, s49, 0
	s_waitcnt vmcnt(30)
	v_fmac_f32_e32 v134, v6, v175
	v_fmac_f32_e32 v216, v22, v176
	global_store_dword v162, v134, s[48:49]
	global_store_dword v162, v216, s[48:49] offset:128
	s_waitcnt vmcnt(30)
	v_fmac_f32_e32 v135, v7, v175
	v_fmac_f32_e32 v217, v23, v176
	global_store_dword v163, v135, s[48:49]
	global_store_dword v163, v217, s[48:49] offset:128
	s_waitcnt vmcnt(30)
	v_fmac_f32_e32 v136, v8, v175
	v_fmac_f32_e32 v218, v24, v176
	global_store_dword v164, v136, s[48:49]
	global_store_dword v164, v218, s[48:49] offset:128
	s_waitcnt vmcnt(30)
	v_fmac_f32_e32 v137, v9, v175
	v_fmac_f32_e32 v219, v25, v176
	global_store_dword v165, v137, s[48:49]
	global_store_dword v165, v219, s[48:49] offset:128
	s_add_u32 s48, s48, 0x8000
	s_addc_u32 s49, s49, 0
	s_waitcnt vmcnt(30)
	v_fmac_f32_e32 v138, v10, v175
	v_fmac_f32_e32 v220, v26, v176
	global_store_dword v162, v138, s[48:49]
	global_store_dword v162, v220, s[48:49] offset:128
	s_waitcnt vmcnt(30)
	v_fmac_f32_e32 v139, v11, v175
	v_fmac_f32_e32 v221, v27, v176
	global_store_dword v163, v139, s[48:49]
	global_store_dword v163, v221, s[48:49] offset:128
	s_waitcnt vmcnt(30)
	v_fmac_f32_e32 v140, v12, v175
	v_fmac_f32_e32 v222, v28, v176
	global_store_dword v164, v140, s[48:49]
	global_store_dword v164, v222, s[48:49] offset:128
	s_waitcnt vmcnt(30)
	v_fmac_f32_e32 v141, v13, v175
	v_fmac_f32_e32 v223, v29, v176
	global_store_dword v165, v141, s[48:49]
	global_store_dword v165, v223, s[48:49] offset:128
	s_add_u32 s48, s48, 0x8000
	s_addc_u32 s49, s49, 0
	s_waitcnt vmcnt(30)
	v_fmac_f32_e32 v142, v14, v175
	v_fmac_f32_e32 v224, v30, v176
	global_store_dword v162, v142, s[48:49]
	global_store_dword v162, v224, s[48:49] offset:128
	s_waitcnt vmcnt(30)
	v_fmac_f32_e32 v143, v15, v175
	v_fmac_f32_e32 v225, v31, v176
	global_store_dword v163, v143, s[48:49]
	global_store_dword v163, v225, s[48:49] offset:128
	s_waitcnt vmcnt(30)
	v_fmac_f32_e32 v144, v16, v175
	v_fmac_f32_e32 v226, v32, v176
	global_store_dword v164, v144, s[48:49]
	global_store_dword v164, v226, s[48:49] offset:128
	s_waitcnt vmcnt(30)
	v_fmac_f32_e32 v145, v17, v175
	v_fmac_f32_e32 v227, v33, v176
	global_store_dword v165, v145, s[48:49]
	global_store_dword v165, v227, s[48:49] offset:128
	s_sub_u32 s48, s48, 0x18000
	s_subb_u32 s49, s49, 0
	v_mul_f32_e32 v130, v130, v130
	v_fmac_f32_e32 v130, v212, v212
	v_mul_f32_e32 v131, v131, v131
	v_fmac_f32_e32 v131, v213, v213
	v_mul_f32_e32 v132, v132, v132
	v_fmac_f32_e32 v132, v214, v214
	v_mul_f32_e32 v133, v133, v133
	v_fmac_f32_e32 v133, v215, v215
	v_mul_f32_e32 v134, v134, v134
	v_fmac_f32_e32 v134, v216, v216
	v_mul_f32_e32 v135, v135, v135
	v_fmac_f32_e32 v135, v217, v217
	v_mul_f32_e32 v136, v136, v136
	v_fmac_f32_e32 v136, v218, v218
	v_mul_f32_e32 v137, v137, v137
	v_fmac_f32_e32 v137, v219, v219
	v_mul_f32_e32 v138, v138, v138
	v_fmac_f32_e32 v138, v220, v220
	v_mul_f32_e32 v139, v139, v139
	v_fmac_f32_e32 v139, v221, v221
	v_mul_f32_e32 v140, v140, v140
	v_fmac_f32_e32 v140, v222, v222
	v_mul_f32_e32 v141, v141, v141
	v_fmac_f32_e32 v141, v223, v223
	v_mul_f32_e32 v142, v142, v142
	v_fmac_f32_e32 v142, v224, v224
	v_mul_f32_e32 v143, v143, v143
	v_fmac_f32_e32 v143, v225, v225
	v_mul_f32_e32 v144, v144, v144
	v_fmac_f32_e32 v144, v226, v226
	v_mul_f32_e32 v145, v145, v145
	v_fmac_f32_e32 v145, v227, v227
	s_waitcnt lgkmcnt(0)
	ds_bpermute_b32 v212, v168, v130
	ds_bpermute_b32 v213, v168, v131
	ds_bpermute_b32 v214, v168, v132
	ds_bpermute_b32 v215, v168, v133
	ds_bpermute_b32 v216, v168, v134
	ds_bpermute_b32 v217, v168, v135
	ds_bpermute_b32 v218, v168, v136
	ds_bpermute_b32 v219, v168, v137
	s_waitcnt lgkmcnt(7)
	v_add_f32_e32 v130, v130, v212
	s_waitcnt lgkmcnt(6)
	v_add_f32_e32 v131, v131, v213
	s_waitcnt lgkmcnt(5)
	v_add_f32_e32 v132, v132, v214
	s_waitcnt lgkmcnt(4)
	v_add_f32_e32 v133, v133, v215
	s_waitcnt lgkmcnt(3)
	v_add_f32_e32 v134, v134, v216
	s_waitcnt lgkmcnt(2)
	v_add_f32_e32 v135, v135, v217
	s_waitcnt lgkmcnt(1)
	v_add_f32_e32 v136, v136, v218
	s_waitcnt lgkmcnt(0)
	v_add_f32_e32 v137, v137, v219
	ds_bpermute_b32 v212, v169, v130
	ds_bpermute_b32 v213, v169, v131
	ds_bpermute_b32 v214, v169, v132
	ds_bpermute_b32 v215, v169, v133
	ds_bpermute_b32 v216, v169, v134
	ds_bpermute_b32 v217, v169, v135
	ds_bpermute_b32 v218, v169, v136
	ds_bpermute_b32 v219, v169, v137
	s_waitcnt lgkmcnt(7)
	v_add_f32_e32 v130, v130, v212
	s_waitcnt lgkmcnt(6)
	v_add_f32_e32 v131, v131, v213
	s_waitcnt lgkmcnt(5)
	v_add_f32_e32 v132, v132, v214
	s_waitcnt lgkmcnt(4)
	v_add_f32_e32 v133, v133, v215
	s_waitcnt lgkmcnt(3)
	v_add_f32_e32 v134, v134, v216
	s_waitcnt lgkmcnt(2)
	v_add_f32_e32 v135, v135, v217
	s_waitcnt lgkmcnt(1)
	v_add_f32_e32 v136, v136, v218
	s_waitcnt lgkmcnt(0)
	v_add_f32_e32 v137, v137, v219
	ds_bpermute_b32 v212, v171, v130
	ds_bpermute_b32 v213, v171, v131
	ds_bpermute_b32 v214, v171, v132
	ds_bpermute_b32 v215, v171, v133
	ds_bpermute_b32 v216, v171, v134
	ds_bpermute_b32 v217, v171, v135
	ds_bpermute_b32 v218, v171, v136
	ds_bpermute_b32 v219, v171, v137
	s_waitcnt lgkmcnt(7)
	v_add_f32_e32 v130, v130, v212
	s_waitcnt lgkmcnt(6)
	v_add_f32_e32 v131, v131, v213
	s_waitcnt lgkmcnt(5)
	v_add_f32_e32 v132, v132, v214
	s_waitcnt lgkmcnt(4)
	v_add_f32_e32 v133, v133, v215
	s_waitcnt lgkmcnt(3)
	v_add_f32_e32 v134, v134, v216
	s_waitcnt lgkmcnt(2)
	v_add_f32_e32 v135, v135, v217
	s_waitcnt lgkmcnt(1)
	v_add_f32_e32 v136, v136, v218
	s_waitcnt lgkmcnt(0)
	v_add_f32_e32 v137, v137, v219
	ds_bpermute_b32 v212, v172, v130
	ds_bpermute_b32 v213, v172, v131
	ds_bpermute_b32 v214, v172, v132
	ds_bpermute_b32 v215, v172, v133
	ds_bpermute_b32 v216, v172, v134
	ds_bpermute_b32 v217, v172, v135
	ds_bpermute_b32 v218, v172, v136
	ds_bpermute_b32 v219, v172, v137
	s_waitcnt lgkmcnt(7)
	v_add_f32_e32 v130, v130, v212
	s_waitcnt lgkmcnt(6)
	v_add_f32_e32 v131, v131, v213
	s_waitcnt lgkmcnt(5)
	v_add_f32_e32 v132, v132, v214
	s_waitcnt lgkmcnt(4)
	v_add_f32_e32 v133, v133, v215
	s_waitcnt lgkmcnt(3)
	v_add_f32_e32 v134, v134, v216
	s_waitcnt lgkmcnt(2)
	v_add_f32_e32 v135, v135, v217
	s_waitcnt lgkmcnt(1)
	v_add_f32_e32 v136, v136, v218
	s_waitcnt lgkmcnt(0)
	v_add_f32_e32 v137, v137, v219
	ds_bpermute_b32 v212, v173, v130
	ds_bpermute_b32 v213, v173, v131
	ds_bpermute_b32 v214, v173, v132
	ds_bpermute_b32 v215, v173, v133
	ds_bpermute_b32 v216, v173, v134
	ds_bpermute_b32 v217, v173, v135
	ds_bpermute_b32 v218, v173, v136
	ds_bpermute_b32 v219, v173, v137
	s_waitcnt lgkmcnt(7)
	v_add_f32_e32 v130, v130, v212
	s_waitcnt lgkmcnt(6)
	v_add_f32_e32 v131, v131, v213
	s_waitcnt lgkmcnt(5)
	v_add_f32_e32 v132, v132, v214
	s_waitcnt lgkmcnt(4)
	v_add_f32_e32 v133, v133, v215
	s_waitcnt lgkmcnt(3)
	v_add_f32_e32 v134, v134, v216
	s_waitcnt lgkmcnt(2)
	v_add_f32_e32 v135, v135, v217
	s_waitcnt lgkmcnt(1)
	v_add_f32_e32 v136, v136, v218
	s_waitcnt lgkmcnt(0)
	v_add_f32_e32 v137, v137, v219
	ds_bpermute_b32 v220, v168, v138
	ds_bpermute_b32 v221, v168, v139
	ds_bpermute_b32 v222, v168, v140
	ds_bpermute_b32 v223, v168, v141
	ds_bpermute_b32 v224, v168, v142
	ds_bpermute_b32 v225, v168, v143
	ds_bpermute_b32 v226, v168, v144
	ds_bpermute_b32 v227, v168, v145
	s_waitcnt lgkmcnt(7)
	v_add_f32_e32 v138, v138, v220
	s_waitcnt lgkmcnt(6)
	v_add_f32_e32 v139, v139, v221
	s_waitcnt lgkmcnt(5)
	v_add_f32_e32 v140, v140, v222
	s_waitcnt lgkmcnt(4)
	v_add_f32_e32 v141, v141, v223
	s_waitcnt lgkmcnt(3)
	v_add_f32_e32 v142, v142, v224
	s_waitcnt lgkmcnt(2)
	v_add_f32_e32 v143, v143, v225
	s_waitcnt lgkmcnt(1)
	v_add_f32_e32 v144, v144, v226
	s_waitcnt lgkmcnt(0)
	v_add_f32_e32 v145, v145, v227
	ds_bpermute_b32 v220, v169, v138
	ds_bpermute_b32 v221, v169, v139
	ds_bpermute_b32 v222, v169, v140
	ds_bpermute_b32 v223, v169, v141
	ds_bpermute_b32 v224, v169, v142
	ds_bpermute_b32 v225, v169, v143
	ds_bpermute_b32 v226, v169, v144
	ds_bpermute_b32 v227, v169, v145
	s_waitcnt lgkmcnt(7)
	v_add_f32_e32 v138, v138, v220
	s_waitcnt lgkmcnt(6)
	v_add_f32_e32 v139, v139, v221
	s_waitcnt lgkmcnt(5)
	v_add_f32_e32 v140, v140, v222
	s_waitcnt lgkmcnt(4)
	v_add_f32_e32 v141, v141, v223
	s_waitcnt lgkmcnt(3)
	v_add_f32_e32 v142, v142, v224
	s_waitcnt lgkmcnt(2)
	v_add_f32_e32 v143, v143, v225
	s_waitcnt lgkmcnt(1)
	v_add_f32_e32 v144, v144, v226
	s_waitcnt lgkmcnt(0)
	v_add_f32_e32 v145, v145, v227
	ds_bpermute_b32 v220, v171, v138
	ds_bpermute_b32 v221, v171, v139
	ds_bpermute_b32 v222, v171, v140
	ds_bpermute_b32 v223, v171, v141
	ds_bpermute_b32 v224, v171, v142
	ds_bpermute_b32 v225, v171, v143
	ds_bpermute_b32 v226, v171, v144
	ds_bpermute_b32 v227, v171, v145
	s_waitcnt lgkmcnt(7)
	v_add_f32_e32 v138, v138, v220
	s_waitcnt lgkmcnt(6)
	v_add_f32_e32 v139, v139, v221
	s_waitcnt lgkmcnt(5)
	v_add_f32_e32 v140, v140, v222
	s_waitcnt lgkmcnt(4)
	v_add_f32_e32 v141, v141, v223
	s_waitcnt lgkmcnt(3)
	v_add_f32_e32 v142, v142, v224
	s_waitcnt lgkmcnt(2)
	v_add_f32_e32 v143, v143, v225
	s_waitcnt lgkmcnt(1)
	v_add_f32_e32 v144, v144, v226
	s_waitcnt lgkmcnt(0)
	v_add_f32_e32 v145, v145, v227
	ds_bpermute_b32 v220, v172, v138
	ds_bpermute_b32 v221, v172, v139
	ds_bpermute_b32 v222, v172, v140
	ds_bpermute_b32 v223, v172, v141
	ds_bpermute_b32 v224, v172, v142
	ds_bpermute_b32 v225, v172, v143
	ds_bpermute_b32 v226, v172, v144
	ds_bpermute_b32 v227, v172, v145
	s_waitcnt lgkmcnt(7)
	v_add_f32_e32 v138, v138, v220
	s_waitcnt lgkmcnt(6)
	v_add_f32_e32 v139, v139, v221
	s_waitcnt lgkmcnt(5)
	v_add_f32_e32 v140, v140, v222
	s_waitcnt lgkmcnt(4)
	v_add_f32_e32 v141, v141, v223
	s_waitcnt lgkmcnt(3)
	v_add_f32_e32 v142, v142, v224
	s_waitcnt lgkmcnt(2)
	v_add_f32_e32 v143, v143, v225
	s_waitcnt lgkmcnt(1)
	v_add_f32_e32 v144, v144, v226
	s_waitcnt lgkmcnt(0)
	v_add_f32_e32 v145, v145, v227
	ds_bpermute_b32 v220, v173, v138
	ds_bpermute_b32 v221, v173, v139
	ds_bpermute_b32 v222, v173, v140
	ds_bpermute_b32 v223, v173, v141
	ds_bpermute_b32 v224, v173, v142
	ds_bpermute_b32 v225, v173, v143
	ds_bpermute_b32 v226, v173, v144
	ds_bpermute_b32 v227, v173, v145
	s_waitcnt lgkmcnt(7)
	v_add_f32_e32 v138, v138, v220
	s_waitcnt lgkmcnt(6)
	v_add_f32_e32 v139, v139, v221
	s_waitcnt lgkmcnt(5)
	v_add_f32_e32 v140, v140, v222
	s_waitcnt lgkmcnt(4)
	v_add_f32_e32 v141, v141, v223
	s_waitcnt lgkmcnt(3)
	v_add_f32_e32 v142, v142, v224
	s_waitcnt lgkmcnt(2)
	v_add_f32_e32 v143, v143, v225
	s_waitcnt lgkmcnt(1)
	v_add_f32_e32 v144, v144, v226
	s_waitcnt lgkmcnt(0)
	v_add_f32_e32 v145, v145, v227
	v_cmp_eq_u32_e32 vcc, 0, v174
	s_and_saveexec_b64 s[58:59], vcc
	global_store_dword v167, v130, s[10:11]
	global_store_dword v167, v131, s[10:11] offset:4
	global_store_dword v167, v132, s[10:11] offset:8
	global_store_dword v167, v133, s[10:11] offset:12
	global_store_dword v167, v134, s[10:11] offset:32
	global_store_dword v167, v135, s[10:11] offset:36
	global_store_dword v167, v136, s[10:11] offset:40
	global_store_dword v167, v137, s[10:11] offset:44
	global_store_dword v167, v138, s[10:11] offset:64
	global_store_dword v167, v139, s[10:11] offset:68
	global_store_dword v167, v140, s[10:11] offset:72
	global_store_dword v167, v141, s[10:11] offset:76
	global_store_dword v167, v142, s[10:11] offset:96
	global_store_dword v167, v143, s[10:11] offset:100
	global_store_dword v167, v144, s[10:11] offset:104
	global_store_dword v167, v145, s[10:11] offset:108
	s_mov_b64 exec, -1
	s_add_u32 s48, s48, 0x20000
	s_addc_u32 s49, s49, 0
	global_load_dword v130, v162, s[48:49]
	global_load_dword v212, v162, s[48:49] offset:128
	global_load_dword v131, v163, s[48:49]
	global_load_dword v213, v163, s[48:49] offset:128
	global_load_dword v132, v164, s[48:49]
	global_load_dword v214, v164, s[48:49] offset:128
	global_load_dword v133, v165, s[48:49]
	global_load_dword v215, v165, s[48:49] offset:128
	s_add_u32 s48, s48, 0x8000
	s_addc_u32 s49, s49, 0
	global_load_dword v134, v162, s[48:49]
	global_load_dword v216, v162, s[48:49] offset:128
	global_load_dword v135, v163, s[48:49]
	global_load_dword v217, v163, s[48:49] offset:128
	global_load_dword v136, v164, s[48:49]
	global_load_dword v218, v164, s[48:49] offset:128
	global_load_dword v137, v165, s[48:49]
	global_load_dword v219, v165, s[48:49] offset:128
	s_add_u32 s48, s48, 0x8000
	s_addc_u32 s49, s49, 0
	global_load_dword v138, v162, s[48:49]
	global_load_dword v220, v162, s[48:49] offset:128
	global_load_dword v139, v163, s[48:49]
	global_load_dword v221, v163, s[48:49] offset:128
	global_load_dword v140, v164, s[48:49]
	global_load_dword v222, v164, s[48:49] offset:128
	global_load_dword v141, v165, s[48:49]
	global_load_dword v223, v165, s[48:49] offset:128
	s_add_u32 s48, s48, 0x8000
	s_addc_u32 s49, s49, 0
	global_load_dword v142, v162, s[48:49]
	global_load_dword v224, v162, s[48:49] offset:128
	global_load_dword v143, v163, s[48:49]
	global_load_dword v225, v163, s[48:49] offset:128
	global_load_dword v144, v164, s[48:49]
	global_load_dword v226, v164, s[48:49] offset:128
	global_load_dword v145, v165, s[48:49]
	global_load_dword v227, v165, s[48:49] offset:128
	s_sub_u32 s48, s48, 0x18000
	s_subb_u32 s49, s49, 0
	s_waitcnt vmcnt(30)
	v_fmac_f32_e32 v130, v34, v175
	v_fmac_f32_e32 v212, v50, v176
	global_store_dword v162, v130, s[48:49]
	global_store_dword v162, v212, s[48:49] offset:128
	s_waitcnt vmcnt(30)
	v_fmac_f32_e32 v131, v35, v175
	v_fmac_f32_e32 v213, v51, v176
	global_store_dword v163, v131, s[48:49]
	global_store_dword v163, v213, s[48:49] offset:128
	s_waitcnt vmcnt(30)
	v_fmac_f32_e32 v132, v36, v175
	v_fmac_f32_e32 v214, v52, v176
	global_store_dword v164, v132, s[48:49]
	global_store_dword v164, v214, s[48:49] offset:128
	s_waitcnt vmcnt(30)
	v_fmac_f32_e32 v133, v37, v175
	v_fmac_f32_e32 v215, v53, v176
	global_store_dword v165, v133, s[48:49]
	global_store_dword v165, v215, s[48:49] offset:128
	s_add_u32 s48, s48, 0x8000
	s_addc_u32 s49, s49, 0
	s_waitcnt vmcnt(30)
	v_fmac_f32_e32 v134, v38, v175
	v_fmac_f32_e32 v216, v54, v176
	global_store_dword v162, v134, s[48:49]
	global_store_dword v162, v216, s[48:49] offset:128
	s_waitcnt vmcnt(30)
	v_fmac_f32_e32 v135, v39, v175
	v_fmac_f32_e32 v217, v55, v176
	global_store_dword v163, v135, s[48:49]
	global_store_dword v163, v217, s[48:49] offset:128
	s_waitcnt vmcnt(30)
	v_fmac_f32_e32 v136, v40, v175
	v_fmac_f32_e32 v218, v56, v176
	global_store_dword v164, v136, s[48:49]
	global_store_dword v164, v218, s[48:49] offset:128
	s_waitcnt vmcnt(30)
	v_fmac_f32_e32 v137, v41, v175
	v_fmac_f32_e32 v219, v57, v176
	global_store_dword v165, v137, s[48:49]
	global_store_dword v165, v219, s[48:49] offset:128
	s_add_u32 s48, s48, 0x8000
	s_addc_u32 s49, s49, 0
	s_waitcnt vmcnt(30)
	v_fmac_f32_e32 v138, v42, v175
	v_fmac_f32_e32 v220, v58, v176
	global_store_dword v162, v138, s[48:49]
	global_store_dword v162, v220, s[48:49] offset:128
	s_waitcnt vmcnt(30)
	v_fmac_f32_e32 v139, v43, v175
	v_fmac_f32_e32 v221, v59, v176
	global_store_dword v163, v139, s[48:49]
	global_store_dword v163, v221, s[48:49] offset:128
	s_waitcnt vmcnt(30)
	v_fmac_f32_e32 v140, v44, v175
	v_fmac_f32_e32 v222, v60, v176
	global_store_dword v164, v140, s[48:49]
	global_store_dword v164, v222, s[48:49] offset:128
	s_waitcnt vmcnt(30)
	v_fmac_f32_e32 v141, v45, v175
	v_fmac_f32_e32 v223, v61, v176
	global_store_dword v165, v141, s[48:49]
	global_store_dword v165, v223, s[48:49] offset:128
	s_add_u32 s48, s48, 0x8000
	s_addc_u32 s49, s49, 0
	s_waitcnt vmcnt(30)
	v_fmac_f32_e32 v142, v46, v175
	v_fmac_f32_e32 v224, v62, v176
	global_store_dword v162, v142, s[48:49]
	global_store_dword v162, v224, s[48:49] offset:128
	s_waitcnt vmcnt(30)
	v_fmac_f32_e32 v143, v47, v175
	v_fmac_f32_e32 v225, v63, v176
	global_store_dword v163, v143, s[48:49]
	global_store_dword v163, v225, s[48:49] offset:128
	s_waitcnt vmcnt(30)
	v_fmac_f32_e32 v144, v48, v175
	v_fmac_f32_e32 v226, v64, v176
	global_store_dword v164, v144, s[48:49]
	global_store_dword v164, v226, s[48:49] offset:128
	s_waitcnt vmcnt(30)
	v_fmac_f32_e32 v145, v49, v175
	v_fmac_f32_e32 v227, v65, v176
	global_store_dword v165, v145, s[48:49]
	global_store_dword v165, v227, s[48:49] offset:128
	s_sub_u32 s48, s48, 0x18000
	s_subb_u32 s49, s49, 0
	v_mul_f32_e32 v130, v130, v130
	v_fmac_f32_e32 v130, v212, v212
	v_mul_f32_e32 v131, v131, v131
	v_fmac_f32_e32 v131, v213, v213
	v_mul_f32_e32 v132, v132, v132
	v_fmac_f32_e32 v132, v214, v214
	v_mul_f32_e32 v133, v133, v133
	v_fmac_f32_e32 v133, v215, v215
	v_mul_f32_e32 v134, v134, v134
	v_fmac_f32_e32 v134, v216, v216
	v_mul_f32_e32 v135, v135, v135
	v_fmac_f32_e32 v135, v217, v217
	v_mul_f32_e32 v136, v136, v136
	v_fmac_f32_e32 v136, v218, v218
	v_mul_f32_e32 v137, v137, v137
	v_fmac_f32_e32 v137, v219, v219
	v_mul_f32_e32 v138, v138, v138
	v_fmac_f32_e32 v138, v220, v220
	v_mul_f32_e32 v139, v139, v139
	v_fmac_f32_e32 v139, v221, v221
	v_mul_f32_e32 v140, v140, v140
	v_fmac_f32_e32 v140, v222, v222
	v_mul_f32_e32 v141, v141, v141
	v_fmac_f32_e32 v141, v223, v223
	v_mul_f32_e32 v142, v142, v142
	v_fmac_f32_e32 v142, v224, v224
	v_mul_f32_e32 v143, v143, v143
	v_fmac_f32_e32 v143, v225, v225
	v_mul_f32_e32 v144, v144, v144
	v_fmac_f32_e32 v144, v226, v226
	v_mul_f32_e32 v145, v145, v145
	v_fmac_f32_e32 v145, v227, v227
	s_waitcnt lgkmcnt(0)
	ds_bpermute_b32 v212, v168, v130
	ds_bpermute_b32 v213, v168, v131
	ds_bpermute_b32 v214, v168, v132
	ds_bpermute_b32 v215, v168, v133
	ds_bpermute_b32 v216, v168, v134
	ds_bpermute_b32 v217, v168, v135
	ds_bpermute_b32 v218, v168, v136
	ds_bpermute_b32 v219, v168, v137
	s_waitcnt lgkmcnt(7)
	v_add_f32_e32 v130, v130, v212
	s_waitcnt lgkmcnt(6)
	v_add_f32_e32 v131, v131, v213
	s_waitcnt lgkmcnt(5)
	v_add_f32_e32 v132, v132, v214
	s_waitcnt lgkmcnt(4)
	v_add_f32_e32 v133, v133, v215
	s_waitcnt lgkmcnt(3)
	v_add_f32_e32 v134, v134, v216
	s_waitcnt lgkmcnt(2)
	v_add_f32_e32 v135, v135, v217
	s_waitcnt lgkmcnt(1)
	v_add_f32_e32 v136, v136, v218
	s_waitcnt lgkmcnt(0)
	v_add_f32_e32 v137, v137, v219
	ds_bpermute_b32 v212, v169, v130
	ds_bpermute_b32 v213, v169, v131
	ds_bpermute_b32 v214, v169, v132
	ds_bpermute_b32 v215, v169, v133
	ds_bpermute_b32 v216, v169, v134
	ds_bpermute_b32 v217, v169, v135
	ds_bpermute_b32 v218, v169, v136
	ds_bpermute_b32 v219, v169, v137
	s_waitcnt lgkmcnt(7)
	v_add_f32_e32 v130, v130, v212
	s_waitcnt lgkmcnt(6)
	v_add_f32_e32 v131, v131, v213
	s_waitcnt lgkmcnt(5)
	v_add_f32_e32 v132, v132, v214
	s_waitcnt lgkmcnt(4)
	v_add_f32_e32 v133, v133, v215
	s_waitcnt lgkmcnt(3)
	v_add_f32_e32 v134, v134, v216
	s_waitcnt lgkmcnt(2)
	v_add_f32_e32 v135, v135, v217
	s_waitcnt lgkmcnt(1)
	v_add_f32_e32 v136, v136, v218
	s_waitcnt lgkmcnt(0)
	v_add_f32_e32 v137, v137, v219
	ds_bpermute_b32 v212, v171, v130
	ds_bpermute_b32 v213, v171, v131
	ds_bpermute_b32 v214, v171, v132
	ds_bpermute_b32 v215, v171, v133
	ds_bpermute_b32 v216, v171, v134
	ds_bpermute_b32 v217, v171, v135
	ds_bpermute_b32 v218, v171, v136
	ds_bpermute_b32 v219, v171, v137
	s_waitcnt lgkmcnt(7)
	v_add_f32_e32 v130, v130, v212
	s_waitcnt lgkmcnt(6)
	v_add_f32_e32 v131, v131, v213
	s_waitcnt lgkmcnt(5)
	v_add_f32_e32 v132, v132, v214
	s_waitcnt lgkmcnt(4)
	v_add_f32_e32 v133, v133, v215
	s_waitcnt lgkmcnt(3)
	v_add_f32_e32 v134, v134, v216
	s_waitcnt lgkmcnt(2)
	v_add_f32_e32 v135, v135, v217
	s_waitcnt lgkmcnt(1)
	v_add_f32_e32 v136, v136, v218
	s_waitcnt lgkmcnt(0)
	v_add_f32_e32 v137, v137, v219
	ds_bpermute_b32 v212, v172, v130
	ds_bpermute_b32 v213, v172, v131
	ds_bpermute_b32 v214, v172, v132
	ds_bpermute_b32 v215, v172, v133
	ds_bpermute_b32 v216, v172, v134
	ds_bpermute_b32 v217, v172, v135
	ds_bpermute_b32 v218, v172, v136
	ds_bpermute_b32 v219, v172, v137
	s_waitcnt lgkmcnt(7)
	v_add_f32_e32 v130, v130, v212
	s_waitcnt lgkmcnt(6)
	v_add_f32_e32 v131, v131, v213
	s_waitcnt lgkmcnt(5)
	v_add_f32_e32 v132, v132, v214
	s_waitcnt lgkmcnt(4)
	v_add_f32_e32 v133, v133, v215
	s_waitcnt lgkmcnt(3)
	v_add_f32_e32 v134, v134, v216
	s_waitcnt lgkmcnt(2)
	v_add_f32_e32 v135, v135, v217
	s_waitcnt lgkmcnt(1)
	v_add_f32_e32 v136, v136, v218
	s_waitcnt lgkmcnt(0)
	v_add_f32_e32 v137, v137, v219
	ds_bpermute_b32 v212, v173, v130
	ds_bpermute_b32 v213, v173, v131
	ds_bpermute_b32 v214, v173, v132
	ds_bpermute_b32 v215, v173, v133
	ds_bpermute_b32 v216, v173, v134
	ds_bpermute_b32 v217, v173, v135
	ds_bpermute_b32 v218, v173, v136
	ds_bpermute_b32 v219, v173, v137
	s_waitcnt lgkmcnt(7)
	v_add_f32_e32 v130, v130, v212
	s_waitcnt lgkmcnt(6)
	v_add_f32_e32 v131, v131, v213
	s_waitcnt lgkmcnt(5)
	v_add_f32_e32 v132, v132, v214
	s_waitcnt lgkmcnt(4)
	v_add_f32_e32 v133, v133, v215
	s_waitcnt lgkmcnt(3)
	v_add_f32_e32 v134, v134, v216
	s_waitcnt lgkmcnt(2)
	v_add_f32_e32 v135, v135, v217
	s_waitcnt lgkmcnt(1)
	v_add_f32_e32 v136, v136, v218
	s_waitcnt lgkmcnt(0)
	v_add_f32_e32 v137, v137, v219
	ds_bpermute_b32 v220, v168, v138
	ds_bpermute_b32 v221, v168, v139
	ds_bpermute_b32 v222, v168, v140
	ds_bpermute_b32 v223, v168, v141
	ds_bpermute_b32 v224, v168, v142
	ds_bpermute_b32 v225, v168, v143
	ds_bpermute_b32 v226, v168, v144
	ds_bpermute_b32 v227, v168, v145
	s_waitcnt lgkmcnt(7)
	v_add_f32_e32 v138, v138, v220
	s_waitcnt lgkmcnt(6)
	v_add_f32_e32 v139, v139, v221
	s_waitcnt lgkmcnt(5)
	v_add_f32_e32 v140, v140, v222
	s_waitcnt lgkmcnt(4)
	v_add_f32_e32 v141, v141, v223
	s_waitcnt lgkmcnt(3)
	v_add_f32_e32 v142, v142, v224
	s_waitcnt lgkmcnt(2)
	v_add_f32_e32 v143, v143, v225
	s_waitcnt lgkmcnt(1)
	v_add_f32_e32 v144, v144, v226
	s_waitcnt lgkmcnt(0)
	v_add_f32_e32 v145, v145, v227
	ds_bpermute_b32 v220, v169, v138
	ds_bpermute_b32 v221, v169, v139
	ds_bpermute_b32 v222, v169, v140
	ds_bpermute_b32 v223, v169, v141
	ds_bpermute_b32 v224, v169, v142
	ds_bpermute_b32 v225, v169, v143
	ds_bpermute_b32 v226, v169, v144
	ds_bpermute_b32 v227, v169, v145
	s_waitcnt lgkmcnt(7)
	v_add_f32_e32 v138, v138, v220
	s_waitcnt lgkmcnt(6)
	v_add_f32_e32 v139, v139, v221
	s_waitcnt lgkmcnt(5)
	v_add_f32_e32 v140, v140, v222
	s_waitcnt lgkmcnt(4)
	v_add_f32_e32 v141, v141, v223
	s_waitcnt lgkmcnt(3)
	v_add_f32_e32 v142, v142, v224
	s_waitcnt lgkmcnt(2)
	v_add_f32_e32 v143, v143, v225
	s_waitcnt lgkmcnt(1)
	v_add_f32_e32 v144, v144, v226
	s_waitcnt lgkmcnt(0)
	v_add_f32_e32 v145, v145, v227
	ds_bpermute_b32 v220, v171, v138
	ds_bpermute_b32 v221, v171, v139
	ds_bpermute_b32 v222, v171, v140
	ds_bpermute_b32 v223, v171, v141
	ds_bpermute_b32 v224, v171, v142
	ds_bpermute_b32 v225, v171, v143
	ds_bpermute_b32 v226, v171, v144
	ds_bpermute_b32 v227, v171, v145
	s_waitcnt lgkmcnt(7)
	v_add_f32_e32 v138, v138, v220
	s_waitcnt lgkmcnt(6)
	v_add_f32_e32 v139, v139, v221
	s_waitcnt lgkmcnt(5)
	v_add_f32_e32 v140, v140, v222
	s_waitcnt lgkmcnt(4)
	v_add_f32_e32 v141, v141, v223
	s_waitcnt lgkmcnt(3)
	v_add_f32_e32 v142, v142, v224
	s_waitcnt lgkmcnt(2)
	v_add_f32_e32 v143, v143, v225
	s_waitcnt lgkmcnt(1)
	v_add_f32_e32 v144, v144, v226
	s_waitcnt lgkmcnt(0)
	v_add_f32_e32 v145, v145, v227
	ds_bpermute_b32 v220, v172, v138
	ds_bpermute_b32 v221, v172, v139
	ds_bpermute_b32 v222, v172, v140
	ds_bpermute_b32 v223, v172, v141
	ds_bpermute_b32 v224, v172, v142
	ds_bpermute_b32 v225, v172, v143
	ds_bpermute_b32 v226, v172, v144
	ds_bpermute_b32 v227, v172, v145
	s_waitcnt lgkmcnt(7)
	v_add_f32_e32 v138, v138, v220
	s_waitcnt lgkmcnt(6)
	v_add_f32_e32 v139, v139, v221
	s_waitcnt lgkmcnt(5)
	v_add_f32_e32 v140, v140, v222
	s_waitcnt lgkmcnt(4)
	v_add_f32_e32 v141, v141, v223
	s_waitcnt lgkmcnt(3)
	v_add_f32_e32 v142, v142, v224
	s_waitcnt lgkmcnt(2)
	v_add_f32_e32 v143, v143, v225
	s_waitcnt lgkmcnt(1)
	v_add_f32_e32 v144, v144, v226
	s_waitcnt lgkmcnt(0)
	v_add_f32_e32 v145, v145, v227
	ds_bpermute_b32 v220, v173, v138
	ds_bpermute_b32 v221, v173, v139
	ds_bpermute_b32 v222, v173, v140
	ds_bpermute_b32 v223, v173, v141
	ds_bpermute_b32 v224, v173, v142
	ds_bpermute_b32 v225, v173, v143
	ds_bpermute_b32 v226, v173, v144
	ds_bpermute_b32 v227, v173, v145
	s_waitcnt lgkmcnt(7)
	v_add_f32_e32 v138, v138, v220
	s_waitcnt lgkmcnt(6)
	v_add_f32_e32 v139, v139, v221
	s_waitcnt lgkmcnt(5)
	v_add_f32_e32 v140, v140, v222
	s_waitcnt lgkmcnt(4)
	v_add_f32_e32 v141, v141, v223
	s_waitcnt lgkmcnt(3)
	v_add_f32_e32 v142, v142, v224
	s_waitcnt lgkmcnt(2)
	v_add_f32_e32 v143, v143, v225
	s_waitcnt lgkmcnt(1)
	v_add_f32_e32 v144, v144, v226
	s_waitcnt lgkmcnt(0)
	v_add_f32_e32 v145, v145, v227
	v_cmp_eq_u32_e32 vcc, 0, v174
	s_and_saveexec_b64 s[58:59], vcc
	global_store_dword v167, v130, s[10:11] offset:128
	global_store_dword v167, v131, s[10:11] offset:132
	global_store_dword v167, v132, s[10:11] offset:136
	global_store_dword v167, v133, s[10:11] offset:140
	global_store_dword v167, v134, s[10:11] offset:160
	global_store_dword v167, v135, s[10:11] offset:164
	global_store_dword v167, v136, s[10:11] offset:168
	global_store_dword v167, v137, s[10:11] offset:172
	global_store_dword v167, v138, s[10:11] offset:192
	global_store_dword v167, v139, s[10:11] offset:196
	global_store_dword v167, v140, s[10:11] offset:200
	global_store_dword v167, v141, s[10:11] offset:204
	global_store_dword v167, v142, s[10:11] offset:224
	global_store_dword v167, v143, s[10:11] offset:228
	global_store_dword v167, v144, s[10:11] offset:232
	global_store_dword v167, v145, s[10:11] offset:236
	s_mov_b64 exec, -1
	s_sub_u32 s48, s48, 0x20000
	s_subb_u32 s49, s49, 0
	s_add_u32 s60, s60, 0x200
	s_addc_u32 s61, s61, 0
	s_add_u32 s10, s10, 0x18000
	s_addc_u32 s11, s11, 0
	s_add_u32 s48, s48, 0x200
	s_addc_u32 s49, s49, 0
	global_load_dword v175, v166, s[60:61]
	global_load_dword v176, v166, s[60:61] offset:128
	global_load_dword v130, v162, s[48:49]
	global_load_dword v212, v162, s[48:49] offset:128
	global_load_dword v131, v163, s[48:49]
	global_load_dword v213, v163, s[48:49] offset:128
	global_load_dword v132, v164, s[48:49]
	global_load_dword v214, v164, s[48:49] offset:128
	global_load_dword v133, v165, s[48:49]
	global_load_dword v215, v165, s[48:49] offset:128
	s_add_u32 s48, s48, 0x8000
	s_addc_u32 s49, s49, 0
	global_load_dword v134, v162, s[48:49]
	global_load_dword v216, v162, s[48:49] offset:128
	global_load_dword v135, v163, s[48:49]
	global_load_dword v217, v163, s[48:49] offset:128
	global_load_dword v136, v164, s[48:49]
	global_load_dword v218, v164, s[48:49] offset:128
	global_load_dword v137, v165, s[48:49]
	global_load_dword v219, v165, s[48:49] offset:128
	s_add_u32 s48, s48, 0x8000
	s_addc_u32 s49, s49, 0
	global_load_dword v138, v162, s[48:49]
	global_load_dword v220, v162, s[48:49] offset:128
	global_load_dword v139, v163, s[48:49]
	global_load_dword v221, v163, s[48:49] offset:128
	global_load_dword v140, v164, s[48:49]
	global_load_dword v222, v164, s[48:49] offset:128
	global_load_dword v141, v165, s[48:49]
	global_load_dword v223, v165, s[48:49] offset:128
	s_add_u32 s48, s48, 0x8000
	s_addc_u32 s49, s49, 0
	global_load_dword v142, v162, s[48:49]
	global_load_dword v224, v162, s[48:49] offset:128
	global_load_dword v143, v163, s[48:49]
	global_load_dword v225, v163, s[48:49] offset:128
	global_load_dword v144, v164, s[48:49]
	global_load_dword v226, v164, s[48:49] offset:128
	global_load_dword v145, v165, s[48:49]
	global_load_dword v227, v165, s[48:49] offset:128
	s_sub_u32 s48, s48, 0x18000
	s_subb_u32 s49, s49, 0
	s_waitcnt vmcnt(32)
	v_mul_f32_e32 v175, 0.5, v175
	v_mul_f32_e32 v176, 0.5, v176
	s_waitcnt vmcnt(30)
	v_fmac_f32_e32 v130, v66, v175
	v_fmac_f32_e32 v212, v82, v176
	global_store_dword v162, v130, s[48:49]
	global_store_dword v162, v212, s[48:49] offset:128
	s_waitcnt vmcnt(30)
	v_fmac_f32_e32 v131, v67, v175
	v_fmac_f32_e32 v213, v83, v176
	global_store_dword v163, v131, s[48:49]
	global_store_dword v163, v213, s[48:49] offset:128
	s_waitcnt vmcnt(30)
	v_fmac_f32_e32 v132, v68, v175
	v_fmac_f32_e32 v214, v84, v176
	global_store_dword v164, v132, s[48:49]
	global_store_dword v164, v214, s[48:49] offset:128
	s_waitcnt vmcnt(30)
	v_fmac_f32_e32 v133, v69, v175
	v_fmac_f32_e32 v215, v85, v176
	global_store_dword v165, v133, s[48:49]
	global_store_dword v165, v215, s[48:49] offset:128
	s_add_u32 s48, s48, 0x8000
	s_addc_u32 s49, s49, 0
	s_waitcnt vmcnt(30)
	v_fmac_f32_e32 v134, v70, v175
	v_fmac_f32_e32 v216, v86, v176
	global_store_dword v162, v134, s[48:49]
	global_store_dword v162, v216, s[48:49] offset:128
	s_waitcnt vmcnt(30)
	v_fmac_f32_e32 v135, v71, v175
	v_fmac_f32_e32 v217, v87, v176
	global_store_dword v163, v135, s[48:49]
	global_store_dword v163, v217, s[48:49] offset:128
	s_waitcnt vmcnt(30)
	v_fmac_f32_e32 v136, v72, v175
	v_fmac_f32_e32 v218, v88, v176
	global_store_dword v164, v136, s[48:49]
	global_store_dword v164, v218, s[48:49] offset:128
	s_waitcnt vmcnt(30)
	v_fmac_f32_e32 v137, v73, v175
	v_fmac_f32_e32 v219, v89, v176
	global_store_dword v165, v137, s[48:49]
	global_store_dword v165, v219, s[48:49] offset:128
	s_add_u32 s48, s48, 0x8000
	s_addc_u32 s49, s49, 0
	s_waitcnt vmcnt(30)
	v_fmac_f32_e32 v138, v74, v175
	v_fmac_f32_e32 v220, v90, v176
	global_store_dword v162, v138, s[48:49]
	global_store_dword v162, v220, s[48:49] offset:128
	s_waitcnt vmcnt(30)
	v_fmac_f32_e32 v139, v75, v175
	v_fmac_f32_e32 v221, v91, v176
	global_store_dword v163, v139, s[48:49]
	global_store_dword v163, v221, s[48:49] offset:128
	s_waitcnt vmcnt(30)
	v_fmac_f32_e32 v140, v76, v175
	v_fmac_f32_e32 v222, v92, v176
	global_store_dword v164, v140, s[48:49]
	global_store_dword v164, v222, s[48:49] offset:128
	s_waitcnt vmcnt(30)
	v_fmac_f32_e32 v141, v77, v175
	v_fmac_f32_e32 v223, v93, v176
	global_store_dword v165, v141, s[48:49]
	global_store_dword v165, v223, s[48:49] offset:128
	s_add_u32 s48, s48, 0x8000
	s_addc_u32 s49, s49, 0
	s_waitcnt vmcnt(30)
	v_fmac_f32_e32 v142, v78, v175
	v_fmac_f32_e32 v224, v94, v176
	global_store_dword v162, v142, s[48:49]
	global_store_dword v162, v224, s[48:49] offset:128
	s_waitcnt vmcnt(30)
	v_fmac_f32_e32 v143, v79, v175
	v_fmac_f32_e32 v225, v95, v176
	global_store_dword v163, v143, s[48:49]
	global_store_dword v163, v225, s[48:49] offset:128
	s_waitcnt vmcnt(30)
	v_fmac_f32_e32 v144, v80, v175
	v_fmac_f32_e32 v226, v96, v176
	global_store_dword v164, v144, s[48:49]
	global_store_dword v164, v226, s[48:49] offset:128
	s_waitcnt vmcnt(30)
	v_fmac_f32_e32 v145, v81, v175
	v_fmac_f32_e32 v227, v97, v176
	global_store_dword v165, v145, s[48:49]
	global_store_dword v165, v227, s[48:49] offset:128
	s_sub_u32 s48, s48, 0x18000
	s_subb_u32 s49, s49, 0
	v_mul_f32_e32 v130, v130, v130
	v_fmac_f32_e32 v130, v212, v212
	v_mul_f32_e32 v131, v131, v131
	v_fmac_f32_e32 v131, v213, v213
	v_mul_f32_e32 v132, v132, v132
	v_fmac_f32_e32 v132, v214, v214
	v_mul_f32_e32 v133, v133, v133
	v_fmac_f32_e32 v133, v215, v215
	v_mul_f32_e32 v134, v134, v134
	v_fmac_f32_e32 v134, v216, v216
	v_mul_f32_e32 v135, v135, v135
	v_fmac_f32_e32 v135, v217, v217
	v_mul_f32_e32 v136, v136, v136
	v_fmac_f32_e32 v136, v218, v218
	v_mul_f32_e32 v137, v137, v137
	v_fmac_f32_e32 v137, v219, v219
	v_mul_f32_e32 v138, v138, v138
	v_fmac_f32_e32 v138, v220, v220
	v_mul_f32_e32 v139, v139, v139
	v_fmac_f32_e32 v139, v221, v221
	v_mul_f32_e32 v140, v140, v140
	v_fmac_f32_e32 v140, v222, v222
	v_mul_f32_e32 v141, v141, v141
	v_fmac_f32_e32 v141, v223, v223
	v_mul_f32_e32 v142, v142, v142
	v_fmac_f32_e32 v142, v224, v224
	v_mul_f32_e32 v143, v143, v143
	v_fmac_f32_e32 v143, v225, v225
	v_mul_f32_e32 v144, v144, v144
	v_fmac_f32_e32 v144, v226, v226
	v_mul_f32_e32 v145, v145, v145
	v_fmac_f32_e32 v145, v227, v227
	s_waitcnt lgkmcnt(0)
	ds_bpermute_b32 v212, v168, v130
	ds_bpermute_b32 v213, v168, v131
	ds_bpermute_b32 v214, v168, v132
	ds_bpermute_b32 v215, v168, v133
	ds_bpermute_b32 v216, v168, v134
	ds_bpermute_b32 v217, v168, v135
	ds_bpermute_b32 v218, v168, v136
	ds_bpermute_b32 v219, v168, v137
	s_waitcnt lgkmcnt(7)
	v_add_f32_e32 v130, v130, v212
	s_waitcnt lgkmcnt(6)
	v_add_f32_e32 v131, v131, v213
	s_waitcnt lgkmcnt(5)
	v_add_f32_e32 v132, v132, v214
	s_waitcnt lgkmcnt(4)
	v_add_f32_e32 v133, v133, v215
	s_waitcnt lgkmcnt(3)
	v_add_f32_e32 v134, v134, v216
	s_waitcnt lgkmcnt(2)
	v_add_f32_e32 v135, v135, v217
	s_waitcnt lgkmcnt(1)
	v_add_f32_e32 v136, v136, v218
	s_waitcnt lgkmcnt(0)
	v_add_f32_e32 v137, v137, v219
	ds_bpermute_b32 v212, v169, v130
	ds_bpermute_b32 v213, v169, v131
	ds_bpermute_b32 v214, v169, v132
	ds_bpermute_b32 v215, v169, v133
	ds_bpermute_b32 v216, v169, v134
	ds_bpermute_b32 v217, v169, v135
	ds_bpermute_b32 v218, v169, v136
	ds_bpermute_b32 v219, v169, v137
	s_waitcnt lgkmcnt(7)
	v_add_f32_e32 v130, v130, v212
	s_waitcnt lgkmcnt(6)
	v_add_f32_e32 v131, v131, v213
	s_waitcnt lgkmcnt(5)
	v_add_f32_e32 v132, v132, v214
	s_waitcnt lgkmcnt(4)
	v_add_f32_e32 v133, v133, v215
	s_waitcnt lgkmcnt(3)
	v_add_f32_e32 v134, v134, v216
	s_waitcnt lgkmcnt(2)
	v_add_f32_e32 v135, v135, v217
	s_waitcnt lgkmcnt(1)
	v_add_f32_e32 v136, v136, v218
	s_waitcnt lgkmcnt(0)
	v_add_f32_e32 v137, v137, v219
	ds_bpermute_b32 v212, v171, v130
	ds_bpermute_b32 v213, v171, v131
	ds_bpermute_b32 v214, v171, v132
	ds_bpermute_b32 v215, v171, v133
	ds_bpermute_b32 v216, v171, v134
	ds_bpermute_b32 v217, v171, v135
	ds_bpermute_b32 v218, v171, v136
	ds_bpermute_b32 v219, v171, v137
	s_waitcnt lgkmcnt(7)
	v_add_f32_e32 v130, v130, v212
	s_waitcnt lgkmcnt(6)
	v_add_f32_e32 v131, v131, v213
	s_waitcnt lgkmcnt(5)
	v_add_f32_e32 v132, v132, v214
	s_waitcnt lgkmcnt(4)
	v_add_f32_e32 v133, v133, v215
	s_waitcnt lgkmcnt(3)
	v_add_f32_e32 v134, v134, v216
	s_waitcnt lgkmcnt(2)
	v_add_f32_e32 v135, v135, v217
	s_waitcnt lgkmcnt(1)
	v_add_f32_e32 v136, v136, v218
	s_waitcnt lgkmcnt(0)
	v_add_f32_e32 v137, v137, v219
	ds_bpermute_b32 v212, v172, v130
	ds_bpermute_b32 v213, v172, v131
	ds_bpermute_b32 v214, v172, v132
	ds_bpermute_b32 v215, v172, v133
	ds_bpermute_b32 v216, v172, v134
	ds_bpermute_b32 v217, v172, v135
	ds_bpermute_b32 v218, v172, v136
	ds_bpermute_b32 v219, v172, v137
	s_waitcnt lgkmcnt(7)
	v_add_f32_e32 v130, v130, v212
	s_waitcnt lgkmcnt(6)
	v_add_f32_e32 v131, v131, v213
	s_waitcnt lgkmcnt(5)
	v_add_f32_e32 v132, v132, v214
	s_waitcnt lgkmcnt(4)
	v_add_f32_e32 v133, v133, v215
	s_waitcnt lgkmcnt(3)
	v_add_f32_e32 v134, v134, v216
	s_waitcnt lgkmcnt(2)
	v_add_f32_e32 v135, v135, v217
	s_waitcnt lgkmcnt(1)
	v_add_f32_e32 v136, v136, v218
	s_waitcnt lgkmcnt(0)
	v_add_f32_e32 v137, v137, v219
	ds_bpermute_b32 v212, v173, v130
	ds_bpermute_b32 v213, v173, v131
	ds_bpermute_b32 v214, v173, v132
	ds_bpermute_b32 v215, v173, v133
	ds_bpermute_b32 v216, v173, v134
	ds_bpermute_b32 v217, v173, v135
	ds_bpermute_b32 v218, v173, v136
	ds_bpermute_b32 v219, v173, v137
	s_waitcnt lgkmcnt(7)
	v_add_f32_e32 v130, v130, v212
	s_waitcnt lgkmcnt(6)
	v_add_f32_e32 v131, v131, v213
	s_waitcnt lgkmcnt(5)
	v_add_f32_e32 v132, v132, v214
	s_waitcnt lgkmcnt(4)
	v_add_f32_e32 v133, v133, v215
	s_waitcnt lgkmcnt(3)
	v_add_f32_e32 v134, v134, v216
	s_waitcnt lgkmcnt(2)
	v_add_f32_e32 v135, v135, v217
	s_waitcnt lgkmcnt(1)
	v_add_f32_e32 v136, v136, v218
	s_waitcnt lgkmcnt(0)
	v_add_f32_e32 v137, v137, v219
	ds_bpermute_b32 v220, v168, v138
	ds_bpermute_b32 v221, v168, v139
	ds_bpermute_b32 v222, v168, v140
	ds_bpermute_b32 v223, v168, v141
	ds_bpermute_b32 v224, v168, v142
	ds_bpermute_b32 v225, v168, v143
	ds_bpermute_b32 v226, v168, v144
	ds_bpermute_b32 v227, v168, v145
	s_waitcnt lgkmcnt(7)
	v_add_f32_e32 v138, v138, v220
	s_waitcnt lgkmcnt(6)
	v_add_f32_e32 v139, v139, v221
	s_waitcnt lgkmcnt(5)
	v_add_f32_e32 v140, v140, v222
	s_waitcnt lgkmcnt(4)
	v_add_f32_e32 v141, v141, v223
	s_waitcnt lgkmcnt(3)
	v_add_f32_e32 v142, v142, v224
	s_waitcnt lgkmcnt(2)
	v_add_f32_e32 v143, v143, v225
	s_waitcnt lgkmcnt(1)
	v_add_f32_e32 v144, v144, v226
	s_waitcnt lgkmcnt(0)
	v_add_f32_e32 v145, v145, v227
	ds_bpermute_b32 v220, v169, v138
	ds_bpermute_b32 v221, v169, v139
	ds_bpermute_b32 v222, v169, v140
	ds_bpermute_b32 v223, v169, v141
	ds_bpermute_b32 v224, v169, v142
	ds_bpermute_b32 v225, v169, v143
	ds_bpermute_b32 v226, v169, v144
	ds_bpermute_b32 v227, v169, v145
	s_waitcnt lgkmcnt(7)
	v_add_f32_e32 v138, v138, v220
	s_waitcnt lgkmcnt(6)
	v_add_f32_e32 v139, v139, v221
	s_waitcnt lgkmcnt(5)
	v_add_f32_e32 v140, v140, v222
	s_waitcnt lgkmcnt(4)
	v_add_f32_e32 v141, v141, v223
	s_waitcnt lgkmcnt(3)
	v_add_f32_e32 v142, v142, v224
	s_waitcnt lgkmcnt(2)
	v_add_f32_e32 v143, v143, v225
	s_waitcnt lgkmcnt(1)
	v_add_f32_e32 v144, v144, v226
	s_waitcnt lgkmcnt(0)
	v_add_f32_e32 v145, v145, v227
	ds_bpermute_b32 v220, v171, v138
	ds_bpermute_b32 v221, v171, v139
	ds_bpermute_b32 v222, v171, v140
	ds_bpermute_b32 v223, v171, v141
	ds_bpermute_b32 v224, v171, v142
	ds_bpermute_b32 v225, v171, v143
	ds_bpermute_b32 v226, v171, v144
	ds_bpermute_b32 v227, v171, v145
	s_waitcnt lgkmcnt(7)
	v_add_f32_e32 v138, v138, v220
	s_waitcnt lgkmcnt(6)
	v_add_f32_e32 v139, v139, v221
	s_waitcnt lgkmcnt(5)
	v_add_f32_e32 v140, v140, v222
	s_waitcnt lgkmcnt(4)
	v_add_f32_e32 v141, v141, v223
	s_waitcnt lgkmcnt(3)
	v_add_f32_e32 v142, v142, v224
	s_waitcnt lgkmcnt(2)
	v_add_f32_e32 v143, v143, v225
	s_waitcnt lgkmcnt(1)
	v_add_f32_e32 v144, v144, v226
	s_waitcnt lgkmcnt(0)
	v_add_f32_e32 v145, v145, v227
	ds_bpermute_b32 v220, v172, v138
	ds_bpermute_b32 v221, v172, v139
	ds_bpermute_b32 v222, v172, v140
	ds_bpermute_b32 v223, v172, v141
	ds_bpermute_b32 v224, v172, v142
	ds_bpermute_b32 v225, v172, v143
	ds_bpermute_b32 v226, v172, v144
	ds_bpermute_b32 v227, v172, v145
	s_waitcnt lgkmcnt(7)
	v_add_f32_e32 v138, v138, v220
	s_waitcnt lgkmcnt(6)
	v_add_f32_e32 v139, v139, v221
	s_waitcnt lgkmcnt(5)
	v_add_f32_e32 v140, v140, v222
	s_waitcnt lgkmcnt(4)
	v_add_f32_e32 v141, v141, v223
	s_waitcnt lgkmcnt(3)
	v_add_f32_e32 v142, v142, v224
	s_waitcnt lgkmcnt(2)
	v_add_f32_e32 v143, v143, v225
	s_waitcnt lgkmcnt(1)
	v_add_f32_e32 v144, v144, v226
	s_waitcnt lgkmcnt(0)
	v_add_f32_e32 v145, v145, v227
	ds_bpermute_b32 v220, v173, v138
	ds_bpermute_b32 v221, v173, v139
	ds_bpermute_b32 v222, v173, v140
	ds_bpermute_b32 v223, v173, v141
	ds_bpermute_b32 v224, v173, v142
	ds_bpermute_b32 v225, v173, v143
	ds_bpermute_b32 v226, v173, v144
	ds_bpermute_b32 v227, v173, v145
	s_waitcnt lgkmcnt(7)
	v_add_f32_e32 v138, v138, v220
	s_waitcnt lgkmcnt(6)
	v_add_f32_e32 v139, v139, v221
	s_waitcnt lgkmcnt(5)
	v_add_f32_e32 v140, v140, v222
	s_waitcnt lgkmcnt(4)
	v_add_f32_e32 v141, v141, v223
	s_waitcnt lgkmcnt(3)
	v_add_f32_e32 v142, v142, v224
	s_waitcnt lgkmcnt(2)
	v_add_f32_e32 v143, v143, v225
	s_waitcnt lgkmcnt(1)
	v_add_f32_e32 v144, v144, v226
	s_waitcnt lgkmcnt(0)
	v_add_f32_e32 v145, v145, v227
	v_cmp_eq_u32_e32 vcc, 0, v174
	s_and_saveexec_b64 s[58:59], vcc
	global_store_dword v167, v130, s[10:11]
	global_store_dword v167, v131, s[10:11] offset:4
	global_store_dword v167, v132, s[10:11] offset:8
	global_store_dword v167, v133, s[10:11] offset:12
	global_store_dword v167, v134, s[10:11] offset:32
	global_store_dword v167, v135, s[10:11] offset:36
	global_store_dword v167, v136, s[10:11] offset:40
	global_store_dword v167, v137, s[10:11] offset:44
	global_store_dword v167, v138, s[10:11] offset:64
	global_store_dword v167, v139, s[10:11] offset:68
	global_store_dword v167, v140, s[10:11] offset:72
	global_store_dword v167, v141, s[10:11] offset:76
	global_store_dword v167, v142, s[10:11] offset:96
	global_store_dword v167, v143, s[10:11] offset:100
	global_store_dword v167, v144, s[10:11] offset:104
	global_store_dword v167, v145, s[10:11] offset:108
	s_mov_b64 exec, -1
	s_add_u32 s48, s48, 0x20000
	s_addc_u32 s49, s49, 0
	global_load_dword v130, v162, s[48:49]
	global_load_dword v212, v162, s[48:49] offset:128
	global_load_dword v131, v163, s[48:49]
	global_load_dword v213, v163, s[48:49] offset:128
	global_load_dword v132, v164, s[48:49]
	global_load_dword v214, v164, s[48:49] offset:128
	global_load_dword v133, v165, s[48:49]
	global_load_dword v215, v165, s[48:49] offset:128
	s_add_u32 s48, s48, 0x8000
	s_addc_u32 s49, s49, 0
	global_load_dword v134, v162, s[48:49]
	global_load_dword v216, v162, s[48:49] offset:128
	global_load_dword v135, v163, s[48:49]
	global_load_dword v217, v163, s[48:49] offset:128
	global_load_dword v136, v164, s[48:49]
	global_load_dword v218, v164, s[48:49] offset:128
	global_load_dword v137, v165, s[48:49]
	global_load_dword v219, v165, s[48:49] offset:128
	s_add_u32 s48, s48, 0x8000
	s_addc_u32 s49, s49, 0
	global_load_dword v138, v162, s[48:49]
	global_load_dword v220, v162, s[48:49] offset:128
	global_load_dword v139, v163, s[48:49]
	global_load_dword v221, v163, s[48:49] offset:128
	global_load_dword v140, v164, s[48:49]
	global_load_dword v222, v164, s[48:49] offset:128
	global_load_dword v141, v165, s[48:49]
	global_load_dword v223, v165, s[48:49] offset:128
	s_add_u32 s48, s48, 0x8000
	s_addc_u32 s49, s49, 0
	global_load_dword v142, v162, s[48:49]
	global_load_dword v224, v162, s[48:49] offset:128
	global_load_dword v143, v163, s[48:49]
	global_load_dword v225, v163, s[48:49] offset:128
	global_load_dword v144, v164, s[48:49]
	global_load_dword v226, v164, s[48:49] offset:128
	global_load_dword v145, v165, s[48:49]
	global_load_dword v227, v165, s[48:49] offset:128
	s_sub_u32 s48, s48, 0x18000
	s_subb_u32 s49, s49, 0
	s_waitcnt vmcnt(30)
	v_fmac_f32_e32 v130, v98, v175
	v_fmac_f32_e32 v212, v114, v176
	global_store_dword v162, v130, s[48:49]
	global_store_dword v162, v212, s[48:49] offset:128
	s_waitcnt vmcnt(30)
	v_fmac_f32_e32 v131, v99, v175
	v_fmac_f32_e32 v213, v115, v176
	global_store_dword v163, v131, s[48:49]
	global_store_dword v163, v213, s[48:49] offset:128
	s_waitcnt vmcnt(30)
	v_fmac_f32_e32 v132, v100, v175
	v_fmac_f32_e32 v214, v116, v176
	global_store_dword v164, v132, s[48:49]
	global_store_dword v164, v214, s[48:49] offset:128
	s_waitcnt vmcnt(30)
	v_fmac_f32_e32 v133, v101, v175
	v_fmac_f32_e32 v215, v117, v176
	global_store_dword v165, v133, s[48:49]
	global_store_dword v165, v215, s[48:49] offset:128
	s_add_u32 s48, s48, 0x8000
	s_addc_u32 s49, s49, 0
	s_waitcnt vmcnt(30)
	v_fmac_f32_e32 v134, v102, v175
	v_fmac_f32_e32 v216, v118, v176
	global_store_dword v162, v134, s[48:49]
	global_store_dword v162, v216, s[48:49] offset:128
	s_waitcnt vmcnt(30)
	v_fmac_f32_e32 v135, v103, v175
	v_fmac_f32_e32 v217, v119, v176
	global_store_dword v163, v135, s[48:49]
	global_store_dword v163, v217, s[48:49] offset:128
	s_waitcnt vmcnt(30)
	v_fmac_f32_e32 v136, v104, v175
	v_fmac_f32_e32 v218, v120, v176
	global_store_dword v164, v136, s[48:49]
	global_store_dword v164, v218, s[48:49] offset:128
	s_waitcnt vmcnt(30)
	v_fmac_f32_e32 v137, v105, v175
	v_fmac_f32_e32 v219, v121, v176
	global_store_dword v165, v137, s[48:49]
	global_store_dword v165, v219, s[48:49] offset:128
	s_add_u32 s48, s48, 0x8000
	s_addc_u32 s49, s49, 0
	s_waitcnt vmcnt(30)
	v_fmac_f32_e32 v138, v106, v175
	v_fmac_f32_e32 v220, v122, v176
	global_store_dword v162, v138, s[48:49]
	global_store_dword v162, v220, s[48:49] offset:128
	s_waitcnt vmcnt(30)
	v_fmac_f32_e32 v139, v107, v175
	v_fmac_f32_e32 v221, v123, v176
	global_store_dword v163, v139, s[48:49]
	global_store_dword v163, v221, s[48:49] offset:128
	s_waitcnt vmcnt(30)
	v_fmac_f32_e32 v140, v108, v175
	v_fmac_f32_e32 v222, v124, v176
	global_store_dword v164, v140, s[48:49]
	global_store_dword v164, v222, s[48:49] offset:128
	s_waitcnt vmcnt(30)
	v_fmac_f32_e32 v141, v109, v175
	v_fmac_f32_e32 v223, v125, v176
	global_store_dword v165, v141, s[48:49]
	global_store_dword v165, v223, s[48:49] offset:128
	s_add_u32 s48, s48, 0x8000
	s_addc_u32 s49, s49, 0
	s_waitcnt vmcnt(30)
	v_fmac_f32_e32 v142, v110, v175
	v_fmac_f32_e32 v224, v126, v176
	global_store_dword v162, v142, s[48:49]
	global_store_dword v162, v224, s[48:49] offset:128
	s_waitcnt vmcnt(30)
	v_fmac_f32_e32 v143, v111, v175
	v_fmac_f32_e32 v225, v127, v176
	global_store_dword v163, v143, s[48:49]
	global_store_dword v163, v225, s[48:49] offset:128
	s_waitcnt vmcnt(30)
	v_fmac_f32_e32 v144, v112, v175
	v_fmac_f32_e32 v226, v128, v176
	global_store_dword v164, v144, s[48:49]
	global_store_dword v164, v226, s[48:49] offset:128
	s_waitcnt vmcnt(30)
	v_fmac_f32_e32 v145, v113, v175
	v_fmac_f32_e32 v227, v129, v176
	global_store_dword v165, v145, s[48:49]
	global_store_dword v165, v227, s[48:49] offset:128
	s_sub_u32 s48, s48, 0x18000
	s_subb_u32 s49, s49, 0
	v_mul_f32_e32 v130, v130, v130
	v_fmac_f32_e32 v130, v212, v212
	v_mul_f32_e32 v131, v131, v131
	v_fmac_f32_e32 v131, v213, v213
	v_mul_f32_e32 v132, v132, v132
	v_fmac_f32_e32 v132, v214, v214
	v_mul_f32_e32 v133, v133, v133
	v_fmac_f32_e32 v133, v215, v215
	v_mul_f32_e32 v134, v134, v134
	v_fmac_f32_e32 v134, v216, v216
	v_mul_f32_e32 v135, v135, v135
	v_fmac_f32_e32 v135, v217, v217
	v_mul_f32_e32 v136, v136, v136
	v_fmac_f32_e32 v136, v218, v218
	v_mul_f32_e32 v137, v137, v137
	v_fmac_f32_e32 v137, v219, v219
	v_mul_f32_e32 v138, v138, v138
	v_fmac_f32_e32 v138, v220, v220
	v_mul_f32_e32 v139, v139, v139
	v_fmac_f32_e32 v139, v221, v221
	v_mul_f32_e32 v140, v140, v140
	v_fmac_f32_e32 v140, v222, v222
	v_mul_f32_e32 v141, v141, v141
	v_fmac_f32_e32 v141, v223, v223
	v_mul_f32_e32 v142, v142, v142
	v_fmac_f32_e32 v142, v224, v224
	v_mul_f32_e32 v143, v143, v143
	v_fmac_f32_e32 v143, v225, v225
	v_mul_f32_e32 v144, v144, v144
	v_fmac_f32_e32 v144, v226, v226
	v_mul_f32_e32 v145, v145, v145
	v_fmac_f32_e32 v145, v227, v227
	s_waitcnt lgkmcnt(0)
	ds_bpermute_b32 v212, v168, v130
	ds_bpermute_b32 v213, v168, v131
	ds_bpermute_b32 v214, v168, v132
	ds_bpermute_b32 v215, v168, v133
	ds_bpermute_b32 v216, v168, v134
	ds_bpermute_b32 v217, v168, v135
	ds_bpermute_b32 v218, v168, v136
	ds_bpermute_b32 v219, v168, v137
	s_waitcnt lgkmcnt(7)
	v_add_f32_e32 v130, v130, v212
	s_waitcnt lgkmcnt(6)
	v_add_f32_e32 v131, v131, v213
	s_waitcnt lgkmcnt(5)
	v_add_f32_e32 v132, v132, v214
	s_waitcnt lgkmcnt(4)
	v_add_f32_e32 v133, v133, v215
	s_waitcnt lgkmcnt(3)
	v_add_f32_e32 v134, v134, v216
	s_waitcnt lgkmcnt(2)
	v_add_f32_e32 v135, v135, v217
	s_waitcnt lgkmcnt(1)
	v_add_f32_e32 v136, v136, v218
	s_waitcnt lgkmcnt(0)
	v_add_f32_e32 v137, v137, v219
	ds_bpermute_b32 v212, v169, v130
	ds_bpermute_b32 v213, v169, v131
	ds_bpermute_b32 v214, v169, v132
	ds_bpermute_b32 v215, v169, v133
	ds_bpermute_b32 v216, v169, v134
	ds_bpermute_b32 v217, v169, v135
	ds_bpermute_b32 v218, v169, v136
	ds_bpermute_b32 v219, v169, v137
	s_waitcnt lgkmcnt(7)
	v_add_f32_e32 v130, v130, v212
	s_waitcnt lgkmcnt(6)
	v_add_f32_e32 v131, v131, v213
	s_waitcnt lgkmcnt(5)
	v_add_f32_e32 v132, v132, v214
	s_waitcnt lgkmcnt(4)
	v_add_f32_e32 v133, v133, v215
	s_waitcnt lgkmcnt(3)
	v_add_f32_e32 v134, v134, v216
	s_waitcnt lgkmcnt(2)
	v_add_f32_e32 v135, v135, v217
	s_waitcnt lgkmcnt(1)
	v_add_f32_e32 v136, v136, v218
	s_waitcnt lgkmcnt(0)
	v_add_f32_e32 v137, v137, v219
	ds_bpermute_b32 v212, v171, v130
	ds_bpermute_b32 v213, v171, v131
	ds_bpermute_b32 v214, v171, v132
	ds_bpermute_b32 v215, v171, v133
	ds_bpermute_b32 v216, v171, v134
	ds_bpermute_b32 v217, v171, v135
	ds_bpermute_b32 v218, v171, v136
	ds_bpermute_b32 v219, v171, v137
	s_waitcnt lgkmcnt(7)
	v_add_f32_e32 v130, v130, v212
	s_waitcnt lgkmcnt(6)
	v_add_f32_e32 v131, v131, v213
	s_waitcnt lgkmcnt(5)
	v_add_f32_e32 v132, v132, v214
	s_waitcnt lgkmcnt(4)
	v_add_f32_e32 v133, v133, v215
	s_waitcnt lgkmcnt(3)
	v_add_f32_e32 v134, v134, v216
	s_waitcnt lgkmcnt(2)
	v_add_f32_e32 v135, v135, v217
	s_waitcnt lgkmcnt(1)
	v_add_f32_e32 v136, v136, v218
	s_waitcnt lgkmcnt(0)
	v_add_f32_e32 v137, v137, v219
	ds_bpermute_b32 v212, v172, v130
	ds_bpermute_b32 v213, v172, v131
	ds_bpermute_b32 v214, v172, v132
	ds_bpermute_b32 v215, v172, v133
	ds_bpermute_b32 v216, v172, v134
	ds_bpermute_b32 v217, v172, v135
	ds_bpermute_b32 v218, v172, v136
	ds_bpermute_b32 v219, v172, v137
	s_waitcnt lgkmcnt(7)
	v_add_f32_e32 v130, v130, v212
	s_waitcnt lgkmcnt(6)
	v_add_f32_e32 v131, v131, v213
	s_waitcnt lgkmcnt(5)
	v_add_f32_e32 v132, v132, v214
	s_waitcnt lgkmcnt(4)
	v_add_f32_e32 v133, v133, v215
	s_waitcnt lgkmcnt(3)
	v_add_f32_e32 v134, v134, v216
	s_waitcnt lgkmcnt(2)
	v_add_f32_e32 v135, v135, v217
	s_waitcnt lgkmcnt(1)
	v_add_f32_e32 v136, v136, v218
	s_waitcnt lgkmcnt(0)
	v_add_f32_e32 v137, v137, v219
	ds_bpermute_b32 v212, v173, v130
	ds_bpermute_b32 v213, v173, v131
	ds_bpermute_b32 v214, v173, v132
	ds_bpermute_b32 v215, v173, v133
	ds_bpermute_b32 v216, v173, v134
	ds_bpermute_b32 v217, v173, v135
	ds_bpermute_b32 v218, v173, v136
	ds_bpermute_b32 v219, v173, v137
	s_waitcnt lgkmcnt(7)
	v_add_f32_e32 v130, v130, v212
	s_waitcnt lgkmcnt(6)
	v_add_f32_e32 v131, v131, v213
	s_waitcnt lgkmcnt(5)
	v_add_f32_e32 v132, v132, v214
	s_waitcnt lgkmcnt(4)
	v_add_f32_e32 v133, v133, v215
	s_waitcnt lgkmcnt(3)
	v_add_f32_e32 v134, v134, v216
	s_waitcnt lgkmcnt(2)
	v_add_f32_e32 v135, v135, v217
	s_waitcnt lgkmcnt(1)
	v_add_f32_e32 v136, v136, v218
	s_waitcnt lgkmcnt(0)
	v_add_f32_e32 v137, v137, v219
	ds_bpermute_b32 v220, v168, v138
	ds_bpermute_b32 v221, v168, v139
	ds_bpermute_b32 v222, v168, v140
	ds_bpermute_b32 v223, v168, v141
	ds_bpermute_b32 v224, v168, v142
	ds_bpermute_b32 v225, v168, v143
	ds_bpermute_b32 v226, v168, v144
	ds_bpermute_b32 v227, v168, v145
	s_waitcnt lgkmcnt(7)
	v_add_f32_e32 v138, v138, v220
	s_waitcnt lgkmcnt(6)
	v_add_f32_e32 v139, v139, v221
	s_waitcnt lgkmcnt(5)
	v_add_f32_e32 v140, v140, v222
	s_waitcnt lgkmcnt(4)
	v_add_f32_e32 v141, v141, v223
	s_waitcnt lgkmcnt(3)
	v_add_f32_e32 v142, v142, v224
	s_waitcnt lgkmcnt(2)
	v_add_f32_e32 v143, v143, v225
	s_waitcnt lgkmcnt(1)
	v_add_f32_e32 v144, v144, v226
	s_waitcnt lgkmcnt(0)
	v_add_f32_e32 v145, v145, v227
	ds_bpermute_b32 v220, v169, v138
	ds_bpermute_b32 v221, v169, v139
	ds_bpermute_b32 v222, v169, v140
	ds_bpermute_b32 v223, v169, v141
	ds_bpermute_b32 v224, v169, v142
	ds_bpermute_b32 v225, v169, v143
	ds_bpermute_b32 v226, v169, v144
	ds_bpermute_b32 v227, v169, v145
	s_waitcnt lgkmcnt(7)
	v_add_f32_e32 v138, v138, v220
	s_waitcnt lgkmcnt(6)
	v_add_f32_e32 v139, v139, v221
	s_waitcnt lgkmcnt(5)
	v_add_f32_e32 v140, v140, v222
	s_waitcnt lgkmcnt(4)
	v_add_f32_e32 v141, v141, v223
	s_waitcnt lgkmcnt(3)
	v_add_f32_e32 v142, v142, v224
	s_waitcnt lgkmcnt(2)
	v_add_f32_e32 v143, v143, v225
	s_waitcnt lgkmcnt(1)
	v_add_f32_e32 v144, v144, v226
	s_waitcnt lgkmcnt(0)
	v_add_f32_e32 v145, v145, v227
	ds_bpermute_b32 v220, v171, v138
	ds_bpermute_b32 v221, v171, v139
	ds_bpermute_b32 v222, v171, v140
	ds_bpermute_b32 v223, v171, v141
	ds_bpermute_b32 v224, v171, v142
	ds_bpermute_b32 v225, v171, v143
	ds_bpermute_b32 v226, v171, v144
	ds_bpermute_b32 v227, v171, v145
	s_waitcnt lgkmcnt(7)
	v_add_f32_e32 v138, v138, v220
	s_waitcnt lgkmcnt(6)
	v_add_f32_e32 v139, v139, v221
	s_waitcnt lgkmcnt(5)
	v_add_f32_e32 v140, v140, v222
	s_waitcnt lgkmcnt(4)
	v_add_f32_e32 v141, v141, v223
	s_waitcnt lgkmcnt(3)
	v_add_f32_e32 v142, v142, v224
	s_waitcnt lgkmcnt(2)
	v_add_f32_e32 v143, v143, v225
	s_waitcnt lgkmcnt(1)
	v_add_f32_e32 v144, v144, v226
	s_waitcnt lgkmcnt(0)
	v_add_f32_e32 v145, v145, v227
	ds_bpermute_b32 v220, v172, v138
	ds_bpermute_b32 v221, v172, v139
	ds_bpermute_b32 v222, v172, v140
	ds_bpermute_b32 v223, v172, v141
	ds_bpermute_b32 v224, v172, v142
	ds_bpermute_b32 v225, v172, v143
	ds_bpermute_b32 v226, v172, v144
	ds_bpermute_b32 v227, v172, v145
	s_waitcnt lgkmcnt(7)
	v_add_f32_e32 v138, v138, v220
	s_waitcnt lgkmcnt(6)
	v_add_f32_e32 v139, v139, v221
	s_waitcnt lgkmcnt(5)
	v_add_f32_e32 v140, v140, v222
	s_waitcnt lgkmcnt(4)
	v_add_f32_e32 v141, v141, v223
	s_waitcnt lgkmcnt(3)
	v_add_f32_e32 v142, v142, v224
	s_waitcnt lgkmcnt(2)
	v_add_f32_e32 v143, v143, v225
	s_waitcnt lgkmcnt(1)
	v_add_f32_e32 v144, v144, v226
	s_waitcnt lgkmcnt(0)
	v_add_f32_e32 v145, v145, v227
	ds_bpermute_b32 v220, v173, v138
	ds_bpermute_b32 v221, v173, v139
	ds_bpermute_b32 v222, v173, v140
	ds_bpermute_b32 v223, v173, v141
	ds_bpermute_b32 v224, v173, v142
	ds_bpermute_b32 v225, v173, v143
	ds_bpermute_b32 v226, v173, v144
	ds_bpermute_b32 v227, v173, v145
	s_waitcnt lgkmcnt(7)
	v_add_f32_e32 v138, v138, v220
	s_waitcnt lgkmcnt(6)
	v_add_f32_e32 v139, v139, v221
	s_waitcnt lgkmcnt(5)
	v_add_f32_e32 v140, v140, v222
	s_waitcnt lgkmcnt(4)
	v_add_f32_e32 v141, v141, v223
	s_waitcnt lgkmcnt(3)
	v_add_f32_e32 v142, v142, v224
	s_waitcnt lgkmcnt(2)
	v_add_f32_e32 v143, v143, v225
	s_waitcnt lgkmcnt(1)
	v_add_f32_e32 v144, v144, v226
	s_waitcnt lgkmcnt(0)
	v_add_f32_e32 v145, v145, v227
	v_cmp_eq_u32_e32 vcc, 0, v174
	s_and_saveexec_b64 s[58:59], vcc
	global_store_dword v167, v130, s[10:11] offset:128
	global_store_dword v167, v131, s[10:11] offset:132
	global_store_dword v167, v132, s[10:11] offset:136
	global_store_dword v167, v133, s[10:11] offset:140
	global_store_dword v167, v134, s[10:11] offset:160
	global_store_dword v167, v135, s[10:11] offset:164
	global_store_dword v167, v136, s[10:11] offset:168
	global_store_dword v167, v137, s[10:11] offset:172
	global_store_dword v167, v138, s[10:11] offset:192
	global_store_dword v167, v139, s[10:11] offset:196
	global_store_dword v167, v140, s[10:11] offset:200
	global_store_dword v167, v141, s[10:11] offset:204
	global_store_dword v167, v142, s[10:11] offset:224
	global_store_dword v167, v143, s[10:11] offset:228
	global_store_dword v167, v144, s[10:11] offset:232
	global_store_dword v167, v145, s[10:11] offset:236
	s_mov_b64 exec, -1
	s_sub_u32 s48, s48, 0x20000
	s_subb_u32 s49, s49, 0
	v_readlane_b32 s2, v246, 14
	s_nop 0
	s_add_i32 s16, s16, s2
	s_branch .Lhw_ffndown_tloop
